# all 7 GEMM K-loops: LDS-DMA loads use SGPR-base saddr form, VALU 64-bit address adds removed (s_nop padded)
# speedup vs baseline: 1.0015x; 1.0015x over previous
; #define PG8_STAGE(bufoff, gbase, voff) do { _Pragma("unroll") for (int _i = 0; _i < 2; ++_i) \
;         __builtin_amdgcn_global_load_lds((const unsigned*)((const char*)(gbase) + (voff)[_i]), (PG8_LAS unsigned*)(lds + (bufoff) + ldsw + _i * 8192), 16, 0, 0); } while (0)
; #define PG8_LDA(dst, b, h) do { _Pragma("unroll") for (int m = 0; m < 4; ++m) _Pragma("unroll") for (int k = 0; k < 2; ++k) dst[m][k] = *(const PG8_LAS bf16x8*)(lds + PG8_SA(b, h) + aoff + m * 2048 + k * 1024); } while (0)
; #define PG8_LDB(dst, b, h) do { _Pragma("unroll") for (int n = 0; n < 2; ++n) _Pragma("unroll") for (int k = 0; k < 2; ++k) dst[n][k] = *(const PG8_LAS bf16x8*)(lds + PG8_SB(b, h) + boff + n * 2048 + k * 1024); } while (0)
; #define PG8_MMA(ai, bj, At, Bt) do { __builtin_amdgcn_s_setprio(1); _Pragma("unroll") for (int m = 0; m < 4; ++m) _Pragma("unroll") for (int n = 0; n < 2; ++n) _Pragma("unroll") for (int k = 0; k < 2; ++k) \
;         acc[ai][bj][m][n] = __builtin_amdgcn_mfma_f32_16x16x32_bf16(Bt[n][k], At[m][k], acc[ai][bj][m][n], 0, 0, 0); __builtin_amdgcn_s_setprio(0); } while (0)
; #define PG8_WAIT_V(n) asm volatile("s_waitcnt vmcnt(" #n ")" ::: "memory")
; template <class Epi, class Sched, bool ALIGN_EPI = false, bool SP2 = false>
; __device__ __forceinline__ void gemm_phase(PG8_LAS unsigned char* lds, const Gemm g, const Sched& S, const Epi& E) {
;     ...
;             const bool last = (t == nt - 2);
;             const char* a1 = cA + (size_t)(t + 1) * kstepA;
;             const char* a2 = last ? nA : cA + (size_t)(t + 2) * kstepA; const char* b2 = last ? nB : cB + (size_t)(t + 2) * kstep;
;             const char* a3 = a2 + kstepA; const char* b3 = b2 + kstep;
;             if (last && has_next) S.a_ready(nxt);
;             if constexpr (SP2) {
;             PG8_LDB(B0, 0, 0); PG8_LDB(B1, 0, 1); PG8_SCHED; PG8_LDA(At, 0, 0); PG8_STAGE(PG8_SA(1, 1), a1 + hstep, voffA);
;             PG8_WAIT_V(8); PG8_WAIT_L(0); PG8_BAR; PG8_MMA(0, 0, At, B0); PG8_MMA(0, 1, At, B1); PG8_BAR; PG8_SCHED;
;             if constexpr (Epi::PREFETCH) { if (t == tpf) E.prefetch(cur, wid, lane); }
;             PG8_LDA(At, 0, 1); PG8_STAGE(PG8_SB(0, 0), b2, voffB); PG8_STAGE(PG8_SB(0, 1), b2 + hstep, voffB); PG8_STAGE(PG8_SA(0, 0), a2, voffA);
;             PG8_WAIT_V(8); PG8_WAIT_L(0); PG8_BAR; PG8_MMA(1, 0, At, B0); PG8_MMA(1, 1, At, B1); PG8_BAR; PG8_SCHED;
.LBB0_208:
	ds_read_b128 v[154:157], v150
	ds_read_b128 v[158:161], v150 offset:1024
	ds_read_b128 v[162:165], v150 offset:2048
	ds_read_b128 v[166:169], v150 offset:3072
	ds_read_b128 v[170:173], v151
	ds_read_b128 v[174:177], v151 offset:1024
	ds_read_b128 v[178:181], v151 offset:2048
	ds_read_b128 v[182:185], v151 offset:3072
	s_add_u32 s24, s22, 0xfffc0080
	s_addc_u32 s25, s23, -1
	s_cmp_eq_u32 s54, 12
	s_cselect_b32 s27, s15, s25
	s_cselect_b32 s26, s50, s24
	s_cselect_b32 s25, s13, s53
	s_cselect_b32 s24, s51, s52
	s_nop 0
	s_nop 0
	s_add_i32 m0, s37, 0xc000
	ds_read_b128 v[186:189], v152
	ds_read_b128 v[190:193], v152 offset:1024
	ds_read_b128 v[194:197], v152 offset:2048
	ds_read_b128 v[198:201], v152 offset:3072
	ds_read_b128 v[202:205], v152 offset:4096
	ds_read_b128 v[206:209], v152 offset:5120
	ds_read_b128 v[210:213], v152 offset:6144
	ds_read_b128 v[214:217], v152 offset:7168
	global_load_lds_dwordx4 v140, s[22:23]
	s_nop 0
	s_nop 0
	s_add_i32 m0, s37, 0xe000
	s_nop 0
	global_load_lds_dwordx4 v142, s[22:23]
	s_waitcnt vmcnt(8)
	s_waitcnt lgkmcnt(0)
	s_barrier
	s_setprio 1
	s_waitcnt lgkmcnt(0)
	v_mfma_f32_16x16x32_bf16 v[126:129], v[154:157], v[186:189], v[126:129]
	v_mfma_f32_16x16x32_bf16 v[122:125], v[162:165], v[186:189], v[122:125]
	v_mfma_f32_16x16x32_bf16 v[110:113], v[154:157], v[194:197], v[110:113]
	v_mfma_f32_16x16x32_bf16 v[106:109], v[162:165], v[194:197], v[106:109]
	v_mfma_f32_16x16x32_bf16 v[94:97], v[154:157], v[202:205], v[94:97]
	v_mfma_f32_16x16x32_bf16 v[90:93], v[162:165], v[202:205], v[90:93]
	v_mfma_f32_16x16x32_bf16 v[78:81], v[154:157], v[210:213], v[78:81]
	v_mfma_f32_16x16x32_bf16 v[74:77], v[162:165], v[210:213], v[74:77]
	v_mfma_f32_16x16x32_bf16 v[126:129], v[158:161], v[190:193], v[126:129]
	v_mfma_f32_16x16x32_bf16 v[122:125], v[166:169], v[190:193], v[122:125]
	v_mfma_f32_16x16x32_bf16 v[110:113], v[158:161], v[198:201], v[110:113]
	v_mfma_f32_16x16x32_bf16 v[106:109], v[166:169], v[198:201], v[106:109]
	v_mfma_f32_16x16x32_bf16 v[94:97], v[158:161], v[206:209], v[94:97]
	v_mfma_f32_16x16x32_bf16 v[90:93], v[166:169], v[206:209], v[90:93]
	v_mfma_f32_16x16x32_bf16 v[78:81], v[158:161], v[214:217], v[78:81]
	v_mfma_f32_16x16x32_bf16 v[74:77], v[166:169], v[214:217], v[74:77]
	s_setprio 0
	s_setprio 1
	v_mfma_f32_16x16x32_bf16 v[118:121], v[170:173], v[186:189], v[118:121]
	v_mfma_f32_16x16x32_bf16 v[114:117], v[178:181], v[186:189], v[114:117]
	v_mfma_f32_16x16x32_bf16 v[102:105], v[170:173], v[194:197], v[102:105]
	v_mfma_f32_16x16x32_bf16 v[98:101], v[178:181], v[194:197], v[98:101]
	v_mfma_f32_16x16x32_bf16 v[86:89], v[170:173], v[202:205], v[86:89]
	v_mfma_f32_16x16x32_bf16 v[82:85], v[178:181], v[202:205], v[82:85]
	v_mfma_f32_16x16x32_bf16 v[70:73], v[170:173], v[210:213], v[70:73]
	v_mfma_f32_16x16x32_bf16 v[66:69], v[178:181], v[210:213], v[66:69]
	v_mfma_f32_16x16x32_bf16 v[118:121], v[174:177], v[190:193], v[118:121]
	v_mfma_f32_16x16x32_bf16 v[114:117], v[182:185], v[190:193], v[114:117]
	v_mfma_f32_16x16x32_bf16 v[102:105], v[174:177], v[198:201], v[102:105]
	v_mfma_f32_16x16x32_bf16 v[98:101], v[182:185], v[198:201], v[98:101]
	v_mfma_f32_16x16x32_bf16 v[86:89], v[174:177], v[206:209], v[86:89]
	v_mfma_f32_16x16x32_bf16 v[82:85], v[182:185], v[206:209], v[82:85]
	v_mfma_f32_16x16x32_bf16 v[70:73], v[174:177], v[214:217], v[70:73]
	v_mfma_f32_16x16x32_bf16 v[66:69], v[182:185], v[214:217], v[66:69]
	s_setprio 0
	s_barrier
	s_add_i32 s55, s47, s34
	s_nop 0
	s_nop 0
	s_add_u32 s98, s24, s8
	s_addc_u32 s99, s25, s9
	s_mov_b32 m0, s55
	ds_read_b128 v[186:189], v152 offset:16384
	ds_read_b128 v[190:193], v152 offset:17408
	ds_read_b128 v[194:197], v152 offset:18432
	ds_read_b128 v[198:201], v152 offset:19456
	ds_read_b128 v[202:205], v152 offset:20480
	ds_read_b128 v[206:209], v152 offset:21504
	ds_read_b128 v[210:213], v152 offset:22528
	ds_read_b128 v[214:217], v152 offset:23552
	global_load_lds_dwordx4 v134, s[24:25]
	s_add_i32 m0, s55, 0x2000
	s_add_u32 s56, s24, 0x40000
	s_nop 0
	s_nop 0
	s_addc_u32 s57, s25, 0
	s_add_i32 s55, s48, s34
	global_load_lds_dwordx4 v130, s[24:25]
	s_nop 0
	s_nop 0
	s_mov_b32 m0, s55
	s_nop 0
	s_nop 0
	global_load_lds_dwordx4 v134, s[56:57]
	s_nop 0
	s_nop 0
	s_add_i32 m0, s55, 0x2000
	s_nop 0
	global_load_lds_dwordx4 v130, s[56:57]
	s_nop 0
	s_nop 0
	s_add_u32 s100, s26, s8
	s_addc_u32 s101, s27, s9
	s_mov_b32 m0, s37
	s_nop 0
	global_load_lds_dwordx4 v136, s[26:27]
	s_mov_b32 m0, s38
	s_nop 0
	global_load_lds_dwordx4 v132, s[26:27]
	s_waitcnt vmcnt(8)
	s_waitcnt lgkmcnt(0)
	s_barrier
; #define PG8_STAGE(bufoff, gbase, voff) do { _Pragma("unroll") for (int _i = 0; _i < 2; ++_i) \
;         __builtin_amdgcn_global_load_lds((const unsigned*)((const char*)(gbase) + (voff)[_i]), (PG8_LAS unsigned*)(lds + (bufoff) + ldsw + _i * 8192), 16, 0, 0); } while (0)
; #define PG8_LDA(dst, b, h) do { _Pragma("unroll") for (int m = 0; m < 4; ++m) _Pragma("unroll") for (int k = 0; k < 2; ++k) dst[m][k] = *(const PG8_LAS bf16x8*)(lds + PG8_SA(b, h) + aoff + m * 2048 + k * 1024); } while (0)
; #define PG8_LDB(dst, b, h) do { _Pragma("unroll") for (int n = 0; n < 2; ++n) _Pragma("unroll") for (int k = 0; k < 2; ++k) dst[n][k] = *(const PG8_LAS bf16x8*)(lds + PG8_SB(b, h) + boff + n * 2048 + k * 1024); } while (0)
; #define PG8_MMA(ai, bj, At, Bt) do { __builtin_amdgcn_s_setprio(1); _Pragma("unroll") for (int m = 0; m < 4; ++m) _Pragma("unroll") for (int n = 0; n < 2; ++n) _Pragma("unroll") for (int k = 0; k < 2; ++k) \
;         acc[ai][bj][m][n] = __builtin_amdgcn_mfma_f32_16x16x32_bf16(Bt[n][k], At[m][k], acc[ai][bj][m][n], 0, 0, 0); __builtin_amdgcn_s_setprio(0); } while (0)
; #define PG8_WAIT_V(n) asm volatile("s_waitcnt vmcnt(" #n ")" ::: "memory")
; #define PG8_WAIT_L(n) asm volatile("s_waitcnt lgkmcnt(" #n ")" ::: "memory")
; #define PG8_BAR __builtin_amdgcn_s_barrier()
; #define PG8_SCHED __builtin_amdgcn_sched_barrier(0)
; template <class Epi, class Sched, bool ALIGN_EPI = false, bool SP2 = false>
; __device__ __forceinline__ void gemm_phase(PG8_LAS unsigned char* lds, const Gemm g, const Sched& S, const Epi& E) {
;     ...
;             PG8_WAIT_V(8); PG8_WAIT_L(0); PG8_BAR; PG8_MMA(1, 0, At, B0); PG8_MMA(1, 1, At, B1); PG8_BAR; PG8_SCHED;
;             PG8_LDB(B0, 1, 0); PG8_LDB(B1, 1, 1); PG8_SCHED; PG8_LDA(At, 1, 0); PG8_STAGE(PG8_SA(0, 1), a2 + hstep, voffA);
;             PG8_WAIT_V(8); PG8_WAIT_L(0); PG8_BAR; PG8_MMA(0, 0, At, B0); PG8_MMA(0, 1, At, B1); PG8_BAR; PG8_SCHED;
	s_setprio 1
	s_waitcnt lgkmcnt(0)
	v_mfma_f32_16x16x32_bf16 v[62:65], v[154:157], v[186:189], v[62:65]
	v_mfma_f32_16x16x32_bf16 v[58:61], v[162:165], v[186:189], v[58:61]
	v_mfma_f32_16x16x32_bf16 v[46:49], v[154:157], v[194:197], v[46:49]
	v_mfma_f32_16x16x32_bf16 v[42:45], v[162:165], v[194:197], v[42:45]
	v_mfma_f32_16x16x32_bf16 v[30:33], v[154:157], v[202:205], v[30:33]
	v_mfma_f32_16x16x32_bf16 v[26:29], v[162:165], v[202:205], v[26:29]
	v_mfma_f32_16x16x32_bf16 v[14:17], v[154:157], v[210:213], v[14:17]
	v_mfma_f32_16x16x32_bf16 v[10:13], v[162:165], v[210:213], v[10:13]
	v_mfma_f32_16x16x32_bf16 v[62:65], v[158:161], v[190:193], v[62:65]
	v_mfma_f32_16x16x32_bf16 v[58:61], v[166:169], v[190:193], v[58:61]
	v_mfma_f32_16x16x32_bf16 v[46:49], v[158:161], v[198:201], v[46:49]
	v_mfma_f32_16x16x32_bf16 v[42:45], v[166:169], v[198:201], v[42:45]
	v_mfma_f32_16x16x32_bf16 v[30:33], v[158:161], v[206:209], v[30:33]
	v_mfma_f32_16x16x32_bf16 v[26:29], v[166:169], v[206:209], v[26:29]
	v_mfma_f32_16x16x32_bf16 v[14:17], v[158:161], v[214:217], v[14:17]
	v_mfma_f32_16x16x32_bf16 v[10:13], v[166:169], v[214:217], v[10:13]
	s_setprio 0
	s_setprio 1
	v_mfma_f32_16x16x32_bf16 v[54:57], v[170:173], v[186:189], v[54:57]
	v_mfma_f32_16x16x32_bf16 v[50:53], v[178:181], v[186:189], v[50:53]
	v_mfma_f32_16x16x32_bf16 v[38:41], v[170:173], v[194:197], v[38:41]
	v_mfma_f32_16x16x32_bf16 v[34:37], v[178:181], v[194:197], v[34:37]
	v_mfma_f32_16x16x32_bf16 v[22:25], v[170:173], v[202:205], v[22:25]
	v_mfma_f32_16x16x32_bf16 v[18:21], v[178:181], v[202:205], v[18:21]
	v_mfma_f32_16x16x32_bf16 v[6:9], v[170:173], v[210:213], v[6:9]
	v_mfma_f32_16x16x32_bf16 v[2:5], v[178:181], v[210:213], v[2:5]
	v_mfma_f32_16x16x32_bf16 v[54:57], v[174:177], v[190:193], v[54:57]
	v_mfma_f32_16x16x32_bf16 v[50:53], v[182:185], v[190:193], v[50:53]
	v_mfma_f32_16x16x32_bf16 v[38:41], v[174:177], v[198:201], v[38:41]
	v_mfma_f32_16x16x32_bf16 v[34:37], v[182:185], v[198:201], v[34:37]
	v_mfma_f32_16x16x32_bf16 v[22:25], v[174:177], v[206:209], v[22:25]
	v_mfma_f32_16x16x32_bf16 v[18:21], v[182:185], v[206:209], v[18:21]
	v_mfma_f32_16x16x32_bf16 v[6:9], v[174:177], v[214:217], v[6:9]
	v_mfma_f32_16x16x32_bf16 v[2:5], v[182:185], v[214:217], v[2:5]
	s_setprio 0
	s_barrier
	s_add_i32 s55, 0, 0x18000
	v_add_u32_e32 v138, s55, v149
	s_add_i32 s56, 0, 0x1c000
	ds_read_b128 v[154:157], v138
	ds_read_b128 v[158:161], v138 offset:1024
	ds_read_b128 v[162:165], v138 offset:2048
	ds_read_b128 v[166:169], v138 offset:3072
	v_add_u32_e32 v138, s56, v149
	ds_read_b128 v[170:173], v138
	ds_read_b128 v[174:177], v138 offset:1024
	ds_read_b128 v[178:181], v138 offset:2048
	ds_read_b128 v[182:185], v138 offset:3072
	s_add_u32 s26, s26, 0x40000
	s_addc_u32 s27, s27, 0
	s_mov_b32 m0, s39
	s_nop 0
	s_nop 0
	ds_read_b128 v[186:189], v152 offset:32768
	ds_read_b128 v[190:193], v152 offset:33792
	ds_read_b128 v[194:197], v152 offset:34816
	ds_read_b128 v[198:201], v152 offset:35840
	ds_read_b128 v[202:205], v152 offset:36864
	ds_read_b128 v[206:209], v152 offset:37888
	ds_read_b128 v[210:213], v152 offset:38912
	ds_read_b128 v[214:217], v152 offset:39936
	global_load_lds_dwordx4 v136, s[26:27]
	s_nop 0
	s_nop 0
	s_mov_b32 m0, s40
	s_nop 0
	global_load_lds_dwordx4 v132, s[26:27]
	s_waitcnt vmcnt(8)
	s_waitcnt lgkmcnt(0)
	s_barrier
	s_setprio 1
	s_waitcnt lgkmcnt(0)
	v_mfma_f32_16x16x32_bf16 v[126:129], v[154:157], v[186:189], v[126:129]
	v_mfma_f32_16x16x32_bf16 v[122:125], v[162:165], v[186:189], v[122:125]
	v_mfma_f32_16x16x32_bf16 v[110:113], v[154:157], v[194:197], v[110:113]
	v_mfma_f32_16x16x32_bf16 v[106:109], v[162:165], v[194:197], v[106:109]
	v_mfma_f32_16x16x32_bf16 v[94:97], v[154:157], v[202:205], v[94:97]
	v_mfma_f32_16x16x32_bf16 v[90:93], v[162:165], v[202:205], v[90:93]
	v_mfma_f32_16x16x32_bf16 v[78:81], v[154:157], v[210:213], v[78:81]
	v_mfma_f32_16x16x32_bf16 v[74:77], v[162:165], v[210:213], v[74:77]
	v_mfma_f32_16x16x32_bf16 v[126:129], v[158:161], v[190:193], v[126:129]
	v_mfma_f32_16x16x32_bf16 v[122:125], v[166:169], v[190:193], v[122:125]
	v_mfma_f32_16x16x32_bf16 v[110:113], v[158:161], v[198:201], v[110:113]
	v_mfma_f32_16x16x32_bf16 v[106:109], v[166:169], v[198:201], v[106:109]
	v_mfma_f32_16x16x32_bf16 v[94:97], v[158:161], v[206:209], v[94:97]
	v_mfma_f32_16x16x32_bf16 v[90:93], v[166:169], v[206:209], v[90:93]
	v_mfma_f32_16x16x32_bf16 v[78:81], v[158:161], v[214:217], v[78:81]
	v_mfma_f32_16x16x32_bf16 v[74:77], v[166:169], v[214:217], v[74:77]
	s_setprio 0
	s_setprio 1
	v_mfma_f32_16x16x32_bf16 v[118:121], v[170:173], v[186:189], v[118:121]
	v_mfma_f32_16x16x32_bf16 v[114:117], v[178:181], v[186:189], v[114:117]
	v_mfma_f32_16x16x32_bf16 v[102:105], v[170:173], v[194:197], v[102:105]
	v_mfma_f32_16x16x32_bf16 v[98:101], v[178:181], v[194:197], v[98:101]
	v_mfma_f32_16x16x32_bf16 v[86:89], v[170:173], v[202:205], v[86:89]
	v_mfma_f32_16x16x32_bf16 v[82:85], v[178:181], v[202:205], v[82:85]
	v_mfma_f32_16x16x32_bf16 v[70:73], v[170:173], v[210:213], v[70:73]
	v_mfma_f32_16x16x32_bf16 v[66:69], v[178:181], v[210:213], v[66:69]
	v_mfma_f32_16x16x32_bf16 v[118:121], v[174:177], v[190:193], v[118:121]
	v_mfma_f32_16x16x32_bf16 v[114:117], v[182:185], v[190:193], v[114:117]
	v_mfma_f32_16x16x32_bf16 v[102:105], v[174:177], v[198:201], v[102:105]
	v_mfma_f32_16x16x32_bf16 v[98:101], v[182:185], v[198:201], v[98:101]
	v_mfma_f32_16x16x32_bf16 v[86:89], v[174:177], v[206:209], v[86:89]
	v_mfma_f32_16x16x32_bf16 v[82:85], v[182:185], v[206:209], v[82:85]
	v_mfma_f32_16x16x32_bf16 v[70:73], v[174:177], v[214:217], v[70:73]
	v_mfma_f32_16x16x32_bf16 v[66:69], v[182:185], v[214:217], v[66:69]
	s_setprio 0
	s_barrier
; #define PG8_STAGE(bufoff, gbase, voff) do { _Pragma("unroll") for (int _i = 0; _i < 2; ++_i) \
;         __builtin_amdgcn_global_load_lds((const unsigned*)((const char*)(gbase) + (voff)[_i]), (PG8_LAS unsigned*)(lds + (bufoff) + ldsw + _i * 8192), 16, 0, 0); } while (0)
; #define PG8_LDA(dst, b, h) do { _Pragma("unroll") for (int m = 0; m < 4; ++m) _Pragma("unroll") for (int k = 0; k < 2; ++k) dst[m][k] = *(const PG8_LAS bf16x8*)(lds + PG8_SA(b, h) + aoff + m * 2048 + k * 1024); } while (0)
; #define PG8_MMA(ai, bj, At, Bt) do { __builtin_amdgcn_s_setprio(1); _Pragma("unroll") for (int m = 0; m < 4; ++m) _Pragma("unroll") for (int n = 0; n < 2; ++n) _Pragma("unroll") for (int k = 0; k < 2; ++k) \
;         acc[ai][bj][m][n] = __builtin_amdgcn_mfma_f32_16x16x32_bf16(Bt[n][k], At[m][k], acc[ai][bj][m][n], 0, 0, 0); __builtin_amdgcn_s_setprio(0); } while (0)
; #define PG8_WAIT_V(n) asm volatile("s_waitcnt vmcnt(" #n ")" ::: "memory")
; #define PG8_WAIT_L(n) asm volatile("s_waitcnt lgkmcnt(" #n ")" ::: "memory")
; #define PG8_BAR __builtin_amdgcn_s_barrier()
; #define PG8_SCHED __builtin_amdgcn_sched_barrier(0)
; template <class Epi, class Sched, bool ALIGN_EPI = false, bool SP2 = false>
; __device__ __forceinline__ void gemm_phase(PG8_LAS unsigned char* lds, const Gemm g, const Sched& S, const Epi& E) {
;     ...
;         for (int t = 0; t < nt; t += 2) {
;     ...
;             PG8_LDA(At, 1, 1); PG8_STAGE(PG8_SB(1, 0), b3, voffB); PG8_STAGE(PG8_SB(1, 1), b3 + hstep, voffB); PG8_STAGE(PG8_SA(1, 0), a3, voffA);
;             PG8_WAIT_V(8); PG8_WAIT_L(0); PG8_BAR; PG8_MMA(1, 0, At, B0); PG8_MMA(1, 1, At, B1); PG8_BAR; PG8_SCHED;
	s_add_i32 s26, s55, s34
	s_nop 0
	s_nop 0
	s_mov_b32 m0, s26
	ds_read_b128 v[186:189], v152 offset:49152
	ds_read_b128 v[190:193], v152 offset:50176
	ds_read_b128 v[194:197], v152 offset:51200
	ds_read_b128 v[198:201], v152 offset:52224
	ds_read_b128 v[202:205], v152 offset:53248
	ds_read_b128 v[206:209], v152 offset:54272
	ds_read_b128 v[210:213], v152 offset:55296
	ds_read_b128 v[214:217], v152 offset:56320
	global_load_lds_dwordx4 v134, s[98:99]
	s_add_i32 m0, s26, 0x2000
	s_add_u32 s24, s24, 0x40080
	s_nop 0
	s_nop 0
	s_addc_u32 s25, s25, 0
	s_add_i32 s26, s56, s34
	global_load_lds_dwordx4 v130, s[98:99]
	s_nop 0
	s_nop 0
	s_mov_b32 m0, s26
	s_nop 0
	global_load_lds_dwordx4 v134, s[24:25]
	s_nop 0
	s_nop 0
	s_add_i32 m0, s26, 0x2000
	s_nop 0
	global_load_lds_dwordx4 v130, s[24:25]
	s_nop 0
	s_nop 0
	s_mov_b32 m0, s42
	s_nop 0
	global_load_lds_dwordx4 v136, s[100:101]
	s_nop 0
	s_nop 0
	s_mov_b32 m0, s43
	s_nop 0
	global_load_lds_dwordx4 v132, s[100:101]
	s_waitcnt vmcnt(8)
	s_waitcnt lgkmcnt(0)
	s_barrier
	s_setprio 1
	s_waitcnt lgkmcnt(0)
	v_mfma_f32_16x16x32_bf16 v[62:65], v[154:157], v[186:189], v[62:65]
	v_mfma_f32_16x16x32_bf16 v[58:61], v[162:165], v[186:189], v[58:61]
	v_mfma_f32_16x16x32_bf16 v[46:49], v[154:157], v[194:197], v[46:49]
	v_mfma_f32_16x16x32_bf16 v[42:45], v[162:165], v[194:197], v[42:45]
	v_mfma_f32_16x16x32_bf16 v[30:33], v[154:157], v[202:205], v[30:33]
	v_mfma_f32_16x16x32_bf16 v[26:29], v[162:165], v[202:205], v[26:29]
	v_mfma_f32_16x16x32_bf16 v[14:17], v[154:157], v[210:213], v[14:17]
	v_mfma_f32_16x16x32_bf16 v[10:13], v[162:165], v[210:213], v[10:13]
	v_mfma_f32_16x16x32_bf16 v[62:65], v[158:161], v[190:193], v[62:65]
	v_mfma_f32_16x16x32_bf16 v[58:61], v[166:169], v[190:193], v[58:61]
	v_mfma_f32_16x16x32_bf16 v[46:49], v[158:161], v[198:201], v[46:49]
	v_mfma_f32_16x16x32_bf16 v[42:45], v[166:169], v[198:201], v[42:45]
	v_mfma_f32_16x16x32_bf16 v[30:33], v[158:161], v[206:209], v[30:33]
	v_mfma_f32_16x16x32_bf16 v[26:29], v[166:169], v[206:209], v[26:29]
	v_mfma_f32_16x16x32_bf16 v[14:17], v[158:161], v[214:217], v[14:17]
	v_mfma_f32_16x16x32_bf16 v[10:13], v[166:169], v[214:217], v[10:13]
	s_setprio 0
	s_setprio 1
	v_mfma_f32_16x16x32_bf16 v[54:57], v[170:173], v[186:189], v[54:57]
	v_mfma_f32_16x16x32_bf16 v[50:53], v[178:181], v[186:189], v[50:53]
	v_mfma_f32_16x16x32_bf16 v[38:41], v[170:173], v[194:197], v[38:41]
	v_mfma_f32_16x16x32_bf16 v[34:37], v[178:181], v[194:197], v[34:37]
	v_mfma_f32_16x16x32_bf16 v[22:25], v[170:173], v[202:205], v[22:25]
	v_mfma_f32_16x16x32_bf16 v[18:21], v[178:181], v[202:205], v[18:21]
	v_mfma_f32_16x16x32_bf16 v[6:9], v[170:173], v[210:213], v[6:9]
	v_mfma_f32_16x16x32_bf16 v[2:5], v[178:181], v[210:213], v[2:5]
	v_mfma_f32_16x16x32_bf16 v[54:57], v[174:177], v[190:193], v[54:57]
	v_mfma_f32_16x16x32_bf16 v[50:53], v[182:185], v[190:193], v[50:53]
	v_mfma_f32_16x16x32_bf16 v[38:41], v[174:177], v[198:201], v[38:41]
	v_mfma_f32_16x16x32_bf16 v[34:37], v[182:185], v[198:201], v[34:37]
	v_mfma_f32_16x16x32_bf16 v[22:25], v[174:177], v[206:209], v[22:25]
	v_mfma_f32_16x16x32_bf16 v[18:21], v[182:185], v[206:209], v[18:21]
	v_mfma_f32_16x16x32_bf16 v[6:9], v[174:177], v[214:217], v[6:9]
	v_mfma_f32_16x16x32_bf16 v[2:5], v[182:185], v[214:217], v[2:5]
	s_setprio 0
	s_barrier
	s_add_i32 s54, s54, 2
	s_add_u32 s22, s22, 0x100
	s_addc_u32 s23, s23, 0
	s_add_u32 s52, s52, 0x100
	s_addc_u32 s53, s53, 0
	s_cmp_gt_u32 s54, 13
	s_cbranch_scc0 .LBB0_208
	s_and_b64 vcc, exec, s[10:11]
	s_cbranch_vccz .LBB0_211
	s_barrier

; #define PG8_STAGE(bufoff, gbase, voff) do { _Pragma("unroll") for (int _i = 0; _i < 2; ++_i) \
;         __builtin_amdgcn_global_load_lds((const unsigned*)((const char*)(gbase) + (voff)[_i]), (PG8_LAS unsigned*)(lds + (bufoff) + ldsw + _i * 8192), 16, 0, 0); } while (0)
; #define PG8_LDA(dst, b, h) do { _Pragma("unroll") for (int m = 0; m < 4; ++m) _Pragma("unroll") for (int k = 0; k < 2; ++k) dst[m][k] = *(const PG8_LAS bf16x8*)(lds + PG8_SA(b, h) + aoff + m * 2048 + k * 1024); } while (0)
; #define PG8_LDB(dst, b, h) do { _Pragma("unroll") for (int n = 0; n < 2; ++n) _Pragma("unroll") for (int k = 0; k < 2; ++k) dst[n][k] = *(const PG8_LAS bf16x8*)(lds + PG8_SB(b, h) + boff + n * 2048 + k * 1024); } while (0)
; #define PG8_MMA(ai, bj, At, Bt) do { __builtin_amdgcn_s_setprio(1); _Pragma("unroll") for (int m = 0; m < 4; ++m) _Pragma("unroll") for (int n = 0; n < 2; ++n) _Pragma("unroll") for (int k = 0; k < 2; ++k) \
;         acc[ai][bj][m][n] = __builtin_amdgcn_mfma_f32_16x16x32_bf16(Bt[n][k], At[m][k], acc[ai][bj][m][n], 0, 0, 0); __builtin_amdgcn_s_setprio(0); } while (0)
; #define PG8_WAIT_V(n) asm volatile("s_waitcnt vmcnt(" #n ")" ::: "memory")
; template <class Epi, class Sched, bool ALIGN_EPI = false, bool SP2 = false>
; __device__ __forceinline__ void gemm_phase(PG8_LAS unsigned char* lds, const Gemm g, const Sched& S, const Epi& E) {
;     ...
;             const bool last = (t == nt - 2);
;             const char* a1 = cA + (size_t)(t + 1) * kstepA;
;             const char* a2 = last ? nA : cA + (size_t)(t + 2) * kstepA; const char* b2 = last ? nB : cB + (size_t)(t + 2) * kstep;
;             const char* a3 = a2 + kstepA; const char* b3 = b2 + kstep;
;             if (last && has_next) S.a_ready(nxt);
;             if constexpr (SP2) {
;             PG8_LDB(B0, 0, 0); PG8_LDB(B1, 0, 1); PG8_SCHED; PG8_LDA(At, 0, 0); PG8_STAGE(PG8_SA(1, 1), a1 + hstep, voffA);
;             PG8_WAIT_V(8); PG8_WAIT_L(0); PG8_BAR; PG8_MMA(0, 0, At, B0); PG8_MMA(0, 1, At, B1); PG8_BAR; PG8_SCHED;
;             if constexpr (Epi::PREFETCH) { if (t == tpf) E.prefetch(cur, wid, lane); }
;             PG8_LDA(At, 0, 1); PG8_STAGE(PG8_SB(0, 0), b2, voffB); PG8_STAGE(PG8_SB(0, 1), b2 + hstep, voffB); PG8_STAGE(PG8_SA(0, 0), a2, voffA);
;             PG8_WAIT_V(8); PG8_WAIT_L(0); PG8_BAR; PG8_MMA(1, 0, At, B0); PG8_MMA(1, 1, At, B1); PG8_BAR; PG8_SCHED;
.LBB0_289:
	ds_read_b128 v[130:133], v223
	ds_read_b128 v[134:137], v223 offset:1024
	ds_read_b128 v[138:141], v223 offset:2048
	ds_read_b128 v[142:145], v223 offset:3072
	ds_read_b128 v[164:167], v224
	ds_read_b128 v[168:171], v224 offset:1024
	ds_read_b128 v[172:175], v224 offset:2048
	ds_read_b128 v[176:179], v224 offset:3072
	s_add_u32 s0, s4, 0x200
	s_addc_u32 s1, s5, 0
	s_cmp_eq_u32 s41, 40
	s_cselect_b32 s37, s31, s1
	s_cselect_b32 s36, s30, s0
	s_cselect_b32 s7, s35, s40
	s_cselect_b32 s6, s34, s39
	s_nop 0
	s_nop 0
	s_add_i32 m0, s51, 0xc000
	ds_read_b128 v[180:183], v225
	ds_read_b128 v[184:187], v225 offset:1024
	ds_read_b128 v[188:191], v225 offset:2048
	ds_read_b128 v[192:195], v225 offset:3072
	ds_read_b128 v[196:199], v225 offset:4096
	ds_read_b128 v[200:203], v225 offset:5120
	ds_read_b128 v[204:207], v225 offset:6144
	ds_read_b128 v[208:211], v225 offset:7168
	global_load_lds_dwordx4 v156, s[4:5]
	s_nop 0
	s_nop 0
	s_add_i32 m0, s51, 0xe000
	s_nop 0
	global_load_lds_dwordx4 v158, s[4:5]
	s_waitcnt vmcnt(8)
	s_waitcnt lgkmcnt(0)
	s_barrier
	s_setprio 1
	s_waitcnt lgkmcnt(0)
	v_mfma_f32_16x16x32_bf16 v[126:129], v[130:133], v[180:183], v[126:129]
	v_mfma_f32_16x16x32_bf16 v[122:125], v[138:141], v[180:183], v[122:125]
	v_mfma_f32_16x16x32_bf16 v[110:113], v[130:133], v[188:191], v[110:113]
	v_mfma_f32_16x16x32_bf16 v[106:109], v[138:141], v[188:191], v[106:109]
	v_mfma_f32_16x16x32_bf16 v[94:97], v[130:133], v[196:199], v[94:97]
	v_mfma_f32_16x16x32_bf16 v[90:93], v[138:141], v[196:199], v[90:93]
	v_mfma_f32_16x16x32_bf16 v[78:81], v[130:133], v[204:207], v[78:81]
	v_mfma_f32_16x16x32_bf16 v[74:77], v[138:141], v[204:207], v[74:77]
	v_mfma_f32_16x16x32_bf16 v[126:129], v[134:137], v[184:187], v[126:129]
	v_mfma_f32_16x16x32_bf16 v[122:125], v[142:145], v[184:187], v[122:125]
	v_mfma_f32_16x16x32_bf16 v[110:113], v[134:137], v[192:195], v[110:113]
	v_mfma_f32_16x16x32_bf16 v[106:109], v[142:145], v[192:195], v[106:109]
	v_mfma_f32_16x16x32_bf16 v[94:97], v[134:137], v[200:203], v[94:97]
	v_mfma_f32_16x16x32_bf16 v[90:93], v[142:145], v[200:203], v[90:93]
	v_mfma_f32_16x16x32_bf16 v[78:81], v[134:137], v[208:211], v[78:81]
	v_mfma_f32_16x16x32_bf16 v[74:77], v[142:145], v[208:211], v[74:77]
	s_setprio 0
	s_setprio 1
	v_mfma_f32_16x16x32_bf16 v[118:121], v[164:167], v[180:183], v[118:121]
	v_mfma_f32_16x16x32_bf16 v[114:117], v[172:175], v[180:183], v[114:117]
	v_mfma_f32_16x16x32_bf16 v[102:105], v[164:167], v[188:191], v[102:105]
	v_mfma_f32_16x16x32_bf16 v[98:101], v[172:175], v[188:191], v[98:101]
	v_mfma_f32_16x16x32_bf16 v[86:89], v[164:167], v[196:199], v[86:89]
	v_mfma_f32_16x16x32_bf16 v[82:85], v[172:175], v[196:199], v[82:85]
	v_mfma_f32_16x16x32_bf16 v[70:73], v[164:167], v[204:207], v[70:73]
	v_mfma_f32_16x16x32_bf16 v[66:69], v[172:175], v[204:207], v[66:69]
	v_mfma_f32_16x16x32_bf16 v[118:121], v[168:171], v[184:187], v[118:121]
	v_mfma_f32_16x16x32_bf16 v[114:117], v[176:179], v[184:187], v[114:117]
	v_mfma_f32_16x16x32_bf16 v[102:105], v[168:171], v[192:195], v[102:105]
	v_mfma_f32_16x16x32_bf16 v[98:101], v[176:179], v[192:195], v[98:101]
	v_mfma_f32_16x16x32_bf16 v[86:89], v[168:171], v[200:203], v[86:89]
	v_mfma_f32_16x16x32_bf16 v[82:85], v[176:179], v[200:203], v[82:85]
	v_mfma_f32_16x16x32_bf16 v[70:73], v[168:171], v[208:211], v[70:73]
	v_mfma_f32_16x16x32_bf16 v[66:69], v[176:179], v[208:211], v[66:69]
	s_setprio 0
	s_barrier
	s_add_i32 s4, s68, s50
	s_nop 0
	s_nop 0
	s_add_u32 s98, s6, s22
	s_addc_u32 s99, s7, s23
	s_mov_b32 m0, s4
	ds_read_b128 v[180:183], v225 offset:16384
	ds_read_b128 v[184:187], v225 offset:17408
	ds_read_b128 v[188:191], v225 offset:18432
	ds_read_b128 v[192:195], v225 offset:19456
	ds_read_b128 v[196:199], v225 offset:20480
	ds_read_b128 v[200:203], v225 offset:21504
	ds_read_b128 v[204:207], v225 offset:22528
	ds_read_b128 v[208:211], v225 offset:23552
	global_load_lds_dwordx4 v148, s[6:7]
	s_add_i32 m0, s4, 0x2000
	s_add_u32 s4, s6, 0xb0000
	s_nop 0
	s_nop 0
	s_addc_u32 s5, s7, 0
	s_add_i32 s42, s69, s50
	global_load_lds_dwordx4 v152, s[6:7]
	s_nop 0
	s_nop 0
	s_mov_b32 m0, s42
	s_nop 0
	s_nop 0
	global_load_lds_dwordx4 v148, s[4:5]
	s_nop 0
	s_nop 0
	s_add_i32 m0, s42, 0x2000
	s_nop 0
	global_load_lds_dwordx4 v152, s[4:5]
	s_nop 0
	s_nop 0
	s_add_u32 s100, s36, s24
	s_addc_u32 s101, s37, s25
	s_mov_b32 m0, s51
	s_nop 0
	global_load_lds_dwordx4 v146, s[36:37]
	s_mov_b32 m0, s52
	s_nop 0
	global_load_lds_dwordx4 v150, s[36:37]
	s_waitcnt vmcnt(8)
	s_waitcnt lgkmcnt(0)
	s_barrier
; #define PG8_STAGE(bufoff, gbase, voff) do { _Pragma("unroll") for (int _i = 0; _i < 2; ++_i) \
;         __builtin_amdgcn_global_load_lds((const unsigned*)((const char*)(gbase) + (voff)[_i]), (PG8_LAS unsigned*)(lds + (bufoff) + ldsw + _i * 8192), 16, 0, 0); } while (0)
; #define PG8_LDA(dst, b, h) do { _Pragma("unroll") for (int m = 0; m < 4; ++m) _Pragma("unroll") for (int k = 0; k < 2; ++k) dst[m][k] = *(const PG8_LAS bf16x8*)(lds + PG8_SA(b, h) + aoff + m * 2048 + k * 1024); } while (0)
; #define PG8_LDB(dst, b, h) do { _Pragma("unroll") for (int n = 0; n < 2; ++n) _Pragma("unroll") for (int k = 0; k < 2; ++k) dst[n][k] = *(const PG8_LAS bf16x8*)(lds + PG8_SB(b, h) + boff + n * 2048 + k * 1024); } while (0)
; #define PG8_MMA(ai, bj, At, Bt) do { __builtin_amdgcn_s_setprio(1); _Pragma("unroll") for (int m = 0; m < 4; ++m) _Pragma("unroll") for (int n = 0; n < 2; ++n) _Pragma("unroll") for (int k = 0; k < 2; ++k) \
;         acc[ai][bj][m][n] = __builtin_amdgcn_mfma_f32_16x16x32_bf16(Bt[n][k], At[m][k], acc[ai][bj][m][n], 0, 0, 0); __builtin_amdgcn_s_setprio(0); } while (0)
; #define PG8_WAIT_V(n) asm volatile("s_waitcnt vmcnt(" #n ")" ::: "memory")
; #define PG8_WAIT_L(n) asm volatile("s_waitcnt lgkmcnt(" #n ")" ::: "memory")
; #define PG8_BAR __builtin_amdgcn_s_barrier()
; #define PG8_SCHED __builtin_amdgcn_sched_barrier(0)
; template <class Epi, class Sched, bool ALIGN_EPI = false, bool SP2 = false>
; __device__ __forceinline__ void gemm_phase(PG8_LAS unsigned char* lds, const Gemm g, const Sched& S, const Epi& E) {
;     ...
;             PG8_WAIT_V(8); PG8_WAIT_L(0); PG8_BAR; PG8_MMA(1, 0, At, B0); PG8_MMA(1, 1, At, B1); PG8_BAR; PG8_SCHED;
;             PG8_LDB(B0, 1, 0); PG8_LDB(B1, 1, 1); PG8_SCHED; PG8_LDA(At, 1, 0); PG8_STAGE(PG8_SA(0, 1), a2 + hstep, voffA);
;             PG8_WAIT_V(8); PG8_WAIT_L(0); PG8_BAR; PG8_MMA(0, 0, At, B0); PG8_MMA(0, 1, At, B1); PG8_BAR; PG8_SCHED;
	s_setprio 1
	s_waitcnt lgkmcnt(0)
	v_mfma_f32_16x16x32_bf16 v[62:65], v[130:133], v[180:183], v[62:65]
	v_mfma_f32_16x16x32_bf16 v[58:61], v[138:141], v[180:183], v[58:61]
	v_mfma_f32_16x16x32_bf16 v[46:49], v[130:133], v[188:191], v[46:49]
	v_mfma_f32_16x16x32_bf16 v[42:45], v[138:141], v[188:191], v[42:45]
	v_mfma_f32_16x16x32_bf16 v[30:33], v[130:133], v[196:199], v[30:33]
	v_mfma_f32_16x16x32_bf16 v[26:29], v[138:141], v[196:199], v[26:29]
	v_mfma_f32_16x16x32_bf16 v[14:17], v[130:133], v[204:207], v[14:17]
	v_mfma_f32_16x16x32_bf16 v[10:13], v[138:141], v[204:207], v[10:13]
	v_mfma_f32_16x16x32_bf16 v[62:65], v[134:137], v[184:187], v[62:65]
	v_mfma_f32_16x16x32_bf16 v[58:61], v[142:145], v[184:187], v[58:61]
	v_mfma_f32_16x16x32_bf16 v[46:49], v[134:137], v[192:195], v[46:49]
	v_mfma_f32_16x16x32_bf16 v[42:45], v[142:145], v[192:195], v[42:45]
	v_mfma_f32_16x16x32_bf16 v[30:33], v[134:137], v[200:203], v[30:33]
	v_mfma_f32_16x16x32_bf16 v[26:29], v[142:145], v[200:203], v[26:29]
	v_mfma_f32_16x16x32_bf16 v[14:17], v[134:137], v[208:211], v[14:17]
	v_mfma_f32_16x16x32_bf16 v[10:13], v[142:145], v[208:211], v[10:13]
	s_setprio 0
	s_setprio 1
	v_mfma_f32_16x16x32_bf16 v[54:57], v[164:167], v[180:183], v[54:57]
	v_mfma_f32_16x16x32_bf16 v[50:53], v[172:175], v[180:183], v[50:53]
	v_mfma_f32_16x16x32_bf16 v[38:41], v[164:167], v[188:191], v[38:41]
	v_mfma_f32_16x16x32_bf16 v[34:37], v[172:175], v[188:191], v[34:37]
	v_mfma_f32_16x16x32_bf16 v[22:25], v[164:167], v[196:199], v[22:25]
	v_mfma_f32_16x16x32_bf16 v[18:21], v[172:175], v[196:199], v[18:21]
	v_mfma_f32_16x16x32_bf16 v[6:9], v[164:167], v[204:207], v[6:9]
	v_mfma_f32_16x16x32_bf16 v[2:5], v[172:175], v[204:207], v[2:5]
	v_mfma_f32_16x16x32_bf16 v[54:57], v[168:171], v[184:187], v[54:57]
	v_mfma_f32_16x16x32_bf16 v[50:53], v[176:179], v[184:187], v[50:53]
	v_mfma_f32_16x16x32_bf16 v[38:41], v[168:171], v[192:195], v[38:41]
	v_mfma_f32_16x16x32_bf16 v[34:37], v[176:179], v[192:195], v[34:37]
	v_mfma_f32_16x16x32_bf16 v[22:25], v[168:171], v[200:203], v[22:25]
	v_mfma_f32_16x16x32_bf16 v[18:21], v[176:179], v[200:203], v[18:21]
	v_mfma_f32_16x16x32_bf16 v[6:9], v[168:171], v[208:211], v[6:9]
	v_mfma_f32_16x16x32_bf16 v[2:5], v[176:179], v[208:211], v[2:5]
	s_setprio 0
	s_barrier
	s_add_i32 s42, 0, 0x18000
	s_add_i32 s43, 0, 0x1c000
	v_add_u32_e32 v142, s42, v222
	v_add_u32_e32 v154, s43, v222
	ds_read_b128 v[130:133], v142
	ds_read_b128 v[134:137], v142 offset:1024
	ds_read_b128 v[138:141], v142 offset:2048
	ds_read_b128 v[142:145], v142 offset:3072
	ds_read_b128 v[164:167], v154
	ds_read_b128 v[168:171], v154 offset:1024
	ds_read_b128 v[172:175], v154 offset:2048
	ds_read_b128 v[176:179], v154 offset:3072
	s_add_u32 s4, s36, 0xb0000
	s_addc_u32 s5, s37, 0
	s_mov_b32 m0, s53
	s_nop 0
	s_nop 0
	ds_read_b128 v[180:183], v225 offset:32768
	ds_read_b128 v[184:187], v225 offset:33792
	ds_read_b128 v[188:191], v225 offset:34816
	ds_read_b128 v[192:195], v225 offset:35840
	ds_read_b128 v[196:199], v225 offset:36864
	ds_read_b128 v[200:203], v225 offset:37888
	ds_read_b128 v[204:207], v225 offset:38912
	ds_read_b128 v[208:211], v225 offset:39936
	global_load_lds_dwordx4 v146, s[4:5]
	s_nop 0
	s_nop 0
	s_mov_b32 m0, s54
	s_nop 0
	global_load_lds_dwordx4 v150, s[4:5]
	s_waitcnt vmcnt(8)
	s_waitcnt lgkmcnt(0)
	s_barrier
	s_setprio 1
	s_waitcnt lgkmcnt(0)
	v_mfma_f32_16x16x32_bf16 v[126:129], v[130:133], v[180:183], v[126:129]
	v_mfma_f32_16x16x32_bf16 v[122:125], v[138:141], v[180:183], v[122:125]
	v_mfma_f32_16x16x32_bf16 v[110:113], v[130:133], v[188:191], v[110:113]
	v_mfma_f32_16x16x32_bf16 v[106:109], v[138:141], v[188:191], v[106:109]
	v_mfma_f32_16x16x32_bf16 v[94:97], v[130:133], v[196:199], v[94:97]
	v_mfma_f32_16x16x32_bf16 v[90:93], v[138:141], v[196:199], v[90:93]
	v_mfma_f32_16x16x32_bf16 v[78:81], v[130:133], v[204:207], v[78:81]
	v_mfma_f32_16x16x32_bf16 v[74:77], v[138:141], v[204:207], v[74:77]
	v_mfma_f32_16x16x32_bf16 v[126:129], v[134:137], v[184:187], v[126:129]
	v_mfma_f32_16x16x32_bf16 v[122:125], v[142:145], v[184:187], v[122:125]
	v_mfma_f32_16x16x32_bf16 v[110:113], v[134:137], v[192:195], v[110:113]
	v_mfma_f32_16x16x32_bf16 v[106:109], v[142:145], v[192:195], v[106:109]
	v_mfma_f32_16x16x32_bf16 v[94:97], v[134:137], v[200:203], v[94:97]
	v_mfma_f32_16x16x32_bf16 v[90:93], v[142:145], v[200:203], v[90:93]
	v_mfma_f32_16x16x32_bf16 v[78:81], v[134:137], v[208:211], v[78:81]
	v_mfma_f32_16x16x32_bf16 v[74:77], v[142:145], v[208:211], v[74:77]
	s_setprio 0
	s_setprio 1
	v_mfma_f32_16x16x32_bf16 v[118:121], v[164:167], v[180:183], v[118:121]
	v_mfma_f32_16x16x32_bf16 v[114:117], v[172:175], v[180:183], v[114:117]
	v_mfma_f32_16x16x32_bf16 v[102:105], v[164:167], v[188:191], v[102:105]
	v_mfma_f32_16x16x32_bf16 v[98:101], v[172:175], v[188:191], v[98:101]
	v_mfma_f32_16x16x32_bf16 v[86:89], v[164:167], v[196:199], v[86:89]
	v_mfma_f32_16x16x32_bf16 v[82:85], v[172:175], v[196:199], v[82:85]
	v_mfma_f32_16x16x32_bf16 v[70:73], v[164:167], v[204:207], v[70:73]
	v_mfma_f32_16x16x32_bf16 v[66:69], v[172:175], v[204:207], v[66:69]
	v_mfma_f32_16x16x32_bf16 v[118:121], v[168:171], v[184:187], v[118:121]
	v_mfma_f32_16x16x32_bf16 v[114:117], v[176:179], v[184:187], v[114:117]
	v_mfma_f32_16x16x32_bf16 v[102:105], v[168:171], v[192:195], v[102:105]
	v_mfma_f32_16x16x32_bf16 v[98:101], v[176:179], v[192:195], v[98:101]
	v_mfma_f32_16x16x32_bf16 v[86:89], v[168:171], v[200:203], v[86:89]
	v_mfma_f32_16x16x32_bf16 v[82:85], v[176:179], v[200:203], v[82:85]
	v_mfma_f32_16x16x32_bf16 v[70:73], v[168:171], v[208:211], v[70:73]
	v_mfma_f32_16x16x32_bf16 v[66:69], v[176:179], v[208:211], v[66:69]
	s_setprio 0
	s_barrier
; #define PG8_STAGE(bufoff, gbase, voff) do { _Pragma("unroll") for (int _i = 0; _i < 2; ++_i) \
;         __builtin_amdgcn_global_load_lds((const unsigned*)((const char*)(gbase) + (voff)[_i]), (PG8_LAS unsigned*)(lds + (bufoff) + ldsw + _i * 8192), 16, 0, 0); } while (0)
; #define PG8_LDA(dst, b, h) do { _Pragma("unroll") for (int m = 0; m < 4; ++m) _Pragma("unroll") for (int k = 0; k < 2; ++k) dst[m][k] = *(const PG8_LAS bf16x8*)(lds + PG8_SA(b, h) + aoff + m * 2048 + k * 1024); } while (0)
; #define PG8_MMA(ai, bj, At, Bt) do { __builtin_amdgcn_s_setprio(1); _Pragma("unroll") for (int m = 0; m < 4; ++m) _Pragma("unroll") for (int n = 0; n < 2; ++n) _Pragma("unroll") for (int k = 0; k < 2; ++k) \
;         acc[ai][bj][m][n] = __builtin_amdgcn_mfma_f32_16x16x32_bf16(Bt[n][k], At[m][k], acc[ai][bj][m][n], 0, 0, 0); __builtin_amdgcn_s_setprio(0); } while (0)
; #define PG8_WAIT_V(n) asm volatile("s_waitcnt vmcnt(" #n ")" ::: "memory")
; #define PG8_WAIT_L(n) asm volatile("s_waitcnt lgkmcnt(" #n ")" ::: "memory")
; #define PG8_BAR __builtin_amdgcn_s_barrier()
; #define PG8_SCHED __builtin_amdgcn_sched_barrier(0)
; template <class Epi, class Sched, bool ALIGN_EPI = false, bool SP2 = false>
; __device__ __forceinline__ void gemm_phase(PG8_LAS unsigned char* lds, const Gemm g, const Sched& S, const Epi& E) {
;     ...
;         for (int t = 0; t < nt; t += 2) {
;     ...
;             PG8_LDA(At, 1, 1); PG8_STAGE(PG8_SB(1, 0), b3, voffB); PG8_STAGE(PG8_SB(1, 1), b3 + hstep, voffB); PG8_STAGE(PG8_SA(1, 0), a3, voffA);
;             PG8_WAIT_V(8); PG8_WAIT_L(0); PG8_BAR; PG8_MMA(1, 0, At, B0); PG8_MMA(1, 1, At, B1); PG8_BAR; PG8_SCHED;
	s_add_i32 s4, s42, s50
	s_nop 0
	s_nop 0
	s_mov_b32 m0, s4
	ds_read_b128 v[180:183], v225 offset:49152
	ds_read_b128 v[184:187], v225 offset:50176
	ds_read_b128 v[188:191], v225 offset:51200
	ds_read_b128 v[192:195], v225 offset:52224
	ds_read_b128 v[196:199], v225 offset:53248
	ds_read_b128 v[200:203], v225 offset:54272
	ds_read_b128 v[204:207], v225 offset:55296
	ds_read_b128 v[208:211], v225 offset:56320
	global_load_lds_dwordx4 v148, s[98:99]
	s_add_i32 m0, s4, 0x2000
	s_add_u32 s4, s6, 0xb0080
	s_nop 0
	s_nop 0
	s_addc_u32 s5, s7, 0
	s_add_i32 s6, s43, s50
	global_load_lds_dwordx4 v152, s[98:99]
	s_nop 0
	s_nop 0
	s_mov_b32 m0, s6
	s_nop 0
	global_load_lds_dwordx4 v148, s[4:5]
	s_nop 0
	s_nop 0
	s_add_i32 m0, s6, 0x2000
	s_nop 0
	global_load_lds_dwordx4 v152, s[4:5]
	s_nop 0
	s_nop 0
	s_mov_b32 m0, s63
	s_nop 0
	global_load_lds_dwordx4 v146, s[100:101]
	s_nop 0
	s_nop 0
	s_mov_b32 m0, s64
	s_nop 0
	global_load_lds_dwordx4 v150, s[100:101]
	s_waitcnt vmcnt(8)
	s_waitcnt lgkmcnt(0)
	s_barrier
	s_setprio 1
	s_waitcnt lgkmcnt(0)
	v_mfma_f32_16x16x32_bf16 v[62:65], v[130:133], v[180:183], v[62:65]
	v_mfma_f32_16x16x32_bf16 v[58:61], v[138:141], v[180:183], v[58:61]
	v_mfma_f32_16x16x32_bf16 v[46:49], v[130:133], v[188:191], v[46:49]
	v_mfma_f32_16x16x32_bf16 v[42:45], v[138:141], v[188:191], v[42:45]
	v_mfma_f32_16x16x32_bf16 v[30:33], v[130:133], v[196:199], v[30:33]
	v_mfma_f32_16x16x32_bf16 v[26:29], v[138:141], v[196:199], v[26:29]
	v_mfma_f32_16x16x32_bf16 v[14:17], v[130:133], v[204:207], v[14:17]
	v_mfma_f32_16x16x32_bf16 v[10:13], v[138:141], v[204:207], v[10:13]
	v_mfma_f32_16x16x32_bf16 v[62:65], v[134:137], v[184:187], v[62:65]
	v_mfma_f32_16x16x32_bf16 v[58:61], v[142:145], v[184:187], v[58:61]
	v_mfma_f32_16x16x32_bf16 v[46:49], v[134:137], v[192:195], v[46:49]
	v_mfma_f32_16x16x32_bf16 v[42:45], v[142:145], v[192:195], v[42:45]
	v_mfma_f32_16x16x32_bf16 v[30:33], v[134:137], v[200:203], v[30:33]
	v_mfma_f32_16x16x32_bf16 v[26:29], v[142:145], v[200:203], v[26:29]
	v_mfma_f32_16x16x32_bf16 v[14:17], v[134:137], v[208:211], v[14:17]
	v_mfma_f32_16x16x32_bf16 v[10:13], v[142:145], v[208:211], v[10:13]
	s_setprio 0
	s_setprio 1
	v_mfma_f32_16x16x32_bf16 v[54:57], v[164:167], v[180:183], v[54:57]
	v_mfma_f32_16x16x32_bf16 v[50:53], v[172:175], v[180:183], v[50:53]
	v_mfma_f32_16x16x32_bf16 v[38:41], v[164:167], v[188:191], v[38:41]
	v_mfma_f32_16x16x32_bf16 v[34:37], v[172:175], v[188:191], v[34:37]
	v_mfma_f32_16x16x32_bf16 v[22:25], v[164:167], v[196:199], v[22:25]
	v_mfma_f32_16x16x32_bf16 v[18:21], v[172:175], v[196:199], v[18:21]
	v_mfma_f32_16x16x32_bf16 v[6:9], v[164:167], v[204:207], v[6:9]
	v_mfma_f32_16x16x32_bf16 v[2:5], v[172:175], v[204:207], v[2:5]
	v_mfma_f32_16x16x32_bf16 v[54:57], v[168:171], v[184:187], v[54:57]
	v_mfma_f32_16x16x32_bf16 v[50:53], v[176:179], v[184:187], v[50:53]
	v_mfma_f32_16x16x32_bf16 v[38:41], v[168:171], v[192:195], v[38:41]
	v_mfma_f32_16x16x32_bf16 v[34:37], v[176:179], v[192:195], v[34:37]
	v_mfma_f32_16x16x32_bf16 v[22:25], v[168:171], v[200:203], v[22:25]
	v_mfma_f32_16x16x32_bf16 v[18:21], v[176:179], v[200:203], v[18:21]
	v_mfma_f32_16x16x32_bf16 v[6:9], v[168:171], v[208:211], v[6:9]
	v_mfma_f32_16x16x32_bf16 v[2:5], v[176:179], v[208:211], v[2:5]
	s_setprio 0
	s_barrier
	s_add_i32 s41, s41, 2
	s_add_u32 s39, s39, 0x100
	s_addc_u32 s40, s40, 0
	s_cmp_gt_u32 s41, 41
	s_mov_b64 s[4:5], s[0:1]
	s_cbranch_scc0 .LBB0_289
	s_and_b64 vcc, exec, s[26:27]
	s_cbranch_vccz .LBB0_292
	s_barrier

; #define PG8_STAGE(bufoff, gbase, voff) do { _Pragma("unroll") for (int _i = 0; _i < 2; ++_i) \
;         __builtin_amdgcn_global_load_lds((const unsigned*)((const char*)(gbase) + (voff)[_i]), (PG8_LAS unsigned*)(lds + (bufoff) + ldsw + _i * 8192), 16, 0, 0); } while (0)
; #define PG8_LDA(dst, b, h) do { _Pragma("unroll") for (int m = 0; m < 4; ++m) _Pragma("unroll") for (int k = 0; k < 2; ++k) dst[m][k] = *(const PG8_LAS bf16x8*)(lds + PG8_SA(b, h) + aoff + m * 2048 + k * 1024); } while (0)
; #define PG8_LDB(dst, b, h) do { _Pragma("unroll") for (int n = 0; n < 2; ++n) _Pragma("unroll") for (int k = 0; k < 2; ++k) dst[n][k] = *(const PG8_LAS bf16x8*)(lds + PG8_SB(b, h) + boff + n * 2048 + k * 1024); } while (0)
; #define PG8_MMA(ai, bj, At, Bt) do { __builtin_amdgcn_s_setprio(1); _Pragma("unroll") for (int m = 0; m < 4; ++m) _Pragma("unroll") for (int n = 0; n < 2; ++n) _Pragma("unroll") for (int k = 0; k < 2; ++k) \
;         acc[ai][bj][m][n] = __builtin_amdgcn_mfma_f32_16x16x32_bf16(Bt[n][k], At[m][k], acc[ai][bj][m][n], 0, 0, 0); __builtin_amdgcn_s_setprio(0); } while (0)
; #define PG8_WAIT_V(n) asm volatile("s_waitcnt vmcnt(" #n ")" ::: "memory")
; #define PG8_WAIT_L(n) asm volatile("s_waitcnt lgkmcnt(" #n ")" ::: "memory")
; #define PG8_BAR __builtin_amdgcn_s_barrier()
; #define PG8_SCHED __builtin_amdgcn_sched_barrier(0)
; template <class Epi, class Sched, bool ALIGN_EPI = false, bool SP2 = false>
; __device__ __forceinline__ void gemm_phase(PG8_LAS unsigned char* lds, const Gemm g, const Sched& S, const Epi& E) {
;     ...
;             PG8_LDA(At, 0, 1); PG8_STAGE(PG8_SB(0, 0), b2, voffB); PG8_STAGE(PG8_SB(0, 1), b2 + hstep, voffB); PG8_STAGE(PG8_SA(0, 0), a2, voffA);
;             PG8_WAIT_V(8); PG8_WAIT_L(0); PG8_BAR; PG8_MMA(1, 0, At, B0); PG8_MMA(1, 1, At, B1); PG8_BAR; PG8_SCHED;
;             PG8_LDB(B0, 1, 0); PG8_LDB(B1, 1, 1); PG8_SCHED; PG8_LDA(At, 1, 0); PG8_STAGE(PG8_SA(0, 1), a2 + hstep, voffA);
;             PG8_WAIT_V(8); PG8_WAIT_L(0); PG8_BAR; PG8_MMA(0, 0, At, B0); PG8_MMA(0, 1, At, B1); PG8_BAR; PG8_SCHED;
.LBB0_438:
	s_add_u32 s29, s10, s56
	s_addc_u32 s58, s11, s57
	s_add_u32 s29, s29, 0x100
	s_addc_u32 s58, s58, 0
	s_add_u32 vcc_lo, s5, s56
	s_addc_u32 s59, s9, s57
	s_cmpk_eq_i32 s56, 0x700
	s_cselect_b32 s61, s7, s58
	s_cselect_b32 s59, s45, s59
	s_cselect_b32 s58, s47, vcc_lo
	s_mov_b32 m0, s70
	s_cselect_b32 s60, s31, s29
	s_nop 0
	s_nop 0
	s_add_u32 s98, s58, s38
	s_addc_u32 s99, s59, s39
	s_add_u32 vcc_lo, s58, 0x40000
	ds_read_b128 v[122:125], v210 offset:16384
	ds_read_b128 v[126:129], v210 offset:17408
	ds_read_b128 v[138:141], v210 offset:18432
	ds_read_b128 v[142:145], v210 offset:19456
	ds_read_b128 v[212:215], v210 offset:20480
	ds_read_b128 v[216:219], v210 offset:21504
	ds_read_b128 v[222:225], v210 offset:22528
	ds_read_b128 v[226:229], v210 offset:23552
	global_load_lds_dwordx4 v180, s[58:59]
	s_nop 0
	s_nop 0
	s_mov_b32 m0, s71
	s_addc_u32 vcc_hi, s59, 0
	global_load_lds_dwordx4 v184, s[58:59]
	v_lshl_add_u64 v[230:231], vcc, 0, v[180:181]
	s_mov_b32 m0, s72
	s_nop 0
	s_nop 0
	s_add_u32 s100, s60, s38
	s_addc_u32 s101, s61, s39
	global_load_lds_dwordx4 v[230:231], off
	v_lshl_add_u64 v[230:231], vcc, 0, v[184:185]
	s_mov_b32 m0, s73
	s_nop 0
	s_nop 0
	global_load_lds_dwordx4 v[230:231], off
	s_mov_b32 m0, s69
	s_nop 0
	global_load_lds_dwordx4 v178, s[60:61]
	s_mov_b32 m0, s74
	s_nop 0
	global_load_lds_dwordx4 v182, s[60:61]
	s_waitcnt vmcnt(8)
	s_waitcnt lgkmcnt(0)
	s_barrier
	s_setprio 1
	s_waitcnt lgkmcnt(0)
	v_mfma_f32_16x16x32_bf16 v[78:81], v[162:165], v[122:125], v[78:81]
	v_mfma_f32_16x16x32_bf16 v[74:77], v[170:173], v[122:125], v[74:77]
	v_mfma_f32_16x16x32_bf16 v[62:65], v[162:165], v[138:141], v[62:65]
	v_mfma_f32_16x16x32_bf16 v[58:61], v[170:173], v[138:141], v[58:61]
	v_mfma_f32_16x16x32_bf16 v[30:33], v[162:165], v[212:215], v[30:33]
	v_mfma_f32_16x16x32_bf16 v[26:29], v[170:173], v[212:215], v[26:29]
	v_mfma_f32_16x16x32_bf16 v[14:17], v[162:165], v[222:225], v[14:17]
	v_mfma_f32_16x16x32_bf16 v[10:13], v[170:173], v[222:225], v[10:13]
	v_mfma_f32_16x16x32_bf16 v[78:81], v[166:169], v[126:129], v[78:81]
	v_mfma_f32_16x16x32_bf16 v[74:77], v[174:177], v[126:129], v[74:77]
	v_mfma_f32_16x16x32_bf16 v[62:65], v[166:169], v[142:145], v[62:65]
	v_mfma_f32_16x16x32_bf16 v[58:61], v[174:177], v[142:145], v[58:61]
	v_mfma_f32_16x16x32_bf16 v[30:33], v[166:169], v[216:219], v[30:33]
	v_mfma_f32_16x16x32_bf16 v[26:29], v[174:177], v[216:219], v[26:29]
	v_mfma_f32_16x16x32_bf16 v[14:17], v[166:169], v[226:229], v[14:17]
	v_mfma_f32_16x16x32_bf16 v[10:13], v[174:177], v[226:229], v[10:13]
	s_setprio 0
	s_setprio 1
	v_mfma_f32_16x16x32_bf16 v[70:73], v[146:149], v[122:125], v[70:73]
	v_mfma_f32_16x16x32_bf16 v[66:69], v[154:157], v[122:125], v[66:69]
	v_mfma_f32_16x16x32_bf16 v[38:41], v[146:149], v[138:141], v[38:41]
	v_mfma_f32_16x16x32_bf16 v[34:37], v[154:157], v[138:141], v[34:37]
	v_mfma_f32_16x16x32_bf16 v[22:25], v[146:149], v[212:215], v[22:25]
	v_mfma_f32_16x16x32_bf16 v[18:21], v[154:157], v[212:215], v[18:21]
	v_mfma_f32_16x16x32_bf16 v[6:9], v[146:149], v[222:225], v[6:9]
	v_mfma_f32_16x16x32_bf16 v[2:5], v[154:157], v[222:225], v[2:5]
	v_mfma_f32_16x16x32_bf16 v[70:73], v[150:153], v[126:129], v[70:73]
	v_mfma_f32_16x16x32_bf16 v[66:69], v[158:161], v[126:129], v[66:69]
	v_mfma_f32_16x16x32_bf16 v[38:41], v[150:153], v[142:145], v[38:41]
	v_mfma_f32_16x16x32_bf16 v[34:37], v[158:161], v[142:145], v[34:37]
	v_mfma_f32_16x16x32_bf16 v[22:25], v[150:153], v[216:219], v[22:25]
	v_mfma_f32_16x16x32_bf16 v[18:21], v[158:161], v[216:219], v[18:21]
	v_mfma_f32_16x16x32_bf16 v[6:9], v[150:153], v[226:229], v[6:9]
	v_mfma_f32_16x16x32_bf16 v[2:5], v[158:161], v[226:229], v[2:5]
	s_setprio 0
	s_barrier
	s_add_i32 s29, 0, 0x18000
	v_add_u32_e32 v122, s29, v203
	s_add_i32 vcc_lo, 0, 0x1c000
	ds_read_b128 v[146:149], v122
	ds_read_b128 v[150:153], v122 offset:1024
	ds_read_b128 v[154:157], v122 offset:2048
	ds_read_b128 v[158:161], v122 offset:3072
	v_add_u32_e32 v122, vcc_lo, v203
	ds_read_b128 v[162:165], v122
	ds_read_b128 v[166:169], v122 offset:1024
	ds_read_b128 v[170:173], v122 offset:2048
	ds_read_b128 v[174:177], v122 offset:3072
	s_add_u32 s60, s60, 0x40000
	s_addc_u32 s61, s61, 0
	s_mov_b32 m0, s75
	s_nop 0
	s_nop 0
	ds_read_b128 v[212:215], v210 offset:32768
	ds_read_b128 v[216:219], v210 offset:33792
	ds_read_b128 v[222:225], v210 offset:34816
	ds_read_b128 v[226:229], v210 offset:35840
	ds_read_b128 v[230:233], v210 offset:36864
	ds_read_b128 v[234:237], v210 offset:37888
	ds_read_b128 v[238:241], v210 offset:38912
	ds_read_b128 v[242:245], v210 offset:39936
	global_load_lds_dwordx4 v178, s[60:61]
	s_nop 0
	s_nop 0
	s_mov_b32 m0, s76
	s_nop 0
	global_load_lds_dwordx4 v182, s[60:61]
	s_waitcnt vmcnt(8)
	s_waitcnt lgkmcnt(0)
	s_barrier
; #define PG8_STAGE(bufoff, gbase, voff) do { _Pragma("unroll") for (int _i = 0; _i < 2; ++_i) \
;         __builtin_amdgcn_global_load_lds((const unsigned*)((const char*)(gbase) + (voff)[_i]), (PG8_LAS unsigned*)(lds + (bufoff) + ldsw + _i * 8192), 16, 0, 0); } while (0)
; #define PG8_LDA(dst, b, h) do { _Pragma("unroll") for (int m = 0; m < 4; ++m) _Pragma("unroll") for (int k = 0; k < 2; ++k) dst[m][k] = *(const PG8_LAS bf16x8*)(lds + PG8_SA(b, h) + aoff + m * 2048 + k * 1024); } while (0)
; #define PG8_MMA(ai, bj, At, Bt) do { __builtin_amdgcn_s_setprio(1); _Pragma("unroll") for (int m = 0; m < 4; ++m) _Pragma("unroll") for (int n = 0; n < 2; ++n) _Pragma("unroll") for (int k = 0; k < 2; ++k) \
;         acc[ai][bj][m][n] = __builtin_amdgcn_mfma_f32_16x16x32_bf16(Bt[n][k], At[m][k], acc[ai][bj][m][n], 0, 0, 0); __builtin_amdgcn_s_setprio(0); } while (0)
; #define PG8_WAIT_V(n) asm volatile("s_waitcnt vmcnt(" #n ")" ::: "memory")
; #define PG8_WAIT_L(n) asm volatile("s_waitcnt lgkmcnt(" #n ")" ::: "memory")
; #define PG8_BAR __builtin_amdgcn_s_barrier()
; #define PG8_SCHED __builtin_amdgcn_sched_barrier(0)
; template <class Epi, class Sched, bool ALIGN_EPI = false, bool SP2 = false>
; __device__ __forceinline__ void gemm_phase(PG8_LAS unsigned char* lds, const Gemm g, const Sched& S, const Epi& E) {
;     ...
;             PG8_WAIT_V(8); PG8_WAIT_L(0); PG8_BAR; PG8_MMA(0, 0, At, B0); PG8_MMA(0, 1, At, B1); PG8_BAR; PG8_SCHED;
;             PG8_LDA(At, 1, 1); PG8_STAGE(PG8_SB(1, 0), b3, voffB); PG8_STAGE(PG8_SB(1, 1), b3 + hstep, voffB); PG8_STAGE(PG8_SA(1, 0), a3, voffA);
;             PG8_WAIT_V(8); PG8_WAIT_L(0); PG8_BAR; PG8_MMA(1, 0, At, B0); PG8_MMA(1, 1, At, B1); PG8_BAR; PG8_SCHED;
	s_setprio 1
	s_waitcnt lgkmcnt(0)
	v_mfma_f32_16x16x32_bf16 v[42:45], v[146:149], v[212:215], v[42:45]
	v_mfma_f32_16x16x32_bf16 v[142:145], v[150:153], v[216:219], v[42:45]
	v_mfma_f32_16x16x32_bf16 v[42:45], v[154:157], v[212:215], v[46:49]
	v_mfma_f32_16x16x32_bf16 v[138:141], v[158:161], v[216:219], v[42:45]
	v_mfma_f32_16x16x32_bf16 v[42:45], v[146:149], v[222:225], v[50:53]
	v_mfma_f32_16x16x32_bf16 v[126:129], v[150:153], v[226:229], v[42:45]
	v_mfma_f32_16x16x32_bf16 v[42:45], v[154:157], v[222:225], v[54:57]
	v_mfma_f32_16x16x32_bf16 v[122:125], v[158:161], v[226:229], v[42:45]
	v_mfma_f32_16x16x32_bf16 v[42:45], v[146:149], v[230:233], v[110:113]
	v_mfma_f32_16x16x32_bf16 v[110:113], v[150:153], v[234:237], v[42:45]
	v_mfma_f32_16x16x32_bf16 v[42:45], v[154:157], v[230:233], v[106:109]
	v_mfma_f32_16x16x32_bf16 v[106:109], v[158:161], v[234:237], v[42:45]
	v_mfma_f32_16x16x32_bf16 v[42:45], v[146:149], v[238:241], v[94:97]
	v_mfma_f32_16x16x32_bf16 v[94:97], v[150:153], v[242:245], v[42:45]
	v_mfma_f32_16x16x32_bf16 v[42:45], v[154:157], v[238:241], v[90:93]
	v_mfma_f32_16x16x32_bf16 v[90:93], v[158:161], v[242:245], v[42:45]
	s_setprio 0
	s_setprio 1
	v_mfma_f32_16x16x32_bf16 v[42:45], v[162:165], v[212:215], v[134:137]
	v_mfma_f32_16x16x32_bf16 v[134:137], v[166:169], v[216:219], v[42:45]
	v_mfma_f32_16x16x32_bf16 v[42:45], v[170:173], v[212:215], v[130:133]
	v_mfma_f32_16x16x32_bf16 v[130:133], v[174:177], v[216:219], v[42:45]
	v_mfma_f32_16x16x32_bf16 v[42:45], v[162:165], v[222:225], v[118:121]
	v_mfma_f32_16x16x32_bf16 v[118:121], v[166:169], v[226:229], v[42:45]
	v_mfma_f32_16x16x32_bf16 v[42:45], v[170:173], v[222:225], v[114:117]
	v_mfma_f32_16x16x32_bf16 v[114:117], v[174:177], v[226:229], v[42:45]
	v_mfma_f32_16x16x32_bf16 v[42:45], v[162:165], v[230:233], v[102:105]
	v_mfma_f32_16x16x32_bf16 v[102:105], v[166:169], v[234:237], v[42:45]
	v_mfma_f32_16x16x32_bf16 v[42:45], v[170:173], v[230:233], v[98:101]
	v_mfma_f32_16x16x32_bf16 v[98:101], v[174:177], v[234:237], v[42:45]
	v_mfma_f32_16x16x32_bf16 v[42:45], v[162:165], v[238:241], v[86:89]
	v_mfma_f32_16x16x32_bf16 v[86:89], v[166:169], v[242:245], v[42:45]
	v_mfma_f32_16x16x32_bf16 v[42:45], v[170:173], v[238:241], v[82:85]
	v_mfma_f32_16x16x32_bf16 v[82:85], v[174:177], v[242:245], v[42:45]
	s_setprio 0
	s_barrier
	s_add_i32 s29, s29, s68
	s_nop 0
	s_nop 0
	s_mov_b32 m0, s29
	s_nop 1
	ds_read_b128 v[42:45], v210 offset:49152
	ds_read_b128 v[46:49], v210 offset:50176
	ds_read_b128 v[50:53], v210 offset:51200
	ds_read_b128 v[54:57], v210 offset:52224
	ds_read_b128 v[212:215], v210 offset:53248
	ds_read_b128 v[216:219], v210 offset:54272
	ds_read_b128 v[222:225], v210 offset:55296
	ds_read_b128 v[226:229], v210 offset:56320
	global_load_lds_dwordx4 v180, s[98:99]
	s_add_i32 m0, s29, 0x2000
	s_add_u32 s58, s58, 0x40080
	s_nop 0
	s_nop 0
	s_addc_u32 s59, s59, 0
	s_add_i32 s29, vcc_lo, s68
	global_load_lds_dwordx4 v184, s[98:99]
	s_nop 0
	s_nop 0
	s_mov_b32 m0, s29
	s_nop 0
	global_load_lds_dwordx4 v180, s[58:59]
	s_nop 0
	s_nop 0
	s_add_i32 m0, s29, 0x2000
	s_nop 0
	global_load_lds_dwordx4 v184, s[58:59]
	s_nop 0
	s_nop 0
	s_mov_b32 m0, s81
	s_nop 0
	global_load_lds_dwordx4 v178, s[100:101]
	s_nop 0
	s_nop 0
	s_mov_b32 m0, s82
	s_nop 0
	global_load_lds_dwordx4 v182, s[100:101]
	s_waitcnt vmcnt(8)
	s_waitcnt lgkmcnt(0)
	s_barrier
	s_setprio 1
	s_waitcnt lgkmcnt(0)
	v_mfma_f32_16x16x32_bf16 v[78:81], v[146:149], v[42:45], v[78:81]
	v_mfma_f32_16x16x32_bf16 v[74:77], v[154:157], v[42:45], v[74:77]
	v_mfma_f32_16x16x32_bf16 v[62:65], v[146:149], v[50:53], v[62:65]
	v_mfma_f32_16x16x32_bf16 v[58:61], v[154:157], v[50:53], v[58:61]
	v_mfma_f32_16x16x32_bf16 v[30:33], v[146:149], v[212:215], v[30:33]
	v_mfma_f32_16x16x32_bf16 v[26:29], v[154:157], v[212:215], v[26:29]
	v_mfma_f32_16x16x32_bf16 v[14:17], v[146:149], v[222:225], v[14:17]
	v_mfma_f32_16x16x32_bf16 v[10:13], v[154:157], v[222:225], v[10:13]
	v_mfma_f32_16x16x32_bf16 v[78:81], v[150:153], v[46:49], v[78:81]
	v_mfma_f32_16x16x32_bf16 v[74:77], v[158:161], v[46:49], v[74:77]
	v_mfma_f32_16x16x32_bf16 v[62:65], v[150:153], v[54:57], v[62:65]
	v_mfma_f32_16x16x32_bf16 v[58:61], v[158:161], v[54:57], v[58:61]
	v_mfma_f32_16x16x32_bf16 v[30:33], v[150:153], v[216:219], v[30:33]
	v_mfma_f32_16x16x32_bf16 v[26:29], v[158:161], v[216:219], v[26:29]
	v_mfma_f32_16x16x32_bf16 v[14:17], v[150:153], v[226:229], v[14:17]
	v_mfma_f32_16x16x32_bf16 v[10:13], v[158:161], v[226:229], v[10:13]
	s_setprio 0
	s_setprio 1
	v_mfma_f32_16x16x32_bf16 v[70:73], v[162:165], v[42:45], v[70:73]
	v_mfma_f32_16x16x32_bf16 v[42:45], v[170:173], v[42:45], v[66:69]
	v_mfma_f32_16x16x32_bf16 v[38:41], v[162:165], v[50:53], v[38:41]
	v_mfma_f32_16x16x32_bf16 v[34:37], v[170:173], v[50:53], v[34:37]
	v_mfma_f32_16x16x32_bf16 v[22:25], v[162:165], v[212:215], v[22:25]
	v_mfma_f32_16x16x32_bf16 v[18:21], v[170:173], v[212:215], v[18:21]
	v_mfma_f32_16x16x32_bf16 v[6:9], v[162:165], v[222:225], v[6:9]
	v_mfma_f32_16x16x32_bf16 v[2:5], v[170:173], v[222:225], v[2:5]
	v_mfma_f32_16x16x32_bf16 v[70:73], v[166:169], v[46:49], v[70:73]
	v_mfma_f32_16x16x32_bf16 v[66:69], v[174:177], v[46:49], v[42:45]
	v_mfma_f32_16x16x32_bf16 v[38:41], v[166:169], v[54:57], v[38:41]
	v_mfma_f32_16x16x32_bf16 v[34:37], v[174:177], v[54:57], v[34:37]
	v_mfma_f32_16x16x32_bf16 v[22:25], v[166:169], v[216:219], v[22:25]
	v_mfma_f32_16x16x32_bf16 v[18:21], v[174:177], v[216:219], v[18:21]
	v_mfma_f32_16x16x32_bf16 v[6:9], v[166:169], v[226:229], v[6:9]
	v_mfma_f32_16x16x32_bf16 v[2:5], v[174:177], v[226:229], v[2:5]
	s_setprio 0
	s_barrier
	s_add_i32 s29, s28, 2
	s_add_u32 s56, s56, 0x100
	s_addc_u32 s57, s57, 0
	s_cmp_gt_u32 s28, 13
	s_mov_b32 s28, s29
	s_cbranch_scc1 .LBB0_442
; #define PG8_LAS __attribute__((address_space(3)))
; #define PG8_STAGE(bufoff, gbase, voff) do { _Pragma("unroll") for (int _i = 0; _i < 2; ++_i) \
;         __builtin_amdgcn_global_load_lds((const unsigned*)((const char*)(gbase) + (voff)[_i]), (PG8_LAS unsigned*)(lds + (bufoff) + ldsw + _i * 8192), 16, 0, 0); } while (0)
; #define PG8_LDA(dst, b, h) do { _Pragma("unroll") for (int m = 0; m < 4; ++m) _Pragma("unroll") for (int k = 0; k < 2; ++k) dst[m][k] = *(const PG8_LAS bf16x8*)(lds + PG8_SA(b, h) + aoff + m * 2048 + k * 1024); } while (0)
; #define PG8_LDB(dst, b, h) do { _Pragma("unroll") for (int n = 0; n < 2; ++n) _Pragma("unroll") for (int k = 0; k < 2; ++k) dst[n][k] = *(const PG8_LAS bf16x8*)(lds + PG8_SB(b, h) + boff + n * 2048 + k * 1024); } while (0)
; #define PG8_MMA(ai, bj, At, Bt) do { __builtin_amdgcn_s_setprio(1); _Pragma("unroll") for (int m = 0; m < 4; ++m) _Pragma("unroll") for (int n = 0; n < 2; ++n) _Pragma("unroll") for (int k = 0; k < 2; ++k) \
;         acc[ai][bj][m][n] = __builtin_amdgcn_mfma_f32_16x16x32_bf16(Bt[n][k], At[m][k], acc[ai][bj][m][n], 0, 0, 0); __builtin_amdgcn_s_setprio(0); } while (0)
; #define PG8_WAIT_V(n) asm volatile("s_waitcnt vmcnt(" #n ")" ::: "memory")
; template <class Epi, class Sched, bool ALIGN_EPI = false, bool SP2 = false>
; __device__ __forceinline__ void gemm_phase(PG8_LAS unsigned char* lds, const Gemm g, const Sched& S, const Epi& E) {
;     ...
;             PG8_LDB(B0, 0, 0); PG8_LDB(B1, 0, 1); PG8_SCHED; PG8_LDA(At, 0, 0); PG8_STAGE(PG8_SA(1, 1), a1 + hstep, voffA);
;             PG8_WAIT_V(8); PG8_WAIT_L(0); PG8_BAR; PG8_MMA(0, 0, At, B0); PG8_MMA(0, 1, At, B1); PG8_BAR; PG8_SCHED;
;             if constexpr (Epi::PREFETCH) { if (t == tpf) E.prefetch(cur, wid, lane); }
; __device__ __forceinline__ void epi_prefetch(PG8_LAS unsigned char* scr, const float* ssq, const float* bias_tile, const Unit& u, int wid, int lane) {
;     unsigned lo = (unsigned)lane * 16u; asm volatile("" : "+v"(lo));
;     const char* src = (const char*)(ssq + (size_t)u.pm * BM * 16 + wid * 512);
; #pragma unroll
;     for (int j = 0; j < 2; ++j) __builtin_amdgcn_global_load_lds((const unsigned*)(src + j * 1024 + lo), (PG8_LAS unsigned*)(scr + (wid * 2 + j) * 1024), 16, 0, 0);
;     if (wid == 0) __builtin_amdgcn_global_load_lds((const unsigned*)((const char*)bias_tile + lo), (PG8_LAS unsigned*)(scr + 16384), 16, 0, 0);
; }
.LBB0_439:
	ds_read_b128 v[162:165], v208
	ds_read_b128 v[166:169], v208 offset:1024
	ds_read_b128 v[170:173], v208 offset:2048
	ds_read_b128 v[174:177], v208 offset:3072
	ds_read_b128 v[146:149], v209
	ds_read_b128 v[150:153], v209 offset:1024
	ds_read_b128 v[154:157], v209 offset:2048
	ds_read_b128 v[158:161], v209 offset:3072
	v_lshl_add_u64 v[42:43], v[196:197], 0, s[56:57]
	s_add_i32 m0, s69, 0xc000
	ds_read_b128 v[212:215], v210
	ds_read_b128 v[216:219], v210 offset:1024
	ds_read_b128 v[222:225], v210 offset:2048
	ds_read_b128 v[226:229], v210 offset:3072
	ds_read_b128 v[230:233], v210 offset:4096
	ds_read_b128 v[234:237], v210 offset:5120
	ds_read_b128 v[238:241], v210 offset:6144
	ds_read_b128 v[242:245], v210 offset:7168
	global_load_lds_dwordx4 v[42:43], off
	v_lshl_add_u64 v[42:43], v[198:199], 0, s[56:57]
	s_add_i32 m0, s69, 0xe000
	s_nop 0
	global_load_lds_dwordx4 v[42:43], off
	s_waitcnt vmcnt(8)
	s_waitcnt lgkmcnt(0)
	s_barrier
	s_setprio 1
	s_waitcnt lgkmcnt(0)
	v_mfma_f32_16x16x32_bf16 v[42:45], v[162:165], v[212:215], v[142:145]
	v_mfma_f32_16x16x32_bf16 v[46:49], v[170:173], v[212:215], v[138:141]
	v_mfma_f32_16x16x32_bf16 v[50:53], v[162:165], v[222:225], v[126:129]
	v_mfma_f32_16x16x32_bf16 v[54:57], v[170:173], v[222:225], v[122:125]
	v_mfma_f32_16x16x32_bf16 v[110:113], v[162:165], v[230:233], v[110:113]
	v_mfma_f32_16x16x32_bf16 v[106:109], v[170:173], v[230:233], v[106:109]
	v_mfma_f32_16x16x32_bf16 v[94:97], v[162:165], v[238:241], v[94:97]
	v_mfma_f32_16x16x32_bf16 v[90:93], v[170:173], v[238:241], v[90:93]
	v_mfma_f32_16x16x32_bf16 v[42:45], v[166:169], v[216:219], v[42:45]
	v_mfma_f32_16x16x32_bf16 v[46:49], v[174:177], v[216:219], v[46:49]
	v_mfma_f32_16x16x32_bf16 v[50:53], v[166:169], v[226:229], v[50:53]
	v_mfma_f32_16x16x32_bf16 v[54:57], v[174:177], v[226:229], v[54:57]
	v_mfma_f32_16x16x32_bf16 v[110:113], v[166:169], v[234:237], v[110:113]
	v_mfma_f32_16x16x32_bf16 v[106:109], v[174:177], v[234:237], v[106:109]
	v_mfma_f32_16x16x32_bf16 v[94:97], v[166:169], v[242:245], v[94:97]
	v_mfma_f32_16x16x32_bf16 v[90:93], v[174:177], v[242:245], v[90:93]
	s_setprio 0
	s_setprio 1
	v_mfma_f32_16x16x32_bf16 v[122:125], v[146:149], v[212:215], v[134:137]
	v_mfma_f32_16x16x32_bf16 v[134:137], v[150:153], v[216:219], v[122:125]
	v_mfma_f32_16x16x32_bf16 v[122:125], v[154:157], v[212:215], v[130:133]
	v_mfma_f32_16x16x32_bf16 v[118:121], v[146:149], v[222:225], v[118:121]
	v_mfma_f32_16x16x32_bf16 v[114:117], v[154:157], v[222:225], v[114:117]
	v_mfma_f32_16x16x32_bf16 v[102:105], v[146:149], v[230:233], v[102:105]
	v_mfma_f32_16x16x32_bf16 v[98:101], v[154:157], v[230:233], v[98:101]
	v_mfma_f32_16x16x32_bf16 v[86:89], v[146:149], v[238:241], v[86:89]
	v_mfma_f32_16x16x32_bf16 v[82:85], v[154:157], v[238:241], v[82:85]
	v_mfma_f32_16x16x32_bf16 v[130:133], v[158:161], v[216:219], v[122:125]
	v_mfma_f32_16x16x32_bf16 v[118:121], v[150:153], v[226:229], v[118:121]
	v_mfma_f32_16x16x32_bf16 v[114:117], v[158:161], v[226:229], v[114:117]
	v_mfma_f32_16x16x32_bf16 v[102:105], v[150:153], v[234:237], v[102:105]
	v_mfma_f32_16x16x32_bf16 v[98:101], v[158:161], v[234:237], v[98:101]
	v_mfma_f32_16x16x32_bf16 v[86:89], v[150:153], v[242:245], v[86:89]
	v_mfma_f32_16x16x32_bf16 v[82:85], v[158:161], v[242:245], v[82:85]
	s_setprio 0
	s_barrier
	s_cmp_lg_u32 s63, s28
	s_cbranch_scc1 .LBB0_438
	v_mov_b32_e32 v186, v207
	s_add_i32 m0, s62, 0x20000
	v_lshl_add_u64 v[122:123], s[52:53], 0, v[186:187]
	s_mov_b64 s[58:59], 0x400
	global_load_lds_dwordx4 v186, s[52:53]
	v_lshl_add_u64 v[122:123], v[122:123], 0, s[58:59]
	s_add_i32 m0, s62, 0x20400
	s_andn2_b64 vcc, exec, s[40:41]
	global_load_lds_dwordx4 v[122:123], off
	s_cbranch_vccnz .LBB0_438
	s_nop 0
	s_nop 0
	s_mov_b32 m0, s30
	s_nop 0
	global_load_lds_dwordx4 v186, s[54:55]
	s_branch .LBB0_438

; #define PG8_STAGE(bufoff, gbase, voff) do { _Pragma("unroll") for (int _i = 0; _i < 2; ++_i) \
;         __builtin_amdgcn_global_load_lds((const unsigned*)((const char*)(gbase) + (voff)[_i]), (PG8_LAS unsigned*)(lds + (bufoff) + ldsw + _i * 8192), 16, 0, 0); } while (0)
; #define PG8_LDA(dst, b, h) do { _Pragma("unroll") for (int m = 0; m < 4; ++m) _Pragma("unroll") for (int k = 0; k < 2; ++k) dst[m][k] = *(const PG8_LAS bf16x8*)(lds + PG8_SA(b, h) + aoff + m * 2048 + k * 1024); } while (0)
; #define PG8_LDB(dst, b, h) do { _Pragma("unroll") for (int n = 0; n < 2; ++n) _Pragma("unroll") for (int k = 0; k < 2; ++k) dst[n][k] = *(const PG8_LAS bf16x8*)(lds + PG8_SB(b, h) + boff + n * 2048 + k * 1024); } while (0)
; #define PG8_MMA(ai, bj, At, Bt) do { __builtin_amdgcn_s_setprio(1); _Pragma("unroll") for (int m = 0; m < 4; ++m) _Pragma("unroll") for (int n = 0; n < 2; ++n) _Pragma("unroll") for (int k = 0; k < 2; ++k) \
;         acc[ai][bj][m][n] = __builtin_amdgcn_mfma_f32_16x16x32_bf16(Bt[n][k], At[m][k], acc[ai][bj][m][n], 0, 0, 0); __builtin_amdgcn_s_setprio(0); } while (0)
; #define PG8_WAIT_V(n) asm volatile("s_waitcnt vmcnt(" #n ")" ::: "memory")
; template <class Epi, class Sched, bool ALIGN_EPI = false, bool SP2 = false>
; __device__ __forceinline__ void gemm_phase(PG8_LAS unsigned char* lds, const Gemm g, const Sched& S, const Epi& E) {
;     ...
;             const bool last = (t == nt - 2);
;             const char* a1 = cA + (size_t)(t + 1) * kstepA;
;             const char* a2 = last ? nA : cA + (size_t)(t + 2) * kstepA; const char* b2 = last ? nB : cB + (size_t)(t + 2) * kstep;
;             const char* a3 = a2 + kstepA; const char* b3 = b2 + kstep;
;             if (last && has_next) S.a_ready(nxt);
;             if constexpr (SP2) {
;             PG8_LDB(B0, 0, 0); PG8_LDB(B1, 0, 1); PG8_SCHED; PG8_LDA(At, 0, 0); PG8_STAGE(PG8_SA(1, 1), a1 + hstep, voffA);
;             PG8_WAIT_V(8); PG8_WAIT_L(0); PG8_BAR; PG8_MMA(0, 0, At, B0); PG8_MMA(0, 1, At, B1); PG8_BAR; PG8_SCHED;
;             if constexpr (Epi::PREFETCH) { if (t == tpf) E.prefetch(cur, wid, lane); }
;             PG8_LDA(At, 0, 1); PG8_STAGE(PG8_SB(0, 0), b2, voffB); PG8_STAGE(PG8_SB(0, 1), b2 + hstep, voffB); PG8_STAGE(PG8_SA(0, 0), a2, voffA);
;             PG8_WAIT_V(8); PG8_WAIT_L(0); PG8_BAR; PG8_MMA(1, 0, At, B0); PG8_MMA(1, 1, At, B1); PG8_BAR; PG8_SCHED;
.LBB0_723:
	v_add_u32_e32 v2, s67, v177
	ds_read_b128 v[134:137], v2
	ds_read_b128 v[138:141], v2 offset:1024
	ds_read_b128 v[142:145], v2 offset:2048
	ds_read_b128 v[146:149], v2 offset:3072
	v_add_u32_e32 v2, s68, v177
	ds_read_b128 v[150:153], v2
	ds_read_b128 v[170:173], v2 offset:1024
	ds_read_b128 v[180:183], v2 offset:2048
	ds_read_b128 v[184:187], v2 offset:3072
	s_add_u32 s28, s0, 0xfffc0080
	s_addc_u32 s29, s1, -1
	s_cmp_eq_u32 s43, 12
	s_cselect_b32 s37, s23, s29
	s_cselect_b32 s36, s39, s28
	s_cselect_b32 s29, s21, s42
	s_cselect_b32 s28, s40, s41
	s_nop 0
	s_nop 0
	s_add_i32 m0, s31, 0xc000
	ds_read_b128 v[188:191], v178
	ds_read_b128 v[192:195], v178 offset:1024
	ds_read_b128 v[196:199], v178 offset:2048
	ds_read_b128 v[200:203], v178 offset:3072
	ds_read_b128 v[204:207], v178 offset:4096
	ds_read_b128 v[208:211], v178 offset:5120
	ds_read_b128 v[212:215], v178 offset:6144
	ds_read_b128 v[216:219], v178 offset:7168
	global_load_lds_dwordx4 v162, s[0:1]
	s_nop 0
	s_nop 0
	s_add_i32 m0, s31, 0xe000
	s_nop 0
	global_load_lds_dwordx4 v164, s[0:1]
	s_waitcnt vmcnt(8)
	s_waitcnt lgkmcnt(0)
	s_barrier
	s_setprio 1
	s_waitcnt lgkmcnt(0)
	v_mfma_f32_16x16x32_bf16 v[130:133], v[134:137], v[188:191], v[130:133]
	v_mfma_f32_16x16x32_bf16 v[126:129], v[142:145], v[188:191], v[126:129]
	v_mfma_f32_16x16x32_bf16 v[122:125], v[134:137], v[196:199], v[122:125]
	v_mfma_f32_16x16x32_bf16 v[118:121], v[142:145], v[196:199], v[118:121]
	v_mfma_f32_16x16x32_bf16 v[114:117], v[134:137], v[204:207], v[114:117]
	v_mfma_f32_16x16x32_bf16 v[110:113], v[142:145], v[204:207], v[110:113]
	v_mfma_f32_16x16x32_bf16 v[106:109], v[134:137], v[212:215], v[106:109]
	v_mfma_f32_16x16x32_bf16 v[102:105], v[142:145], v[212:215], v[102:105]
	v_mfma_f32_16x16x32_bf16 v[130:133], v[138:141], v[192:195], v[130:133]
	v_mfma_f32_16x16x32_bf16 v[126:129], v[146:149], v[192:195], v[126:129]
	v_mfma_f32_16x16x32_bf16 v[122:125], v[138:141], v[200:203], v[122:125]
	v_mfma_f32_16x16x32_bf16 v[118:121], v[146:149], v[200:203], v[118:121]
	v_mfma_f32_16x16x32_bf16 v[114:117], v[138:141], v[208:211], v[114:117]
	v_mfma_f32_16x16x32_bf16 v[110:113], v[146:149], v[208:211], v[110:113]
	v_mfma_f32_16x16x32_bf16 v[106:109], v[138:141], v[216:219], v[106:109]
	v_mfma_f32_16x16x32_bf16 v[102:105], v[146:149], v[216:219], v[102:105]
	s_setprio 0
	s_setprio 1
	v_mfma_f32_16x16x32_bf16 v[98:101], v[150:153], v[188:191], v[98:101]
	v_mfma_f32_16x16x32_bf16 v[94:97], v[180:183], v[188:191], v[94:97]
	v_mfma_f32_16x16x32_bf16 v[90:93], v[150:153], v[196:199], v[90:93]
	v_mfma_f32_16x16x32_bf16 v[86:89], v[180:183], v[196:199], v[86:89]
	v_mfma_f32_16x16x32_bf16 v[82:85], v[150:153], v[204:207], v[82:85]
	v_mfma_f32_16x16x32_bf16 v[78:81], v[180:183], v[204:207], v[78:81]
	v_mfma_f32_16x16x32_bf16 v[74:77], v[150:153], v[212:215], v[74:77]
	v_mfma_f32_16x16x32_bf16 v[70:73], v[180:183], v[212:215], v[70:73]
	v_mfma_f32_16x16x32_bf16 v[98:101], v[170:173], v[192:195], v[98:101]
	v_mfma_f32_16x16x32_bf16 v[94:97], v[184:187], v[192:195], v[94:97]
	v_mfma_f32_16x16x32_bf16 v[90:93], v[170:173], v[200:203], v[90:93]
	v_mfma_f32_16x16x32_bf16 v[86:89], v[184:187], v[200:203], v[86:89]
	v_mfma_f32_16x16x32_bf16 v[82:85], v[170:173], v[208:211], v[82:85]
	v_mfma_f32_16x16x32_bf16 v[78:81], v[184:187], v[208:211], v[78:81]
	v_mfma_f32_16x16x32_bf16 v[74:77], v[170:173], v[216:219], v[74:77]
	v_mfma_f32_16x16x32_bf16 v[70:73], v[184:187], v[216:219], v[70:73]
	s_setprio 0
	s_barrier
	s_add_i32 s71, s67, s48
	s_nop 0
	s_nop 0
	s_add_u32 s98, s28, s14
	s_addc_u32 s99, s29, s15
	s_mov_b32 m0, s71
	ds_read_b128 v[188:191], v178 offset:16384
	ds_read_b128 v[192:195], v178 offset:17408
	ds_read_b128 v[196:199], v178 offset:18432
	ds_read_b128 v[200:203], v178 offset:19456
	ds_read_b128 v[204:207], v178 offset:20480
	ds_read_b128 v[208:211], v178 offset:21504
	ds_read_b128 v[212:215], v178 offset:22528
	ds_read_b128 v[216:219], v178 offset:23552
	global_load_lds_dwordx4 v156, s[28:29]
	s_add_i32 m0, s71, 0x2000
	s_add_u32 s72, s28, 0x40000
	s_nop 0
	s_nop 0
	s_addc_u32 s73, s29, 0
	s_add_i32 s71, s68, s48
	global_load_lds_dwordx4 v160, s[28:29]
	s_nop 0
	s_nop 0
	s_mov_b32 m0, s71
	s_nop 0
	s_nop 0
	s_add_u32 s100, s36, s14
	s_addc_u32 s101, s37, s15
	global_load_lds_dwordx4 v156, s[72:73]
	s_nop 0
	s_nop 0
	s_add_i32 m0, s71, 0x2000
	s_nop 0
	s_nop 0
	global_load_lds_dwordx4 v160, s[72:73]
	s_mov_b32 m0, s31
	s_nop 0
	global_load_lds_dwordx4 v154, s[36:37]
	s_mov_b32 m0, s35
	s_nop 0
	global_load_lds_dwordx4 v158, s[36:37]
	s_waitcnt vmcnt(8)
	s_waitcnt lgkmcnt(0)
	s_barrier
; #define PG8_STAGE(bufoff, gbase, voff) do { _Pragma("unroll") for (int _i = 0; _i < 2; ++_i) \
;         __builtin_amdgcn_global_load_lds((const unsigned*)((const char*)(gbase) + (voff)[_i]), (PG8_LAS unsigned*)(lds + (bufoff) + ldsw + _i * 8192), 16, 0, 0); } while (0)
; #define PG8_LDA(dst, b, h) do { _Pragma("unroll") for (int m = 0; m < 4; ++m) _Pragma("unroll") for (int k = 0; k < 2; ++k) dst[m][k] = *(const PG8_LAS bf16x8*)(lds + PG8_SA(b, h) + aoff + m * 2048 + k * 1024); } while (0)
; #define PG8_LDB(dst, b, h) do { _Pragma("unroll") for (int n = 0; n < 2; ++n) _Pragma("unroll") for (int k = 0; k < 2; ++k) dst[n][k] = *(const PG8_LAS bf16x8*)(lds + PG8_SB(b, h) + boff + n * 2048 + k * 1024); } while (0)
; #define PG8_MMA(ai, bj, At, Bt) do { __builtin_amdgcn_s_setprio(1); _Pragma("unroll") for (int m = 0; m < 4; ++m) _Pragma("unroll") for (int n = 0; n < 2; ++n) _Pragma("unroll") for (int k = 0; k < 2; ++k) \
;         acc[ai][bj][m][n] = __builtin_amdgcn_mfma_f32_16x16x32_bf16(Bt[n][k], At[m][k], acc[ai][bj][m][n], 0, 0, 0); __builtin_amdgcn_s_setprio(0); } while (0)
; #define PG8_WAIT_V(n) asm volatile("s_waitcnt vmcnt(" #n ")" ::: "memory")
; #define PG8_WAIT_L(n) asm volatile("s_waitcnt lgkmcnt(" #n ")" ::: "memory")
; #define PG8_BAR __builtin_amdgcn_s_barrier()
; #define PG8_SCHED __builtin_amdgcn_sched_barrier(0)
; template <class Epi, class Sched, bool ALIGN_EPI = false, bool SP2 = false>
; __device__ __forceinline__ void gemm_phase(PG8_LAS unsigned char* lds, const Gemm g, const Sched& S, const Epi& E) {
;     ...
;             PG8_WAIT_V(8); PG8_WAIT_L(0); PG8_BAR; PG8_MMA(1, 0, At, B0); PG8_MMA(1, 1, At, B1); PG8_BAR; PG8_SCHED;
;             PG8_LDB(B0, 1, 0); PG8_LDB(B1, 1, 1); PG8_SCHED; PG8_LDA(At, 1, 0); PG8_STAGE(PG8_SA(0, 1), a2 + hstep, voffA);
;             PG8_WAIT_V(8); PG8_WAIT_L(0); PG8_BAR; PG8_MMA(0, 0, At, B0); PG8_MMA(0, 1, At, B1); PG8_BAR; PG8_SCHED;
	s_setprio 1
	s_waitcnt lgkmcnt(0)
	v_mfma_f32_16x16x32_bf16 v[66:69], v[134:137], v[188:191], v[66:69]
	v_mfma_f32_16x16x32_bf16 v[62:65], v[142:145], v[188:191], v[62:65]
	v_mfma_f32_16x16x32_bf16 v[58:61], v[134:137], v[196:199], v[58:61]
	v_mfma_f32_16x16x32_bf16 v[54:57], v[142:145], v[196:199], v[54:57]
	v_mfma_f32_16x16x32_bf16 v[50:53], v[134:137], v[204:207], v[50:53]
	v_mfma_f32_16x16x32_bf16 v[46:49], v[142:145], v[204:207], v[46:49]
	v_mfma_f32_16x16x32_bf16 v[42:45], v[134:137], v[212:215], v[42:45]
	v_mfma_f32_16x16x32_bf16 v[38:41], v[142:145], v[212:215], v[38:41]
	v_mfma_f32_16x16x32_bf16 v[66:69], v[138:141], v[192:195], v[66:69]
	v_mfma_f32_16x16x32_bf16 v[62:65], v[146:149], v[192:195], v[62:65]
	v_mfma_f32_16x16x32_bf16 v[58:61], v[138:141], v[200:203], v[58:61]
	v_mfma_f32_16x16x32_bf16 v[54:57], v[146:149], v[200:203], v[54:57]
	v_mfma_f32_16x16x32_bf16 v[50:53], v[138:141], v[208:211], v[50:53]
	v_mfma_f32_16x16x32_bf16 v[46:49], v[146:149], v[208:211], v[46:49]
	v_mfma_f32_16x16x32_bf16 v[42:45], v[138:141], v[216:219], v[42:45]
	v_mfma_f32_16x16x32_bf16 v[38:41], v[146:149], v[216:219], v[38:41]
	s_setprio 0
	s_setprio 1
	v_mfma_f32_16x16x32_bf16 v[34:37], v[150:153], v[188:191], v[34:37]
	v_mfma_f32_16x16x32_bf16 v[30:33], v[180:183], v[188:191], v[30:33]
	v_mfma_f32_16x16x32_bf16 v[26:29], v[150:153], v[196:199], v[26:29]
	v_mfma_f32_16x16x32_bf16 v[22:25], v[180:183], v[196:199], v[22:25]
	v_mfma_f32_16x16x32_bf16 v[18:21], v[150:153], v[204:207], v[18:21]
	v_mfma_f32_16x16x32_bf16 v[14:17], v[180:183], v[204:207], v[14:17]
	v_mfma_f32_16x16x32_bf16 v[10:13], v[150:153], v[212:215], v[10:13]
	v_mfma_f32_16x16x32_bf16 v[4:7], v[180:183], v[212:215], v[6:9]
	v_mfma_f32_16x16x32_bf16 v[34:37], v[170:173], v[192:195], v[34:37]
	v_mfma_f32_16x16x32_bf16 v[30:33], v[184:187], v[192:195], v[30:33]
	v_mfma_f32_16x16x32_bf16 v[26:29], v[170:173], v[200:203], v[26:29]
	v_mfma_f32_16x16x32_bf16 v[22:25], v[184:187], v[200:203], v[22:25]
	v_mfma_f32_16x16x32_bf16 v[18:21], v[170:173], v[208:211], v[18:21]
	v_mfma_f32_16x16x32_bf16 v[14:17], v[184:187], v[208:211], v[14:17]
	v_mfma_f32_16x16x32_bf16 v[10:13], v[170:173], v[216:219], v[10:13]
	v_mfma_f32_16x16x32_bf16 v[4:7], v[184:187], v[216:219], v[4:7]
	s_setprio 0
	s_barrier
	s_add_i32 s71, 0, 0x18000
	v_add_u32_e32 v2, s71, v177
	s_add_i32 s72, 0, 0x1c000
	ds_read_b128 v[134:137], v2
	ds_read_b128 v[138:141], v2 offset:1024
	ds_read_b128 v[142:145], v2 offset:2048
	ds_read_b128 v[146:149], v2 offset:3072
	v_add_u32_e32 v2, s72, v177
	ds_read_b128 v[150:153], v2
	ds_read_b128 v[170:173], v2 offset:1024
	ds_read_b128 v[180:183], v2 offset:2048
	ds_read_b128 v[184:187], v2 offset:3072
	s_add_u32 s36, s36, 0x40000
	s_addc_u32 s37, s37, 0
	s_mov_b32 m0, s49
	s_nop 0
	s_nop 0
	ds_read_b128 v[188:191], v178 offset:32768
	ds_read_b128 v[192:195], v178 offset:33792
	ds_read_b128 v[196:199], v178 offset:34816
	ds_read_b128 v[200:203], v178 offset:35840
	ds_read_b128 v[204:207], v178 offset:36864
	ds_read_b128 v[208:211], v178 offset:37888
	ds_read_b128 v[212:215], v178 offset:38912
	ds_read_b128 v[216:219], v178 offset:39936
	global_load_lds_dwordx4 v154, s[36:37]
	s_nop 0
	s_nop 0
	s_mov_b32 m0, s50
	s_nop 0
	global_load_lds_dwordx4 v158, s[36:37]
	s_waitcnt vmcnt(8)
	s_waitcnt lgkmcnt(0)
	s_barrier
	s_setprio 1
	s_waitcnt lgkmcnt(0)
	v_mfma_f32_16x16x32_bf16 v[130:133], v[134:137], v[188:191], v[130:133]
	v_mfma_f32_16x16x32_bf16 v[126:129], v[142:145], v[188:191], v[126:129]
	v_mfma_f32_16x16x32_bf16 v[122:125], v[134:137], v[196:199], v[122:125]
	v_mfma_f32_16x16x32_bf16 v[118:121], v[142:145], v[196:199], v[118:121]
	v_mfma_f32_16x16x32_bf16 v[114:117], v[134:137], v[204:207], v[114:117]
	v_mfma_f32_16x16x32_bf16 v[110:113], v[142:145], v[204:207], v[110:113]
	v_mfma_f32_16x16x32_bf16 v[106:109], v[134:137], v[212:215], v[106:109]
	v_mfma_f32_16x16x32_bf16 v[102:105], v[142:145], v[212:215], v[102:105]
	v_mfma_f32_16x16x32_bf16 v[130:133], v[138:141], v[192:195], v[130:133]
	v_mfma_f32_16x16x32_bf16 v[126:129], v[146:149], v[192:195], v[126:129]
	v_mfma_f32_16x16x32_bf16 v[122:125], v[138:141], v[200:203], v[122:125]
	v_mfma_f32_16x16x32_bf16 v[118:121], v[146:149], v[200:203], v[118:121]
	v_mfma_f32_16x16x32_bf16 v[114:117], v[138:141], v[208:211], v[114:117]
	v_mfma_f32_16x16x32_bf16 v[110:113], v[146:149], v[208:211], v[110:113]
	v_mfma_f32_16x16x32_bf16 v[106:109], v[138:141], v[216:219], v[106:109]
	v_mfma_f32_16x16x32_bf16 v[102:105], v[146:149], v[216:219], v[102:105]
	s_setprio 0
	s_setprio 1
	v_mfma_f32_16x16x32_bf16 v[98:101], v[150:153], v[188:191], v[98:101]
	v_mfma_f32_16x16x32_bf16 v[94:97], v[180:183], v[188:191], v[94:97]
	v_mfma_f32_16x16x32_bf16 v[90:93], v[150:153], v[196:199], v[90:93]
	v_mfma_f32_16x16x32_bf16 v[86:89], v[180:183], v[196:199], v[86:89]
	v_mfma_f32_16x16x32_bf16 v[82:85], v[150:153], v[204:207], v[82:85]
	v_mfma_f32_16x16x32_bf16 v[78:81], v[180:183], v[204:207], v[78:81]
	v_mfma_f32_16x16x32_bf16 v[74:77], v[150:153], v[212:215], v[74:77]
	v_mfma_f32_16x16x32_bf16 v[70:73], v[180:183], v[212:215], v[70:73]
	v_mfma_f32_16x16x32_bf16 v[98:101], v[170:173], v[192:195], v[98:101]
	v_mfma_f32_16x16x32_bf16 v[94:97], v[184:187], v[192:195], v[94:97]
	v_mfma_f32_16x16x32_bf16 v[90:93], v[170:173], v[200:203], v[90:93]
	v_mfma_f32_16x16x32_bf16 v[86:89], v[184:187], v[200:203], v[86:89]
	v_mfma_f32_16x16x32_bf16 v[82:85], v[170:173], v[208:211], v[82:85]
	v_mfma_f32_16x16x32_bf16 v[78:81], v[184:187], v[208:211], v[78:81]
	v_mfma_f32_16x16x32_bf16 v[74:77], v[170:173], v[216:219], v[74:77]
	v_mfma_f32_16x16x32_bf16 v[70:73], v[184:187], v[216:219], v[70:73]
	s_setprio 0
	s_barrier
; #define PG8_STAGE(bufoff, gbase, voff) do { _Pragma("unroll") for (int _i = 0; _i < 2; ++_i) \
;         __builtin_amdgcn_global_load_lds((const unsigned*)((const char*)(gbase) + (voff)[_i]), (PG8_LAS unsigned*)(lds + (bufoff) + ldsw + _i * 8192), 16, 0, 0); } while (0)
; #define PG8_LDA(dst, b, h) do { _Pragma("unroll") for (int m = 0; m < 4; ++m) _Pragma("unroll") for (int k = 0; k < 2; ++k) dst[m][k] = *(const PG8_LAS bf16x8*)(lds + PG8_SA(b, h) + aoff + m * 2048 + k * 1024); } while (0)
; #define PG8_MMA(ai, bj, At, Bt) do { __builtin_amdgcn_s_setprio(1); _Pragma("unroll") for (int m = 0; m < 4; ++m) _Pragma("unroll") for (int n = 0; n < 2; ++n) _Pragma("unroll") for (int k = 0; k < 2; ++k) \
;         acc[ai][bj][m][n] = __builtin_amdgcn_mfma_f32_16x16x32_bf16(Bt[n][k], At[m][k], acc[ai][bj][m][n], 0, 0, 0); __builtin_amdgcn_s_setprio(0); } while (0)
; #define PG8_WAIT_V(n) asm volatile("s_waitcnt vmcnt(" #n ")" ::: "memory")
; #define PG8_WAIT_L(n) asm volatile("s_waitcnt lgkmcnt(" #n ")" ::: "memory")
; #define PG8_BAR __builtin_amdgcn_s_barrier()
; #define PG8_SCHED __builtin_amdgcn_sched_barrier(0)
; template <class Epi, class Sched, bool ALIGN_EPI = false, bool SP2 = false>
; __device__ __forceinline__ void gemm_phase(PG8_LAS unsigned char* lds, const Gemm g, const Sched& S, const Epi& E) {
;     ...
;         for (int t = 0; t < nt; t += 2) {
;     ...
;             PG8_LDA(At, 1, 1); PG8_STAGE(PG8_SB(1, 0), b3, voffB); PG8_STAGE(PG8_SB(1, 1), b3 + hstep, voffB); PG8_STAGE(PG8_SA(1, 0), a3, voffA);
;             PG8_WAIT_V(8); PG8_WAIT_L(0); PG8_BAR; PG8_MMA(1, 0, At, B0); PG8_MMA(1, 1, At, B1); PG8_BAR; PG8_SCHED;
	s_add_i32 s36, s71, s48
	s_nop 0
	s_nop 0
	s_mov_b32 m0, s36
	ds_read_b128 v[188:191], v178 offset:49152
	ds_read_b128 v[192:195], v178 offset:50176
	ds_read_b128 v[196:199], v178 offset:51200
	ds_read_b128 v[200:203], v178 offset:52224
	ds_read_b128 v[204:207], v178 offset:53248
	ds_read_b128 v[208:211], v178 offset:54272
	ds_read_b128 v[212:215], v178 offset:55296
	ds_read_b128 v[216:219], v178 offset:56320
	global_load_lds_dwordx4 v156, s[98:99]
	s_add_i32 m0, s36, 0x2000
	s_add_u32 s28, s28, 0x40080
	s_nop 0
	s_nop 0
	s_addc_u32 s29, s29, 0
	s_add_i32 s36, s72, s48
	global_load_lds_dwordx4 v160, s[98:99]
	s_nop 0
	s_nop 0
	s_mov_b32 m0, s36
	s_nop 0
	global_load_lds_dwordx4 v156, s[28:29]
	s_nop 0
	s_nop 0
	s_add_i32 m0, s36, 0x2000
	s_nop 0
	global_load_lds_dwordx4 v160, s[28:29]
	s_nop 0
	s_nop 0
	s_mov_b32 m0, s58
	s_nop 0
	global_load_lds_dwordx4 v154, s[100:101]
	s_nop 0
	s_nop 0
	s_mov_b32 m0, s59
	s_nop 0
	global_load_lds_dwordx4 v158, s[100:101]
	s_waitcnt vmcnt(8)
	s_waitcnt lgkmcnt(0)
	s_barrier
	s_setprio 1
	s_waitcnt lgkmcnt(0)
	v_mfma_f32_16x16x32_bf16 v[66:69], v[134:137], v[188:191], v[66:69]
	v_mfma_f32_16x16x32_bf16 v[62:65], v[142:145], v[188:191], v[62:65]
	v_mfma_f32_16x16x32_bf16 v[58:61], v[134:137], v[196:199], v[58:61]
	v_mfma_f32_16x16x32_bf16 v[54:57], v[142:145], v[196:199], v[54:57]
	v_mfma_f32_16x16x32_bf16 v[50:53], v[134:137], v[204:207], v[50:53]
	v_mfma_f32_16x16x32_bf16 v[46:49], v[142:145], v[204:207], v[46:49]
	v_mfma_f32_16x16x32_bf16 v[42:45], v[134:137], v[212:215], v[42:45]
	v_mfma_f32_16x16x32_bf16 v[38:41], v[142:145], v[212:215], v[38:41]
	v_mfma_f32_16x16x32_bf16 v[66:69], v[138:141], v[192:195], v[66:69]
	v_mfma_f32_16x16x32_bf16 v[62:65], v[146:149], v[192:195], v[62:65]
	v_mfma_f32_16x16x32_bf16 v[58:61], v[138:141], v[200:203], v[58:61]
	v_mfma_f32_16x16x32_bf16 v[54:57], v[146:149], v[200:203], v[54:57]
	v_mfma_f32_16x16x32_bf16 v[50:53], v[138:141], v[208:211], v[50:53]
	v_mfma_f32_16x16x32_bf16 v[46:49], v[146:149], v[208:211], v[46:49]
	v_mfma_f32_16x16x32_bf16 v[42:45], v[138:141], v[216:219], v[42:45]
	v_mfma_f32_16x16x32_bf16 v[38:41], v[146:149], v[216:219], v[38:41]
	s_setprio 0
	s_setprio 1
	v_mfma_f32_16x16x32_bf16 v[34:37], v[150:153], v[188:191], v[34:37]
	v_mfma_f32_16x16x32_bf16 v[30:33], v[180:183], v[188:191], v[30:33]
	v_mfma_f32_16x16x32_bf16 v[26:29], v[150:153], v[196:199], v[26:29]
	v_mfma_f32_16x16x32_bf16 v[22:25], v[180:183], v[196:199], v[22:25]
	v_mfma_f32_16x16x32_bf16 v[18:21], v[150:153], v[204:207], v[18:21]
	v_mfma_f32_16x16x32_bf16 v[14:17], v[180:183], v[204:207], v[14:17]
	v_mfma_f32_16x16x32_bf16 v[8:11], v[150:153], v[212:215], v[10:13]
	v_mfma_f32_16x16x32_bf16 v[4:7], v[180:183], v[212:215], v[4:7]
	v_mfma_f32_16x16x32_bf16 v[34:37], v[170:173], v[192:195], v[34:37]
	v_mfma_f32_16x16x32_bf16 v[30:33], v[184:187], v[192:195], v[30:33]
	v_mfma_f32_16x16x32_bf16 v[26:29], v[170:173], v[200:203], v[26:29]
	v_mfma_f32_16x16x32_bf16 v[22:25], v[184:187], v[200:203], v[22:25]
	v_mfma_f32_16x16x32_bf16 v[18:21], v[170:173], v[208:211], v[18:21]
	v_mfma_f32_16x16x32_bf16 v[14:17], v[184:187], v[208:211], v[14:17]
	v_mfma_f32_16x16x32_bf16 v[10:13], v[170:173], v[216:219], v[8:11]
	v_mfma_f32_16x16x32_bf16 v[6:9], v[184:187], v[216:219], v[4:7]
	s_setprio 0
	s_barrier
	s_add_i32 s43, s43, 2
	s_add_u32 s0, s0, 0x100
	s_addc_u32 s1, s1, 0
	s_add_u32 s41, s41, 0x100
	s_addc_u32 s42, s42, 0
	s_cmp_gt_u32 s43, 13
	s_cbranch_scc0 .LBB0_723
	s_and_b64 vcc, exec, s[16:17]
	s_cbranch_vccz .LBB0_726
	s_barrier

; #define PG8_STAGE(bufoff, gbase, voff) do { _Pragma("unroll") for (int _i = 0; _i < 2; ++_i) \
;         __builtin_amdgcn_global_load_lds((const unsigned*)((const char*)(gbase) + (voff)[_i]), (PG8_LAS unsigned*)(lds + (bufoff) + ldsw + _i * 8192), 16, 0, 0); } while (0)
; #define PG8_LDA(dst, b, h) do { _Pragma("unroll") for (int m = 0; m < 4; ++m) _Pragma("unroll") for (int k = 0; k < 2; ++k) dst[m][k] = *(const PG8_LAS bf16x8*)(lds + PG8_SA(b, h) + aoff + m * 2048 + k * 1024); } while (0)
; #define PG8_LDB(dst, b, h) do { _Pragma("unroll") for (int n = 0; n < 2; ++n) _Pragma("unroll") for (int k = 0; k < 2; ++k) dst[n][k] = *(const PG8_LAS bf16x8*)(lds + PG8_SB(b, h) + boff + n * 2048 + k * 1024); } while (0)
; #define PG8_MMA(ai, bj, At, Bt) do { __builtin_amdgcn_s_setprio(1); _Pragma("unroll") for (int m = 0; m < 4; ++m) _Pragma("unroll") for (int n = 0; n < 2; ++n) _Pragma("unroll") for (int k = 0; k < 2; ++k) \
;         acc[ai][bj][m][n] = __builtin_amdgcn_mfma_f32_16x16x32_bf16(Bt[n][k], At[m][k], acc[ai][bj][m][n], 0, 0, 0); __builtin_amdgcn_s_setprio(0); } while (0)
; #define PG8_WAIT_V(n) asm volatile("s_waitcnt vmcnt(" #n ")" ::: "memory")
; template <class Epi, class Sched, bool ALIGN_EPI = false, bool SP2 = false>
; __device__ __forceinline__ void gemm_phase(PG8_LAS unsigned char* lds, const Gemm g, const Sched& S, const Epi& E) {
;     ...
;             const bool last = (t == nt - 2);
;             const char* a1 = cA + (size_t)(t + 1) * kstepA;
;             const char* a2 = last ? nA : cA + (size_t)(t + 2) * kstepA; const char* b2 = last ? nB : cB + (size_t)(t + 2) * kstep;
;             const char* a3 = a2 + kstepA; const char* b3 = b2 + kstep;
;             if (last && has_next) S.a_ready(nxt);
;             if constexpr (SP2) {
;             PG8_LDB(B0, 0, 0); PG8_LDB(B1, 0, 1); PG8_SCHED; PG8_LDA(At, 0, 0); PG8_STAGE(PG8_SA(1, 1), a1 + hstep, voffA);
;             PG8_WAIT_V(8); PG8_WAIT_L(0); PG8_BAR; PG8_MMA(0, 0, At, B0); PG8_MMA(0, 1, At, B1); PG8_BAR; PG8_SCHED;
;             if constexpr (Epi::PREFETCH) { if (t == tpf) E.prefetch(cur, wid, lane); }
;             PG8_LDA(At, 0, 1); PG8_STAGE(PG8_SB(0, 0), b2, voffB); PG8_STAGE(PG8_SB(0, 1), b2 + hstep, voffB); PG8_STAGE(PG8_SA(0, 0), a2, voffA);
;             PG8_WAIT_V(8); PG8_WAIT_L(0); PG8_BAR; PG8_MMA(1, 0, At, B0); PG8_MMA(1, 1, At, B1); PG8_BAR; PG8_SCHED;
.LBB0_838:
	ds_read_b128 v[50:53], v214
	ds_read_b128 v[54:57], v214 offset:1024
	ds_read_b128 v[66:69], v214 offset:2048
	ds_read_b128 v[70:73], v214 offset:3072
	ds_read_b128 v[146:149], v215
	ds_read_b128 v[150:153], v215 offset:1024
	ds_read_b128 v[172:175], v215 offset:2048
	ds_read_b128 v[176:179], v215 offset:3072
	s_add_u32 s6, s4, 0xfffc0080
	s_addc_u32 s7, s5, -1
	s_cmp_eq_u32 s41, 12
	s_cselect_b32 s37, s1, s7
	s_cselect_b32 s36, s29, s6
	s_cselect_b32 s7, s27, s40
	s_cselect_b32 s6, s38, s39
	s_nop 0
	s_nop 0
	s_add_i32 m0, s51, 0xc000
	ds_read_b128 v[180:183], v216
	ds_read_b128 v[184:187], v216 offset:1024
	ds_read_b128 v[188:191], v216 offset:2048
	ds_read_b128 v[192:195], v216 offset:3072
	ds_read_b128 v[196:199], v216 offset:4096
	ds_read_b128 v[200:203], v216 offset:5120
	ds_read_b128 v[204:207], v216 offset:6144
	ds_read_b128 v[208:211], v216 offset:7168
	global_load_lds_dwordx4 v164, s[4:5]
	s_nop 0
	s_nop 0
	s_add_i32 m0, s51, 0xe000
	s_nop 0
	global_load_lds_dwordx4 v166, s[4:5]
	s_waitcnt vmcnt(8)
	s_waitcnt lgkmcnt(0)
	s_barrier
	s_setprio 1
	s_waitcnt lgkmcnt(0)
	v_mfma_f32_16x16x32_bf16 v[142:145], v[50:53], v[180:183], v[142:145]
	v_mfma_f32_16x16x32_bf16 v[138:141], v[66:69], v[180:183], v[138:141]
	v_mfma_f32_16x16x32_bf16 v[126:129], v[50:53], v[188:191], v[126:129]
	v_mfma_f32_16x16x32_bf16 v[122:125], v[66:69], v[188:191], v[122:125]
	v_mfma_f32_16x16x32_bf16 v[110:113], v[50:53], v[196:199], v[110:113]
	v_mfma_f32_16x16x32_bf16 v[106:109], v[66:69], v[196:199], v[106:109]
	v_mfma_f32_16x16x32_bf16 v[94:97], v[50:53], v[204:207], v[94:97]
	v_mfma_f32_16x16x32_bf16 v[90:93], v[66:69], v[204:207], v[90:93]
	v_mfma_f32_16x16x32_bf16 v[142:145], v[54:57], v[184:187], v[142:145]
	v_mfma_f32_16x16x32_bf16 v[138:141], v[70:73], v[184:187], v[138:141]
	v_mfma_f32_16x16x32_bf16 v[126:129], v[54:57], v[192:195], v[126:129]
	v_mfma_f32_16x16x32_bf16 v[122:125], v[70:73], v[192:195], v[122:125]
	v_mfma_f32_16x16x32_bf16 v[110:113], v[54:57], v[200:203], v[110:113]
	v_mfma_f32_16x16x32_bf16 v[106:109], v[70:73], v[200:203], v[106:109]
	v_mfma_f32_16x16x32_bf16 v[94:97], v[54:57], v[208:211], v[94:97]
	v_mfma_f32_16x16x32_bf16 v[90:93], v[70:73], v[208:211], v[90:93]
	s_setprio 0
	s_setprio 1
	v_mfma_f32_16x16x32_bf16 v[134:137], v[146:149], v[180:183], v[134:137]
	v_mfma_f32_16x16x32_bf16 v[130:133], v[172:175], v[180:183], v[130:133]
	v_mfma_f32_16x16x32_bf16 v[118:121], v[146:149], v[188:191], v[118:121]
	v_mfma_f32_16x16x32_bf16 v[114:117], v[172:175], v[188:191], v[114:117]
	v_mfma_f32_16x16x32_bf16 v[102:105], v[146:149], v[196:199], v[102:105]
	v_mfma_f32_16x16x32_bf16 v[98:101], v[172:175], v[196:199], v[98:101]
	v_mfma_f32_16x16x32_bf16 v[86:89], v[146:149], v[204:207], v[86:89]
	v_mfma_f32_16x16x32_bf16 v[82:85], v[172:175], v[204:207], v[82:85]
	v_mfma_f32_16x16x32_bf16 v[134:137], v[150:153], v[184:187], v[134:137]
	v_mfma_f32_16x16x32_bf16 v[130:133], v[176:179], v[184:187], v[130:133]
	v_mfma_f32_16x16x32_bf16 v[118:121], v[150:153], v[192:195], v[118:121]
	v_mfma_f32_16x16x32_bf16 v[114:117], v[176:179], v[192:195], v[114:117]
	v_mfma_f32_16x16x32_bf16 v[102:105], v[150:153], v[200:203], v[102:105]
	v_mfma_f32_16x16x32_bf16 v[98:101], v[176:179], v[200:203], v[98:101]
	v_mfma_f32_16x16x32_bf16 v[86:89], v[150:153], v[208:211], v[86:89]
	v_mfma_f32_16x16x32_bf16 v[82:85], v[176:179], v[208:211], v[82:85]
	s_setprio 0
	s_barrier
	s_add_i32 s42, s68, s50
	s_nop 0
	s_nop 0
	s_add_u32 s98, s6, s20
	s_addc_u32 s99, s7, s21
	s_mov_b32 m0, s42
	ds_read_b128 v[180:183], v216 offset:16384
	ds_read_b128 v[184:187], v216 offset:17408
	ds_read_b128 v[188:191], v216 offset:18432
	ds_read_b128 v[192:195], v216 offset:19456
	ds_read_b128 v[196:199], v216 offset:20480
	ds_read_b128 v[200:203], v216 offset:21504
	ds_read_b128 v[204:207], v216 offset:22528
	ds_read_b128 v[208:211], v216 offset:23552
	global_load_lds_dwordx4 v156, s[6:7]
	s_add_i32 m0, s42, 0x2000
	s_add_u32 s42, s6, 0x40000
	s_nop 0
	s_nop 0
	s_addc_u32 s43, s7, 0
	s_add_i32 s44, s69, s50
	global_load_lds_dwordx4 v160, s[6:7]
	s_nop 0
	s_nop 0
	s_mov_b32 m0, s44
	s_nop 0
	s_nop 0
	global_load_lds_dwordx4 v156, s[42:43]
	s_nop 0
	s_nop 0
	s_add_i32 m0, s44, 0x2000
	s_nop 0
	global_load_lds_dwordx4 v160, s[42:43]
	s_nop 0
	s_nop 0
	s_add_u32 s100, s36, s20
	s_addc_u32 s101, s37, s21
	s_mov_b32 m0, s51
	s_nop 0
	global_load_lds_dwordx4 v154, s[36:37]
	s_mov_b32 m0, s52
	s_nop 0
	global_load_lds_dwordx4 v158, s[36:37]
	s_waitcnt vmcnt(8)
	s_waitcnt lgkmcnt(0)
	s_barrier
; #define PG8_STAGE(bufoff, gbase, voff) do { _Pragma("unroll") for (int _i = 0; _i < 2; ++_i) \
;         __builtin_amdgcn_global_load_lds((const unsigned*)((const char*)(gbase) + (voff)[_i]), (PG8_LAS unsigned*)(lds + (bufoff) + ldsw + _i * 8192), 16, 0, 0); } while (0)
; #define PG8_LDA(dst, b, h) do { _Pragma("unroll") for (int m = 0; m < 4; ++m) _Pragma("unroll") for (int k = 0; k < 2; ++k) dst[m][k] = *(const PG8_LAS bf16x8*)(lds + PG8_SA(b, h) + aoff + m * 2048 + k * 1024); } while (0)
; #define PG8_LDB(dst, b, h) do { _Pragma("unroll") for (int n = 0; n < 2; ++n) _Pragma("unroll") for (int k = 0; k < 2; ++k) dst[n][k] = *(const PG8_LAS bf16x8*)(lds + PG8_SB(b, h) + boff + n * 2048 + k * 1024); } while (0)
; #define PG8_MMA(ai, bj, At, Bt) do { __builtin_amdgcn_s_setprio(1); _Pragma("unroll") for (int m = 0; m < 4; ++m) _Pragma("unroll") for (int n = 0; n < 2; ++n) _Pragma("unroll") for (int k = 0; k < 2; ++k) \
;         acc[ai][bj][m][n] = __builtin_amdgcn_mfma_f32_16x16x32_bf16(Bt[n][k], At[m][k], acc[ai][bj][m][n], 0, 0, 0); __builtin_amdgcn_s_setprio(0); } while (0)
; #define PG8_WAIT_V(n) asm volatile("s_waitcnt vmcnt(" #n ")" ::: "memory")
; #define PG8_WAIT_L(n) asm volatile("s_waitcnt lgkmcnt(" #n ")" ::: "memory")
; #define PG8_BAR __builtin_amdgcn_s_barrier()
; #define PG8_SCHED __builtin_amdgcn_sched_barrier(0)
; template <class Epi, class Sched, bool ALIGN_EPI = false, bool SP2 = false>
; __device__ __forceinline__ void gemm_phase(PG8_LAS unsigned char* lds, const Gemm g, const Sched& S, const Epi& E) {
;     ...
;             PG8_WAIT_V(8); PG8_WAIT_L(0); PG8_BAR; PG8_MMA(1, 0, At, B0); PG8_MMA(1, 1, At, B1); PG8_BAR; PG8_SCHED;
;             PG8_LDB(B0, 1, 0); PG8_LDB(B1, 1, 1); PG8_SCHED; PG8_LDA(At, 1, 0); PG8_STAGE(PG8_SA(0, 1), a2 + hstep, voffA);
;             PG8_WAIT_V(8); PG8_WAIT_L(0); PG8_BAR; PG8_MMA(0, 0, At, B0); PG8_MMA(0, 1, At, B1); PG8_BAR; PG8_SCHED;
	s_setprio 1
	s_waitcnt lgkmcnt(0)
	v_mfma_f32_16x16x32_bf16 v[78:81], v[50:53], v[180:183], v[78:81]
	v_mfma_f32_16x16x32_bf16 v[74:77], v[66:69], v[180:183], v[74:77]
	v_mfma_f32_16x16x32_bf16 v[46:49], v[50:53], v[188:191], v[46:49]
	v_mfma_f32_16x16x32_bf16 v[42:45], v[66:69], v[188:191], v[42:45]
	v_mfma_f32_16x16x32_bf16 v[30:33], v[50:53], v[196:199], v[30:33]
	v_mfma_f32_16x16x32_bf16 v[26:29], v[66:69], v[196:199], v[26:29]
	v_mfma_f32_16x16x32_bf16 v[14:17], v[50:53], v[204:207], v[14:17]
	v_mfma_f32_16x16x32_bf16 v[10:13], v[66:69], v[204:207], v[10:13]
	v_mfma_f32_16x16x32_bf16 v[78:81], v[54:57], v[184:187], v[78:81]
	v_mfma_f32_16x16x32_bf16 v[74:77], v[70:73], v[184:187], v[74:77]
	v_mfma_f32_16x16x32_bf16 v[46:49], v[54:57], v[192:195], v[46:49]
	v_mfma_f32_16x16x32_bf16 v[42:45], v[70:73], v[192:195], v[42:45]
	v_mfma_f32_16x16x32_bf16 v[30:33], v[54:57], v[200:203], v[30:33]
	v_mfma_f32_16x16x32_bf16 v[26:29], v[70:73], v[200:203], v[26:29]
	v_mfma_f32_16x16x32_bf16 v[14:17], v[54:57], v[208:211], v[14:17]
	v_mfma_f32_16x16x32_bf16 v[10:13], v[70:73], v[208:211], v[10:13]
	s_setprio 0
	s_setprio 1
	v_mfma_f32_16x16x32_bf16 v[38:41], v[146:149], v[188:191], v[38:41]
	v_mfma_f32_16x16x32_bf16 v[34:37], v[172:175], v[188:191], v[34:37]
	v_mfma_f32_16x16x32_bf16 v[22:25], v[146:149], v[196:199], v[22:25]
	v_mfma_f32_16x16x32_bf16 v[18:21], v[172:175], v[196:199], v[18:21]
	v_mfma_f32_16x16x32_bf16 v[6:9], v[146:149], v[204:207], v[6:9]
	v_mfma_f32_16x16x32_bf16 v[2:5], v[172:175], v[204:207], v[2:5]
	v_mfma_f32_16x16x32_bf16 v[50:53], v[146:149], v[180:183], v[62:65]
	v_mfma_f32_16x16x32_bf16 v[54:57], v[172:175], v[180:183], v[58:61]
	v_mfma_f32_16x16x32_bf16 v[38:41], v[150:153], v[192:195], v[38:41]
	v_mfma_f32_16x16x32_bf16 v[34:37], v[176:179], v[192:195], v[34:37]
	v_mfma_f32_16x16x32_bf16 v[22:25], v[150:153], v[200:203], v[22:25]
	v_mfma_f32_16x16x32_bf16 v[18:21], v[176:179], v[200:203], v[18:21]
	v_mfma_f32_16x16x32_bf16 v[6:9], v[150:153], v[208:211], v[6:9]
	v_mfma_f32_16x16x32_bf16 v[2:5], v[176:179], v[208:211], v[2:5]
	v_mfma_f32_16x16x32_bf16 v[50:53], v[150:153], v[184:187], v[50:53]
	v_mfma_f32_16x16x32_bf16 v[54:57], v[176:179], v[184:187], v[54:57]
	s_setprio 0
	s_barrier
	s_add_i32 s42, 0, 0x18000
	s_add_i32 s43, 0, 0x1c000
	v_add_u32_e32 v70, s42, v213
	v_add_u32_e32 v162, s43, v213
	ds_read_b128 v[58:61], v70
	ds_read_b128 v[62:65], v70 offset:1024
	ds_read_b128 v[66:69], v70 offset:2048
	ds_read_b128 v[70:73], v70 offset:3072
	ds_read_b128 v[146:149], v162
	ds_read_b128 v[150:153], v162 offset:1024
	ds_read_b128 v[172:175], v162 offset:2048
	ds_read_b128 v[176:179], v162 offset:3072
	s_add_u32 s36, s36, 0x40000
	s_addc_u32 s37, s37, 0
	s_mov_b32 m0, s53
	s_nop 0
	s_nop 0
	ds_read_b128 v[180:183], v216 offset:32768
	ds_read_b128 v[184:187], v216 offset:33792
	ds_read_b128 v[188:191], v216 offset:34816
	ds_read_b128 v[192:195], v216 offset:35840
	ds_read_b128 v[196:199], v216 offset:36864
	ds_read_b128 v[200:203], v216 offset:37888
	ds_read_b128 v[204:207], v216 offset:38912
	ds_read_b128 v[208:211], v216 offset:39936
	global_load_lds_dwordx4 v154, s[36:37]
	s_nop 0
	s_nop 0
	s_mov_b32 m0, s54
	s_nop 0
	global_load_lds_dwordx4 v158, s[36:37]
	s_waitcnt vmcnt(8)
	s_waitcnt lgkmcnt(0)
	s_barrier
	s_setprio 1
	s_waitcnt lgkmcnt(0)
	v_mfma_f32_16x16x32_bf16 v[142:145], v[58:61], v[180:183], v[142:145]
	v_mfma_f32_16x16x32_bf16 v[138:141], v[66:69], v[180:183], v[138:141]
	v_mfma_f32_16x16x32_bf16 v[126:129], v[58:61], v[188:191], v[126:129]
	v_mfma_f32_16x16x32_bf16 v[122:125], v[66:69], v[188:191], v[122:125]
	v_mfma_f32_16x16x32_bf16 v[110:113], v[58:61], v[196:199], v[110:113]
	v_mfma_f32_16x16x32_bf16 v[106:109], v[66:69], v[196:199], v[106:109]
	v_mfma_f32_16x16x32_bf16 v[94:97], v[58:61], v[204:207], v[94:97]
	v_mfma_f32_16x16x32_bf16 v[90:93], v[66:69], v[204:207], v[90:93]
	v_mfma_f32_16x16x32_bf16 v[142:145], v[62:65], v[184:187], v[142:145]
	v_mfma_f32_16x16x32_bf16 v[138:141], v[70:73], v[184:187], v[138:141]
	v_mfma_f32_16x16x32_bf16 v[126:129], v[62:65], v[192:195], v[126:129]
	v_mfma_f32_16x16x32_bf16 v[122:125], v[70:73], v[192:195], v[122:125]
	v_mfma_f32_16x16x32_bf16 v[110:113], v[62:65], v[200:203], v[110:113]
	v_mfma_f32_16x16x32_bf16 v[106:109], v[70:73], v[200:203], v[106:109]
	v_mfma_f32_16x16x32_bf16 v[94:97], v[62:65], v[208:211], v[94:97]
	v_mfma_f32_16x16x32_bf16 v[90:93], v[70:73], v[208:211], v[90:93]
	s_setprio 0
	s_setprio 1
	v_mfma_f32_16x16x32_bf16 v[134:137], v[146:149], v[180:183], v[134:137]
	v_mfma_f32_16x16x32_bf16 v[130:133], v[172:175], v[180:183], v[130:133]
	v_mfma_f32_16x16x32_bf16 v[118:121], v[146:149], v[188:191], v[118:121]
	v_mfma_f32_16x16x32_bf16 v[114:117], v[172:175], v[188:191], v[114:117]
	v_mfma_f32_16x16x32_bf16 v[102:105], v[146:149], v[196:199], v[102:105]
	v_mfma_f32_16x16x32_bf16 v[98:101], v[172:175], v[196:199], v[98:101]
	v_mfma_f32_16x16x32_bf16 v[86:89], v[146:149], v[204:207], v[86:89]
	v_mfma_f32_16x16x32_bf16 v[82:85], v[172:175], v[204:207], v[82:85]
	v_mfma_f32_16x16x32_bf16 v[134:137], v[150:153], v[184:187], v[134:137]
	v_mfma_f32_16x16x32_bf16 v[130:133], v[176:179], v[184:187], v[130:133]
	v_mfma_f32_16x16x32_bf16 v[118:121], v[150:153], v[192:195], v[118:121]
	v_mfma_f32_16x16x32_bf16 v[114:117], v[176:179], v[192:195], v[114:117]
	v_mfma_f32_16x16x32_bf16 v[102:105], v[150:153], v[200:203], v[102:105]
	v_mfma_f32_16x16x32_bf16 v[98:101], v[176:179], v[200:203], v[98:101]
	v_mfma_f32_16x16x32_bf16 v[86:89], v[150:153], v[208:211], v[86:89]
	v_mfma_f32_16x16x32_bf16 v[82:85], v[176:179], v[208:211], v[82:85]
	s_setprio 0
	s_barrier
; #define PG8_STAGE(bufoff, gbase, voff) do { _Pragma("unroll") for (int _i = 0; _i < 2; ++_i) \
;         __builtin_amdgcn_global_load_lds((const unsigned*)((const char*)(gbase) + (voff)[_i]), (PG8_LAS unsigned*)(lds + (bufoff) + ldsw + _i * 8192), 16, 0, 0); } while (0)
; #define PG8_LDA(dst, b, h) do { _Pragma("unroll") for (int m = 0; m < 4; ++m) _Pragma("unroll") for (int k = 0; k < 2; ++k) dst[m][k] = *(const PG8_LAS bf16x8*)(lds + PG8_SA(b, h) + aoff + m * 2048 + k * 1024); } while (0)
; #define PG8_MMA(ai, bj, At, Bt) do { __builtin_amdgcn_s_setprio(1); _Pragma("unroll") for (int m = 0; m < 4; ++m) _Pragma("unroll") for (int n = 0; n < 2; ++n) _Pragma("unroll") for (int k = 0; k < 2; ++k) \
;         acc[ai][bj][m][n] = __builtin_amdgcn_mfma_f32_16x16x32_bf16(Bt[n][k], At[m][k], acc[ai][bj][m][n], 0, 0, 0); __builtin_amdgcn_s_setprio(0); } while (0)
; #define PG8_WAIT_V(n) asm volatile("s_waitcnt vmcnt(" #n ")" ::: "memory")
; #define PG8_WAIT_L(n) asm volatile("s_waitcnt lgkmcnt(" #n ")" ::: "memory")
; #define PG8_BAR __builtin_amdgcn_s_barrier()
; #define PG8_SCHED __builtin_amdgcn_sched_barrier(0)
; template <class Epi, class Sched, bool ALIGN_EPI = false, bool SP2 = false>
; __device__ __forceinline__ void gemm_phase(PG8_LAS unsigned char* lds, const Gemm g, const Sched& S, const Epi& E) {
;     ...
;         for (int t = 0; t < nt; t += 2) {
;     ...
;             PG8_LDA(At, 1, 1); PG8_STAGE(PG8_SB(1, 0), b3, voffB); PG8_STAGE(PG8_SB(1, 1), b3 + hstep, voffB); PG8_STAGE(PG8_SA(1, 0), a3, voffA);
;             PG8_WAIT_V(8); PG8_WAIT_L(0); PG8_BAR; PG8_MMA(1, 0, At, B0); PG8_MMA(1, 1, At, B1); PG8_BAR; PG8_SCHED;
	s_add_i32 s36, s42, s50
	s_nop 0
	s_nop 0
	s_mov_b32 m0, s36
	ds_read_b128 v[180:183], v216 offset:49152
	ds_read_b128 v[184:187], v216 offset:50176
	ds_read_b128 v[188:191], v216 offset:51200
	ds_read_b128 v[192:195], v216 offset:52224
	ds_read_b128 v[196:199], v216 offset:53248
	ds_read_b128 v[200:203], v216 offset:54272
	ds_read_b128 v[204:207], v216 offset:55296
	ds_read_b128 v[208:211], v216 offset:56320
	global_load_lds_dwordx4 v156, s[98:99]
	s_add_i32 m0, s36, 0x2000
	s_add_u32 s6, s6, 0x40080
	s_nop 0
	s_nop 0
	s_addc_u32 s7, s7, 0
	s_add_i32 s36, s43, s50
	global_load_lds_dwordx4 v160, s[98:99]
	s_nop 0
	s_nop 0
	s_mov_b32 m0, s36
	s_nop 0
	global_load_lds_dwordx4 v156, s[6:7]
	s_nop 0
	s_nop 0
	s_add_i32 m0, s36, 0x2000
	s_nop 0
	global_load_lds_dwordx4 v160, s[6:7]
	s_nop 0
	s_nop 0
	s_mov_b32 m0, s63
	s_nop 0
	global_load_lds_dwordx4 v154, s[100:101]
	s_nop 0
	s_nop 0
	s_mov_b32 m0, s64
	s_nop 0
	global_load_lds_dwordx4 v158, s[100:101]
	s_waitcnt vmcnt(8)
	s_waitcnt lgkmcnt(0)
	s_barrier
	s_setprio 1
	s_waitcnt lgkmcnt(0)
	v_mfma_f32_16x16x32_bf16 v[78:81], v[58:61], v[180:183], v[78:81]
	v_mfma_f32_16x16x32_bf16 v[74:77], v[66:69], v[180:183], v[74:77]
	v_mfma_f32_16x16x32_bf16 v[46:49], v[58:61], v[188:191], v[46:49]
	v_mfma_f32_16x16x32_bf16 v[42:45], v[66:69], v[188:191], v[42:45]
	v_mfma_f32_16x16x32_bf16 v[30:33], v[58:61], v[196:199], v[30:33]
	v_mfma_f32_16x16x32_bf16 v[26:29], v[66:69], v[196:199], v[26:29]
	v_mfma_f32_16x16x32_bf16 v[14:17], v[58:61], v[204:207], v[14:17]
	v_mfma_f32_16x16x32_bf16 v[10:13], v[66:69], v[204:207], v[10:13]
	v_mfma_f32_16x16x32_bf16 v[78:81], v[62:65], v[184:187], v[78:81]
	v_mfma_f32_16x16x32_bf16 v[74:77], v[70:73], v[184:187], v[74:77]
	v_mfma_f32_16x16x32_bf16 v[46:49], v[62:65], v[192:195], v[46:49]
	v_mfma_f32_16x16x32_bf16 v[42:45], v[70:73], v[192:195], v[42:45]
	v_mfma_f32_16x16x32_bf16 v[30:33], v[62:65], v[200:203], v[30:33]
	v_mfma_f32_16x16x32_bf16 v[26:29], v[70:73], v[200:203], v[26:29]
	v_mfma_f32_16x16x32_bf16 v[14:17], v[62:65], v[208:211], v[14:17]
	v_mfma_f32_16x16x32_bf16 v[10:13], v[70:73], v[208:211], v[10:13]
	s_setprio 0
	s_setprio 1
	v_mfma_f32_16x16x32_bf16 v[50:53], v[146:149], v[180:183], v[50:53]
	v_mfma_f32_16x16x32_bf16 v[62:65], v[150:153], v[184:187], v[50:53]
	v_mfma_f32_16x16x32_bf16 v[50:53], v[172:175], v[180:183], v[54:57]
	v_mfma_f32_16x16x32_bf16 v[38:41], v[146:149], v[188:191], v[38:41]
	v_mfma_f32_16x16x32_bf16 v[34:37], v[172:175], v[188:191], v[34:37]
	v_mfma_f32_16x16x32_bf16 v[22:25], v[146:149], v[196:199], v[22:25]
	v_mfma_f32_16x16x32_bf16 v[18:21], v[172:175], v[196:199], v[18:21]
	v_mfma_f32_16x16x32_bf16 v[6:9], v[146:149], v[204:207], v[6:9]
	v_mfma_f32_16x16x32_bf16 v[2:5], v[172:175], v[204:207], v[2:5]
	v_mfma_f32_16x16x32_bf16 v[58:61], v[176:179], v[184:187], v[50:53]
	v_mfma_f32_16x16x32_bf16 v[38:41], v[150:153], v[192:195], v[38:41]
	v_mfma_f32_16x16x32_bf16 v[34:37], v[176:179], v[192:195], v[34:37]
	v_mfma_f32_16x16x32_bf16 v[22:25], v[150:153], v[200:203], v[22:25]
	v_mfma_f32_16x16x32_bf16 v[18:21], v[176:179], v[200:203], v[18:21]
	v_mfma_f32_16x16x32_bf16 v[6:9], v[150:153], v[208:211], v[6:9]
	v_mfma_f32_16x16x32_bf16 v[2:5], v[176:179], v[208:211], v[2:5]
	s_setprio 0
	s_barrier
	s_add_i32 s41, s41, 2
	s_add_u32 s4, s4, 0x100
	s_addc_u32 s5, s5, 0
	s_add_u32 s39, s39, 0x100
	s_addc_u32 s40, s40, 0
	s_cmp_gt_u32 s41, 13
	s_cbranch_scc0 .LBB0_838
	s_and_b64 vcc, exec, s[22:23]
	s_cbranch_vccz .LBB0_841
	s_barrier

; #define PG8_STAGE(bufoff, gbase, voff) do { _Pragma("unroll") for (int _i = 0; _i < 2; ++_i) \
;         __builtin_amdgcn_global_load_lds((const unsigned*)((const char*)(gbase) + (voff)[_i]), (PG8_LAS unsigned*)(lds + (bufoff) + ldsw + _i * 8192), 16, 0, 0); } while (0)
; #define PG8_LDA(dst, b, h) do { _Pragma("unroll") for (int m = 0; m < 4; ++m) _Pragma("unroll") for (int k = 0; k < 2; ++k) dst[m][k] = *(const PG8_LAS bf16x8*)(lds + PG8_SA(b, h) + aoff + m * 2048 + k * 1024); } while (0)
; #define PG8_LDB(dst, b, h) do { _Pragma("unroll") for (int n = 0; n < 2; ++n) _Pragma("unroll") for (int k = 0; k < 2; ++k) dst[n][k] = *(const PG8_LAS bf16x8*)(lds + PG8_SB(b, h) + boff + n * 2048 + k * 1024); } while (0)
; #define PG8_MMA(ai, bj, At, Bt) do { __builtin_amdgcn_s_setprio(1); _Pragma("unroll") for (int m = 0; m < 4; ++m) _Pragma("unroll") for (int n = 0; n < 2; ++n) _Pragma("unroll") for (int k = 0; k < 2; ++k) \
;         acc[ai][bj][m][n] = __builtin_amdgcn_mfma_f32_16x16x32_bf16(Bt[n][k], At[m][k], acc[ai][bj][m][n], 0, 0, 0); __builtin_amdgcn_s_setprio(0); } while (0)
; #define PG8_WAIT_V(n) asm volatile("s_waitcnt vmcnt(" #n ")" ::: "memory")
; #define PG8_WAIT_L(n) asm volatile("s_waitcnt lgkmcnt(" #n ")" ::: "memory")
; #define PG8_BAR __builtin_amdgcn_s_barrier()
; #define PG8_SCHED __builtin_amdgcn_sched_barrier(0)
; template <class Epi, class Sched, bool ALIGN_EPI = false, bool SP2 = false>
; __device__ __forceinline__ void gemm_phase(PG8_LAS unsigned char* lds, const Gemm g, const Sched& S, const Epi& E) {
;     ...
;             PG8_LDA(At, 0, 1); PG8_STAGE(PG8_SB(0, 0), b2, voffB); PG8_STAGE(PG8_SB(0, 1), b2 + hstep, voffB); PG8_STAGE(PG8_SA(0, 0), a2, voffA);
;             PG8_WAIT_V(8); PG8_WAIT_L(0); PG8_BAR; PG8_MMA(1, 0, At, B0); PG8_MMA(1, 1, At, B1); PG8_BAR; PG8_SCHED;
;             PG8_LDB(B0, 1, 0); PG8_LDB(B1, 1, 1); PG8_SCHED; PG8_LDA(At, 1, 0); PG8_STAGE(PG8_SA(0, 1), a2 + hstep, voffA);
;             PG8_WAIT_V(8); PG8_WAIT_L(0); PG8_BAR; PG8_MMA(0, 0, At, B0); PG8_MMA(0, 1, At, B1); PG8_BAR; PG8_SCHED;
.LBB0_985:
	s_add_u32 s42, s30, s40
	s_addc_u32 s43, s31, s41
	s_add_u32 s42, s42, 0x100
	s_addc_u32 s43, s43, 0
	s_add_u32 s84, s29, s40
	s_addc_u32 s85, s35, s41
	s_cmpk_eq_i32 s40, 0x700
	s_cselect_b32 s45, s23, s43
	s_cselect_b32 s44, s81, s42
	s_cselect_b32 s43, s21, s85
	s_cselect_b32 s42, s82, s84
	s_mov_b32 m0, s55
	s_nop 0
	s_nop 0
	s_add_u32 s98, s42, s8
	s_addc_u32 s99, s43, s9
	s_add_u32 s84, s42, 0x40000
	ds_read_b128 v[130:133], v197 offset:16384
	ds_read_b128 v[134:137], v197 offset:17408
	ds_read_b128 v[200:203], v197 offset:18432
	ds_read_b128 v[204:207], v197 offset:19456
	ds_read_b128 v[208:211], v197 offset:20480
	ds_read_b128 v[212:215], v197 offset:21504
	ds_read_b128 v[216:219], v197 offset:22528
	ds_read_b128 v[220:223], v197 offset:23552
	global_load_lds_dwordx4 v174, s[42:43]
	s_nop 0
	s_nop 0
	s_mov_b32 m0, s56
	s_addc_u32 s85, s43, 0
	global_load_lds_dwordx4 v170, s[42:43]
	s_nop 0
	s_nop 0
	s_mov_b32 m0, s57
	s_nop 0
	s_nop 0
	s_add_u32 s100, s44, s8
	s_addc_u32 s101, s45, s9
	global_load_lds_dwordx4 v174, s[84:85]
	s_nop 0
	s_nop 0
	s_mov_b32 m0, s58
	s_nop 0
	s_nop 0
	global_load_lds_dwordx4 v170, s[84:85]
	s_mov_b32 m0, s54
	s_nop 0
	global_load_lds_dwordx4 v176, s[44:45]
	s_mov_b32 m0, s59
	s_nop 0
	global_load_lds_dwordx4 v172, s[44:45]
	s_waitcnt vmcnt(8)
	s_waitcnt lgkmcnt(0)
	s_barrier
	s_setprio 1
	s_waitcnt lgkmcnt(0)
	v_mfma_f32_16x16x32_bf16 v[62:65], v[154:157], v[130:133], v[62:65]
	v_mfma_f32_16x16x32_bf16 v[58:61], v[162:165], v[130:133], v[58:61]
	v_mfma_f32_16x16x32_bf16 v[46:49], v[154:157], v[200:203], v[46:49]
	v_mfma_f32_16x16x32_bf16 v[42:45], v[162:165], v[200:203], v[42:45]
	v_mfma_f32_16x16x32_bf16 v[30:33], v[154:157], v[208:211], v[30:33]
	v_mfma_f32_16x16x32_bf16 v[26:29], v[162:165], v[208:211], v[26:29]
	v_mfma_f32_16x16x32_bf16 v[14:17], v[154:157], v[216:219], v[14:17]
	v_mfma_f32_16x16x32_bf16 v[10:13], v[162:165], v[216:219], v[10:13]
	v_mfma_f32_16x16x32_bf16 v[62:65], v[158:161], v[134:137], v[62:65]
	v_mfma_f32_16x16x32_bf16 v[58:61], v[166:169], v[134:137], v[58:61]
	v_mfma_f32_16x16x32_bf16 v[46:49], v[158:161], v[204:207], v[46:49]
	v_mfma_f32_16x16x32_bf16 v[42:45], v[166:169], v[204:207], v[42:45]
	v_mfma_f32_16x16x32_bf16 v[30:33], v[158:161], v[212:215], v[30:33]
	v_mfma_f32_16x16x32_bf16 v[26:29], v[166:169], v[212:215], v[26:29]
	v_mfma_f32_16x16x32_bf16 v[14:17], v[158:161], v[220:223], v[14:17]
	v_mfma_f32_16x16x32_bf16 v[10:13], v[166:169], v[220:223], v[10:13]
	s_setprio 0
	s_setprio 1
	v_mfma_f32_16x16x32_bf16 v[54:57], v[138:141], v[130:133], v[54:57]
	v_mfma_f32_16x16x32_bf16 v[50:53], v[146:149], v[130:133], v[50:53]
	v_mfma_f32_16x16x32_bf16 v[38:41], v[138:141], v[200:203], v[38:41]
	v_mfma_f32_16x16x32_bf16 v[34:37], v[146:149], v[200:203], v[34:37]
	v_mfma_f32_16x16x32_bf16 v[22:25], v[138:141], v[208:211], v[22:25]
	v_mfma_f32_16x16x32_bf16 v[18:21], v[146:149], v[208:211], v[18:21]
	v_mfma_f32_16x16x32_bf16 v[6:9], v[138:141], v[216:219], v[6:9]
	v_mfma_f32_16x16x32_bf16 v[2:5], v[146:149], v[216:219], v[2:5]
	v_mfma_f32_16x16x32_bf16 v[54:57], v[142:145], v[134:137], v[54:57]
	v_mfma_f32_16x16x32_bf16 v[50:53], v[150:153], v[134:137], v[50:53]
	v_mfma_f32_16x16x32_bf16 v[38:41], v[142:145], v[204:207], v[38:41]
	v_mfma_f32_16x16x32_bf16 v[34:37], v[150:153], v[204:207], v[34:37]
	v_mfma_f32_16x16x32_bf16 v[22:25], v[142:145], v[212:215], v[22:25]
	v_mfma_f32_16x16x32_bf16 v[18:21], v[150:153], v[212:215], v[18:21]
	v_mfma_f32_16x16x32_bf16 v[6:9], v[142:145], v[220:223], v[6:9]
	v_mfma_f32_16x16x32_bf16 v[2:5], v[150:153], v[220:223], v[2:5]
	s_setprio 0
	s_barrier
	s_add_i32 s84, 0, 0x18000
	v_add_u32_e32 v130, s84, v193
	s_add_i32 s85, 0, 0x1c000
	ds_read_b128 v[138:141], v130
	ds_read_b128 v[142:145], v130 offset:1024
	ds_read_b128 v[146:149], v130 offset:2048
	ds_read_b128 v[150:153], v130 offset:3072
	v_add_u32_e32 v130, s85, v193
	ds_read_b128 v[154:157], v130
	ds_read_b128 v[158:161], v130 offset:1024
	ds_read_b128 v[162:165], v130 offset:2048
	ds_read_b128 v[166:169], v130 offset:3072
	s_add_u32 s44, s44, 0x40000
	s_addc_u32 s45, s45, 0
	s_mov_b32 m0, s60
	s_nop 0
	s_nop 0
	ds_read_b128 v[200:203], v197 offset:32768
	ds_read_b128 v[204:207], v197 offset:33792
	ds_read_b128 v[208:211], v197 offset:34816
	ds_read_b128 v[212:215], v197 offset:35840
	ds_read_b128 v[216:219], v197 offset:36864
	ds_read_b128 v[220:223], v197 offset:37888
	ds_read_b128 v[224:227], v197 offset:38912
	ds_read_b128 v[228:231], v197 offset:39936
	global_load_lds_dwordx4 v176, s[44:45]
	s_nop 0
	s_nop 0
	s_mov_b32 m0, s61
	s_nop 0
	global_load_lds_dwordx4 v172, s[44:45]
	s_waitcnt vmcnt(8)
	s_waitcnt lgkmcnt(0)
	s_barrier
; #define PG8_STAGE(bufoff, gbase, voff) do { _Pragma("unroll") for (int _i = 0; _i < 2; ++_i) \
;         __builtin_amdgcn_global_load_lds((const unsigned*)((const char*)(gbase) + (voff)[_i]), (PG8_LAS unsigned*)(lds + (bufoff) + ldsw + _i * 8192), 16, 0, 0); } while (0)
; #define PG8_LDA(dst, b, h) do { _Pragma("unroll") for (int m = 0; m < 4; ++m) _Pragma("unroll") for (int k = 0; k < 2; ++k) dst[m][k] = *(const PG8_LAS bf16x8*)(lds + PG8_SA(b, h) + aoff + m * 2048 + k * 1024); } while (0)
; #define PG8_MMA(ai, bj, At, Bt) do { __builtin_amdgcn_s_setprio(1); _Pragma("unroll") for (int m = 0; m < 4; ++m) _Pragma("unroll") for (int n = 0; n < 2; ++n) _Pragma("unroll") for (int k = 0; k < 2; ++k) \
;         acc[ai][bj][m][n] = __builtin_amdgcn_mfma_f32_16x16x32_bf16(Bt[n][k], At[m][k], acc[ai][bj][m][n], 0, 0, 0); __builtin_amdgcn_s_setprio(0); } while (0)
; #define PG8_WAIT_V(n) asm volatile("s_waitcnt vmcnt(" #n ")" ::: "memory")
; #define PG8_WAIT_L(n) asm volatile("s_waitcnt lgkmcnt(" #n ")" ::: "memory")
; #define PG8_BAR __builtin_amdgcn_s_barrier()
; #define PG8_SCHED __builtin_amdgcn_sched_barrier(0)
; template <class Epi, class Sched, bool ALIGN_EPI = false, bool SP2 = false>
; __device__ __forceinline__ void gemm_phase(PG8_LAS unsigned char* lds, const Gemm g, const Sched& S, const Epi& E) {
;     ...
;             PG8_WAIT_V(8); PG8_WAIT_L(0); PG8_BAR; PG8_MMA(0, 0, At, B0); PG8_MMA(0, 1, At, B1); PG8_BAR; PG8_SCHED;
;             PG8_LDA(At, 1, 1); PG8_STAGE(PG8_SB(1, 0), b3, voffB); PG8_STAGE(PG8_SB(1, 1), b3 + hstep, voffB); PG8_STAGE(PG8_SA(1, 0), a3, voffA);
;             PG8_WAIT_V(8); PG8_WAIT_L(0); PG8_BAR; PG8_MMA(1, 0, At, B0); PG8_MMA(1, 1, At, B1); PG8_BAR; PG8_SCHED;
	s_setprio 1
	s_waitcnt lgkmcnt(0)
	v_mfma_f32_16x16x32_bf16 v[98:101], v[138:141], v[200:203], v[98:101]
	v_mfma_f32_16x16x32_bf16 v[134:137], v[142:145], v[204:207], v[98:101]
	v_mfma_f32_16x16x32_bf16 v[98:101], v[146:149], v[200:203], v[106:109]
	v_mfma_f32_16x16x32_bf16 v[130:133], v[150:153], v[204:207], v[98:101]
	v_mfma_f32_16x16x32_bf16 v[98:101], v[138:141], v[208:211], v[118:121]
	v_mfma_f32_16x16x32_bf16 v[118:121], v[142:145], v[212:215], v[98:101]
	v_mfma_f32_16x16x32_bf16 v[98:101], v[146:149], v[208:211], v[114:117]
	v_mfma_f32_16x16x32_bf16 v[94:97], v[138:141], v[216:219], v[94:97]
	v_mfma_f32_16x16x32_bf16 v[90:93], v[146:149], v[216:219], v[90:93]
	v_mfma_f32_16x16x32_bf16 v[78:81], v[138:141], v[224:227], v[78:81]
	v_mfma_f32_16x16x32_bf16 v[74:77], v[146:149], v[224:227], v[74:77]
	v_mfma_f32_16x16x32_bf16 v[114:117], v[150:153], v[212:215], v[98:101]
	v_mfma_f32_16x16x32_bf16 v[94:97], v[142:145], v[220:223], v[94:97]
	v_mfma_f32_16x16x32_bf16 v[90:93], v[150:153], v[220:223], v[90:93]
	v_mfma_f32_16x16x32_bf16 v[78:81], v[142:145], v[228:231], v[78:81]
	v_mfma_f32_16x16x32_bf16 v[74:77], v[150:153], v[228:231], v[74:77]
	s_setprio 0
	s_setprio 1
	v_mfma_f32_16x16x32_bf16 v[98:101], v[154:157], v[200:203], v[126:129]
	v_mfma_f32_16x16x32_bf16 v[126:129], v[158:161], v[204:207], v[98:101]
	v_mfma_f32_16x16x32_bf16 v[98:101], v[162:165], v[200:203], v[122:125]
	v_mfma_f32_16x16x32_bf16 v[122:125], v[166:169], v[204:207], v[98:101]
	v_mfma_f32_16x16x32_bf16 v[98:101], v[154:157], v[208:211], v[110:113]
	v_mfma_f32_16x16x32_bf16 v[110:113], v[158:161], v[212:215], v[98:101]
	v_mfma_f32_16x16x32_bf16 v[98:101], v[162:165], v[208:211], v[102:105]
	v_mfma_f32_16x16x32_bf16 v[86:89], v[154:157], v[216:219], v[86:89]
	v_mfma_f32_16x16x32_bf16 v[82:85], v[162:165], v[216:219], v[82:85]
	v_mfma_f32_16x16x32_bf16 v[70:73], v[154:157], v[224:227], v[70:73]
	v_mfma_f32_16x16x32_bf16 v[66:69], v[162:165], v[224:227], v[66:69]
	v_mfma_f32_16x16x32_bf16 v[102:105], v[166:169], v[212:215], v[98:101]
	v_mfma_f32_16x16x32_bf16 v[86:89], v[158:161], v[220:223], v[86:89]
	v_mfma_f32_16x16x32_bf16 v[82:85], v[166:169], v[220:223], v[82:85]
	v_mfma_f32_16x16x32_bf16 v[70:73], v[158:161], v[228:231], v[70:73]
	v_mfma_f32_16x16x32_bf16 v[66:69], v[166:169], v[228:231], v[66:69]
	s_setprio 0
	s_barrier
	s_add_i32 s44, s84, s51
	s_nop 0
	s_nop 0
	s_mov_b32 m0, s44
	ds_read_b128 v[98:101], v197 offset:49152
	ds_read_b128 v[106:109], v197 offset:50176
	ds_read_b128 v[200:203], v197 offset:51200
	ds_read_b128 v[204:207], v197 offset:52224
	ds_read_b128 v[208:211], v197 offset:53248
	ds_read_b128 v[212:215], v197 offset:54272
	ds_read_b128 v[216:219], v197 offset:55296
	ds_read_b128 v[220:223], v197 offset:56320
	global_load_lds_dwordx4 v174, s[98:99]
	s_add_i32 m0, s44, 0x2000
	s_add_u32 s42, s42, 0x40080
	s_nop 0
	s_nop 0
	s_addc_u32 s43, s43, 0
	s_add_i32 s44, s85, s51
	global_load_lds_dwordx4 v170, s[98:99]
	s_nop 0
	s_nop 0
	s_mov_b32 m0, s44
	s_nop 0
	global_load_lds_dwordx4 v174, s[42:43]
	s_nop 0
	s_nop 0
	s_add_i32 m0, s44, 0x2000
	s_nop 0
	global_load_lds_dwordx4 v170, s[42:43]
	s_nop 0
	s_nop 0
	s_mov_b32 m0, s65
	s_nop 0
	global_load_lds_dwordx4 v176, s[100:101]
	s_nop 0
	s_nop 0
	s_mov_b32 m0, s66
	s_nop 0
	global_load_lds_dwordx4 v172, s[100:101]
	s_waitcnt vmcnt(8)
	s_waitcnt lgkmcnt(0)
	s_barrier
	s_setprio 1
	s_waitcnt lgkmcnt(0)
	v_mfma_f32_16x16x32_bf16 v[62:65], v[138:141], v[98:101], v[62:65]
	v_mfma_f32_16x16x32_bf16 v[58:61], v[146:149], v[98:101], v[58:61]
	v_mfma_f32_16x16x32_bf16 v[46:49], v[138:141], v[200:203], v[46:49]
	v_mfma_f32_16x16x32_bf16 v[42:45], v[146:149], v[200:203], v[42:45]
	v_mfma_f32_16x16x32_bf16 v[30:33], v[138:141], v[208:211], v[30:33]
	v_mfma_f32_16x16x32_bf16 v[26:29], v[146:149], v[208:211], v[26:29]
	v_mfma_f32_16x16x32_bf16 v[14:17], v[138:141], v[216:219], v[14:17]
	v_mfma_f32_16x16x32_bf16 v[10:13], v[146:149], v[216:219], v[10:13]
	v_mfma_f32_16x16x32_bf16 v[62:65], v[142:145], v[106:109], v[62:65]
	v_mfma_f32_16x16x32_bf16 v[58:61], v[150:153], v[106:109], v[58:61]
	v_mfma_f32_16x16x32_bf16 v[46:49], v[142:145], v[204:207], v[46:49]
	v_mfma_f32_16x16x32_bf16 v[42:45], v[150:153], v[204:207], v[42:45]
	v_mfma_f32_16x16x32_bf16 v[30:33], v[142:145], v[212:215], v[30:33]
	v_mfma_f32_16x16x32_bf16 v[26:29], v[150:153], v[212:215], v[26:29]
	v_mfma_f32_16x16x32_bf16 v[14:17], v[142:145], v[220:223], v[14:17]
	v_mfma_f32_16x16x32_bf16 v[10:13], v[150:153], v[220:223], v[10:13]
	s_setprio 0
	s_setprio 1
	v_mfma_f32_16x16x32_bf16 v[54:57], v[154:157], v[98:101], v[54:57]
	v_mfma_f32_16x16x32_bf16 v[50:53], v[162:165], v[98:101], v[50:53]
	v_mfma_f32_16x16x32_bf16 v[38:41], v[154:157], v[200:203], v[38:41]
	v_mfma_f32_16x16x32_bf16 v[34:37], v[162:165], v[200:203], v[34:37]
	v_mfma_f32_16x16x32_bf16 v[22:25], v[154:157], v[208:211], v[22:25]
	v_mfma_f32_16x16x32_bf16 v[18:21], v[162:165], v[208:211], v[18:21]
	v_mfma_f32_16x16x32_bf16 v[6:9], v[154:157], v[216:219], v[6:9]
	v_mfma_f32_16x16x32_bf16 v[2:5], v[162:165], v[216:219], v[2:5]
	v_mfma_f32_16x16x32_bf16 v[54:57], v[158:161], v[106:109], v[54:57]
	v_mfma_f32_16x16x32_bf16 v[50:53], v[166:169], v[106:109], v[50:53]
	v_mfma_f32_16x16x32_bf16 v[38:41], v[158:161], v[204:207], v[38:41]
	v_mfma_f32_16x16x32_bf16 v[34:37], v[166:169], v[204:207], v[34:37]
	v_mfma_f32_16x16x32_bf16 v[22:25], v[158:161], v[212:215], v[22:25]
	v_mfma_f32_16x16x32_bf16 v[18:21], v[166:169], v[212:215], v[18:21]
	v_mfma_f32_16x16x32_bf16 v[6:9], v[158:161], v[220:223], v[6:9]
	v_mfma_f32_16x16x32_bf16 v[2:5], v[166:169], v[220:223], v[2:5]
	s_setprio 0
	s_barrier
	s_add_i32 s42, s83, 2
	s_add_u32 s40, s40, 0x100
	s_addc_u32 s41, s41, 0
	s_cmp_gt_u32 s83, 13
	s_mov_b32 s83, s42
	s_cbranch_scc1 .LBB0_989
; #define PG8_LAS __attribute__((address_space(3)))
; #define PG8_STAGE(bufoff, gbase, voff) do { _Pragma("unroll") for (int _i = 0; _i < 2; ++_i) \
;         __builtin_amdgcn_global_load_lds((const unsigned*)((const char*)(gbase) + (voff)[_i]), (PG8_LAS unsigned*)(lds + (bufoff) + ldsw + _i * 8192), 16, 0, 0); } while (0)
; #define PG8_LDA(dst, b, h) do { _Pragma("unroll") for (int m = 0; m < 4; ++m) _Pragma("unroll") for (int k = 0; k < 2; ++k) dst[m][k] = *(const PG8_LAS bf16x8*)(lds + PG8_SA(b, h) + aoff + m * 2048 + k * 1024); } while (0)
; #define PG8_LDB(dst, b, h) do { _Pragma("unroll") for (int n = 0; n < 2; ++n) _Pragma("unroll") for (int k = 0; k < 2; ++k) dst[n][k] = *(const PG8_LAS bf16x8*)(lds + PG8_SB(b, h) + boff + n * 2048 + k * 1024); } while (0)
; #define PG8_MMA(ai, bj, At, Bt) do { __builtin_amdgcn_s_setprio(1); _Pragma("unroll") for (int m = 0; m < 4; ++m) _Pragma("unroll") for (int n = 0; n < 2; ++n) _Pragma("unroll") for (int k = 0; k < 2; ++k) \
;         acc[ai][bj][m][n] = __builtin_amdgcn_mfma_f32_16x16x32_bf16(Bt[n][k], At[m][k], acc[ai][bj][m][n], 0, 0, 0); __builtin_amdgcn_s_setprio(0); } while (0)
; #define PG8_WAIT_V(n) asm volatile("s_waitcnt vmcnt(" #n ")" ::: "memory")
; template <class Epi, class Sched, bool ALIGN_EPI = false, bool SP2 = false>
; __device__ __forceinline__ void gemm_phase(PG8_LAS unsigned char* lds, const Gemm g, const Sched& S, const Epi& E) {
;     ...
;             PG8_LDB(B0, 0, 0); PG8_LDB(B1, 0, 1); PG8_SCHED; PG8_LDA(At, 0, 0); PG8_STAGE(PG8_SA(1, 1), a1 + hstep, voffA);
;             PG8_WAIT_V(8); PG8_WAIT_L(0); PG8_BAR; PG8_MMA(0, 0, At, B0); PG8_MMA(0, 1, At, B1); PG8_BAR; PG8_SCHED;
;             if constexpr (Epi::PREFETCH) { if (t == tpf) E.prefetch(cur, wid, lane); }
; __device__ __forceinline__ void epi_prefetch(PG8_LAS unsigned char* scr, const float* ssq, const float* bias_tile, const Unit& u, int wid, int lane) {
;     unsigned lo = (unsigned)lane * 16u; asm volatile("" : "+v"(lo));
;     const char* src = (const char*)(ssq + (size_t)u.pm * BM * 16 + wid * 512);
; #pragma unroll
;     for (int j = 0; j < 2; ++j) __builtin_amdgcn_global_load_lds((const unsigned*)(src + j * 1024 + lo), (PG8_LAS unsigned*)(scr + (wid * 2 + j) * 1024), 16, 0, 0);
;     if (wid == 0) __builtin_amdgcn_global_load_lds((const unsigned*)((const char*)bias_tile + lo), (PG8_LAS unsigned*)(scr + 16384), 16, 0, 0);
; }
.LBB0_986:
	ds_read_b128 v[154:157], v195
	ds_read_b128 v[158:161], v195 offset:1024
	ds_read_b128 v[162:165], v195 offset:2048
	ds_read_b128 v[166:169], v195 offset:3072
	ds_read_b128 v[138:141], v196
	ds_read_b128 v[142:145], v196 offset:1024
	ds_read_b128 v[146:149], v196 offset:2048
	ds_read_b128 v[150:153], v196 offset:3072
	v_lshl_add_u64 v[98:99], v[188:189], 0, s[40:41]
	s_add_i32 m0, s54, 0xc000
	ds_read_b128 v[200:203], v197
	ds_read_b128 v[204:207], v197 offset:1024
	ds_read_b128 v[208:211], v197 offset:2048
	ds_read_b128 v[212:215], v197 offset:3072
	ds_read_b128 v[216:219], v197 offset:4096
	ds_read_b128 v[220:223], v197 offset:5120
	ds_read_b128 v[224:227], v197 offset:6144
	ds_read_b128 v[228:231], v197 offset:7168
	global_load_lds_dwordx4 v[98:99], off
	v_lshl_add_u64 v[98:99], v[190:191], 0, s[40:41]
	s_add_i32 m0, s54, 0xe000
	s_nop 0
	global_load_lds_dwordx4 v[98:99], off
	s_waitcnt vmcnt(8)
	s_waitcnt lgkmcnt(0)
	s_barrier
	s_setprio 1
	s_waitcnt lgkmcnt(0)
	v_mfma_f32_16x16x32_bf16 v[98:101], v[154:157], v[200:203], v[134:137]
	v_mfma_f32_16x16x32_bf16 v[106:109], v[162:165], v[200:203], v[130:133]
	v_mfma_f32_16x16x32_bf16 v[118:121], v[154:157], v[208:211], v[118:121]
	v_mfma_f32_16x16x32_bf16 v[114:117], v[162:165], v[208:211], v[114:117]
	v_mfma_f32_16x16x32_bf16 v[94:97], v[154:157], v[216:219], v[94:97]
	v_mfma_f32_16x16x32_bf16 v[90:93], v[162:165], v[216:219], v[90:93]
	v_mfma_f32_16x16x32_bf16 v[78:81], v[154:157], v[224:227], v[78:81]
	v_mfma_f32_16x16x32_bf16 v[74:77], v[162:165], v[224:227], v[74:77]
	v_mfma_f32_16x16x32_bf16 v[98:101], v[158:161], v[204:207], v[98:101]
	v_mfma_f32_16x16x32_bf16 v[106:109], v[166:169], v[204:207], v[106:109]
	v_mfma_f32_16x16x32_bf16 v[118:121], v[158:161], v[212:215], v[118:121]
	v_mfma_f32_16x16x32_bf16 v[114:117], v[166:169], v[212:215], v[114:117]
	v_mfma_f32_16x16x32_bf16 v[94:97], v[158:161], v[220:223], v[94:97]
	v_mfma_f32_16x16x32_bf16 v[90:93], v[166:169], v[220:223], v[90:93]
	v_mfma_f32_16x16x32_bf16 v[78:81], v[158:161], v[228:231], v[78:81]
	v_mfma_f32_16x16x32_bf16 v[74:77], v[166:169], v[228:231], v[74:77]
	s_setprio 0
	s_setprio 1
	v_mfma_f32_16x16x32_bf16 v[126:129], v[138:141], v[200:203], v[126:129]
	v_mfma_f32_16x16x32_bf16 v[122:125], v[146:149], v[200:203], v[122:125]
	v_mfma_f32_16x16x32_bf16 v[110:113], v[138:141], v[208:211], v[110:113]
	v_mfma_f32_16x16x32_bf16 v[102:105], v[146:149], v[208:211], v[102:105]
	v_mfma_f32_16x16x32_bf16 v[86:89], v[138:141], v[216:219], v[86:89]
	v_mfma_f32_16x16x32_bf16 v[82:85], v[146:149], v[216:219], v[82:85]
	v_mfma_f32_16x16x32_bf16 v[70:73], v[138:141], v[224:227], v[70:73]
	v_mfma_f32_16x16x32_bf16 v[66:69], v[146:149], v[224:227], v[66:69]
	v_mfma_f32_16x16x32_bf16 v[126:129], v[142:145], v[204:207], v[126:129]
	v_mfma_f32_16x16x32_bf16 v[122:125], v[150:153], v[204:207], v[122:125]
	v_mfma_f32_16x16x32_bf16 v[110:113], v[142:145], v[212:215], v[110:113]
	v_mfma_f32_16x16x32_bf16 v[102:105], v[150:153], v[212:215], v[102:105]
	v_mfma_f32_16x16x32_bf16 v[86:89], v[142:145], v[220:223], v[86:89]
	v_mfma_f32_16x16x32_bf16 v[82:85], v[150:153], v[220:223], v[82:85]
	v_mfma_f32_16x16x32_bf16 v[70:73], v[142:145], v[228:231], v[70:73]
	v_mfma_f32_16x16x32_bf16 v[66:69], v[150:153], v[228:231], v[66:69]
	s_setprio 0
	s_barrier
	s_cmp_lg_u32 s46, s83
	s_cbranch_scc1 .LBB0_985
	v_mov_b32_e32 v178, v194
	s_add_i32 m0, s79, 0x20000
	v_lshl_add_u64 v[130:131], s[36:37], 0, v[178:179]
	global_load_lds_dwordx4 v178, s[36:37]
	v_lshl_add_u64 v[130:131], v[130:131], 0, s[18:19]
	s_add_i32 m0, s79, 0x20400
	s_andn2_b64 vcc, exec, s[14:15]
	global_load_lds_dwordx4 v[130:131], off
	s_cbranch_vccnz .LBB0_985
	s_nop 0
	s_nop 0
	s_add_i32 m0, 0, 0x24000
	s_nop 0
	global_load_lds_dwordx4 v178, s[38:39]
	s_branch .LBB0_985

; #define PG8_STAGE(bufoff, gbase, voff) do { _Pragma("unroll") for (int _i = 0; _i < 2; ++_i) \
;         __builtin_amdgcn_global_load_lds((const unsigned*)((const char*)(gbase) + (voff)[_i]), (PG8_LAS unsigned*)(lds + (bufoff) + ldsw + _i * 8192), 16, 0, 0); } while (0)
; #define PG8_LDA(dst, b, h) do { _Pragma("unroll") for (int m = 0; m < 4; ++m) _Pragma("unroll") for (int k = 0; k < 2; ++k) dst[m][k] = *(const PG8_LAS bf16x8*)(lds + PG8_SA(b, h) + aoff + m * 2048 + k * 1024); } while (0)
; #define PG8_LDB(dst, b, h) do { _Pragma("unroll") for (int n = 0; n < 2; ++n) _Pragma("unroll") for (int k = 0; k < 2; ++k) dst[n][k] = *(const PG8_LAS bf16x8*)(lds + PG8_SB(b, h) + boff + n * 2048 + k * 1024); } while (0)
; #define PG8_MMA(ai, bj, At, Bt) do { __builtin_amdgcn_s_setprio(1); _Pragma("unroll") for (int m = 0; m < 4; ++m) _Pragma("unroll") for (int n = 0; n < 2; ++n) _Pragma("unroll") for (int k = 0; k < 2; ++k) \
;         acc[ai][bj][m][n] = __builtin_amdgcn_mfma_f32_16x16x32_bf16(Bt[n][k], At[m][k], acc[ai][bj][m][n], 0, 0, 0); __builtin_amdgcn_s_setprio(0); } while (0)
; #define PG8_WAIT_V(n) asm volatile("s_waitcnt vmcnt(" #n ")" ::: "memory")
; template <class Epi, class Sched, bool ALIGN_EPI = false, bool SP2 = false>
; __device__ __forceinline__ void gemm_phase(PG8_LAS unsigned char* lds, const Gemm g, const Sched& S, const Epi& E) {
;     ...
;             const bool last = (t == nt - 2);
;             const char* a1 = cA + (size_t)(t + 1) * kstepA;
;             const char* a2 = last ? nA : cA + (size_t)(t + 2) * kstepA; const char* b2 = last ? nB : cB + (size_t)(t + 2) * kstep;
;             const char* a3 = a2 + kstepA; const char* b3 = b2 + kstep;
;             if (last && has_next) S.a_ready(nxt);
;             if constexpr (SP2) {
;             PG8_LDB(B0, 0, 0); PG8_LDB(B1, 0, 1); PG8_SCHED; PG8_LDA(At, 0, 0); PG8_STAGE(PG8_SA(1, 1), a1 + hstep, voffA);
;             PG8_WAIT_V(8); PG8_WAIT_L(0); PG8_BAR; PG8_MMA(0, 0, At, B0); PG8_MMA(0, 1, At, B1); PG8_BAR; PG8_SCHED;
;             if constexpr (Epi::PREFETCH) { if (t == tpf) E.prefetch(cur, wid, lane); }
;             PG8_LDA(At, 0, 1); PG8_STAGE(PG8_SB(0, 0), b2, voffB); PG8_STAGE(PG8_SB(0, 1), b2 + hstep, voffB); PG8_STAGE(PG8_SA(0, 0), a2, voffA);
;             PG8_WAIT_V(8); PG8_WAIT_L(0); PG8_BAR; PG8_MMA(1, 0, At, B0); PG8_MMA(1, 1, At, B1); PG8_BAR; PG8_SCHED;
.LBB0_1069:
	ds_read_b128 v[130:133], v192
	ds_read_b128 v[134:137], v192 offset:1024
	ds_read_b128 v[156:159], v192 offset:2048
	ds_read_b128 v[160:163], v192 offset:3072
	ds_read_b128 v[164:167], v193
	ds_read_b128 v[168:171], v193 offset:1024
	ds_read_b128 v[172:175], v193 offset:2048
	ds_read_b128 v[176:179], v193 offset:3072
	s_add_u32 s0, s4, 0x200
	s_addc_u32 s1, s5, 0
	s_cmp_eq_u32 s37, 40
	s_cselect_b32 s31, s27, s1
	s_cselect_b32 s30, s26, s0
	s_cselect_b32 s7, s29, s36
	s_cselect_b32 s6, s28, s35
	s_nop 0
	s_nop 0
	s_add_i32 m0, s45, 0xc000
	ds_read_b128 v[180:183], v194
	ds_read_b128 v[184:187], v194 offset:1024
	ds_read_b128 v[196:199], v194 offset:2048
	ds_read_b128 v[200:203], v194 offset:3072
	ds_read_b128 v[204:207], v194 offset:4096
	ds_read_b128 v[208:211], v194 offset:5120
	ds_read_b128 v[212:215], v194 offset:6144
	ds_read_b128 v[216:219], v194 offset:7168
	global_load_lds_dwordx4 v148, s[4:5]
	s_nop 0
	s_nop 0
	s_add_i32 m0, s45, 0xe000
	s_nop 0
	global_load_lds_dwordx4 v150, s[4:5]
	s_waitcnt vmcnt(8)
	s_waitcnt lgkmcnt(0)
	s_barrier
	s_setprio 1
	s_waitcnt lgkmcnt(0)
	v_mfma_f32_16x16x32_bf16 v[126:129], v[130:133], v[180:183], v[126:129]
	v_mfma_f32_16x16x32_bf16 v[122:125], v[156:159], v[180:183], v[122:125]
	v_mfma_f32_16x16x32_bf16 v[110:113], v[130:133], v[196:199], v[110:113]
	v_mfma_f32_16x16x32_bf16 v[106:109], v[156:159], v[196:199], v[106:109]
	v_mfma_f32_16x16x32_bf16 v[94:97], v[130:133], v[204:207], v[94:97]
	v_mfma_f32_16x16x32_bf16 v[90:93], v[156:159], v[204:207], v[90:93]
	v_mfma_f32_16x16x32_bf16 v[78:81], v[130:133], v[212:215], v[78:81]
	v_mfma_f32_16x16x32_bf16 v[74:77], v[156:159], v[212:215], v[74:77]
	v_mfma_f32_16x16x32_bf16 v[126:129], v[134:137], v[184:187], v[126:129]
	v_mfma_f32_16x16x32_bf16 v[122:125], v[160:163], v[184:187], v[122:125]
	v_mfma_f32_16x16x32_bf16 v[110:113], v[134:137], v[200:203], v[110:113]
	v_mfma_f32_16x16x32_bf16 v[106:109], v[160:163], v[200:203], v[106:109]
	v_mfma_f32_16x16x32_bf16 v[94:97], v[134:137], v[208:211], v[94:97]
	v_mfma_f32_16x16x32_bf16 v[90:93], v[160:163], v[208:211], v[90:93]
	v_mfma_f32_16x16x32_bf16 v[78:81], v[134:137], v[216:219], v[78:81]
	v_mfma_f32_16x16x32_bf16 v[74:77], v[160:163], v[216:219], v[74:77]
	s_setprio 0
	s_setprio 1
	v_mfma_f32_16x16x32_bf16 v[118:121], v[164:167], v[180:183], v[118:121]
	v_mfma_f32_16x16x32_bf16 v[114:117], v[172:175], v[180:183], v[114:117]
	v_mfma_f32_16x16x32_bf16 v[102:105], v[164:167], v[196:199], v[102:105]
	v_mfma_f32_16x16x32_bf16 v[98:101], v[172:175], v[196:199], v[98:101]
	v_mfma_f32_16x16x32_bf16 v[86:89], v[164:167], v[204:207], v[86:89]
	v_mfma_f32_16x16x32_bf16 v[82:85], v[172:175], v[204:207], v[82:85]
	v_mfma_f32_16x16x32_bf16 v[70:73], v[164:167], v[212:215], v[70:73]
	v_mfma_f32_16x16x32_bf16 v[66:69], v[172:175], v[212:215], v[66:69]
	v_mfma_f32_16x16x32_bf16 v[118:121], v[168:171], v[184:187], v[118:121]
	v_mfma_f32_16x16x32_bf16 v[114:117], v[176:179], v[184:187], v[114:117]
	v_mfma_f32_16x16x32_bf16 v[102:105], v[168:171], v[200:203], v[102:105]
	v_mfma_f32_16x16x32_bf16 v[98:101], v[176:179], v[200:203], v[98:101]
	v_mfma_f32_16x16x32_bf16 v[86:89], v[168:171], v[208:211], v[86:89]
	v_mfma_f32_16x16x32_bf16 v[82:85], v[176:179], v[208:211], v[82:85]
	v_mfma_f32_16x16x32_bf16 v[70:73], v[168:171], v[216:219], v[70:73]
	v_mfma_f32_16x16x32_bf16 v[66:69], v[176:179], v[216:219], v[66:69]
	s_setprio 0
	s_barrier
	s_add_i32 s4, s61, s44
	s_nop 0
	s_nop 0
	s_add_u32 s98, s6, s18
	s_addc_u32 s99, s7, s19
	s_mov_b32 m0, s4
	ds_read_b128 v[180:183], v194 offset:16384
	ds_read_b128 v[184:187], v194 offset:17408
	ds_read_b128 v[196:199], v194 offset:18432
	ds_read_b128 v[200:203], v194 offset:19456
	ds_read_b128 v[204:207], v194 offset:20480
	ds_read_b128 v[208:211], v194 offset:21504
	ds_read_b128 v[212:215], v194 offset:22528
	ds_read_b128 v[216:219], v194 offset:23552
	global_load_lds_dwordx4 v140, s[6:7]
	s_add_i32 m0, s4, 0x2000
	s_add_u32 s4, s6, 0xb0000
	s_nop 0
	s_nop 0
	s_addc_u32 s5, s7, 0
	s_add_i32 s38, s62, s44
	global_load_lds_dwordx4 v144, s[6:7]
	s_nop 0
	s_nop 0
	s_mov_b32 m0, s38
	s_nop 0
	s_nop 0
	global_load_lds_dwordx4 v140, s[4:5]
	s_nop 0
	s_nop 0
	s_add_i32 m0, s38, 0x2000
	s_nop 0
	global_load_lds_dwordx4 v144, s[4:5]
	s_nop 0
	s_nop 0
	s_add_u32 s100, s30, s20
	s_addc_u32 s101, s31, s21
	s_mov_b32 m0, s45
	s_nop 0
	global_load_lds_dwordx4 v138, s[30:31]
	s_mov_b32 m0, s46
	s_nop 0
	global_load_lds_dwordx4 v142, s[30:31]
	s_waitcnt vmcnt(8)
	s_waitcnt lgkmcnt(0)
	s_barrier
; #define PG8_STAGE(bufoff, gbase, voff) do { _Pragma("unroll") for (int _i = 0; _i < 2; ++_i) \
;         __builtin_amdgcn_global_load_lds((const unsigned*)((const char*)(gbase) + (voff)[_i]), (PG8_LAS unsigned*)(lds + (bufoff) + ldsw + _i * 8192), 16, 0, 0); } while (0)
; #define PG8_LDA(dst, b, h) do { _Pragma("unroll") for (int m = 0; m < 4; ++m) _Pragma("unroll") for (int k = 0; k < 2; ++k) dst[m][k] = *(const PG8_LAS bf16x8*)(lds + PG8_SA(b, h) + aoff + m * 2048 + k * 1024); } while (0)
; #define PG8_LDB(dst, b, h) do { _Pragma("unroll") for (int n = 0; n < 2; ++n) _Pragma("unroll") for (int k = 0; k < 2; ++k) dst[n][k] = *(const PG8_LAS bf16x8*)(lds + PG8_SB(b, h) + boff + n * 2048 + k * 1024); } while (0)
; #define PG8_MMA(ai, bj, At, Bt) do { __builtin_amdgcn_s_setprio(1); _Pragma("unroll") for (int m = 0; m < 4; ++m) _Pragma("unroll") for (int n = 0; n < 2; ++n) _Pragma("unroll") for (int k = 0; k < 2; ++k) \
;         acc[ai][bj][m][n] = __builtin_amdgcn_mfma_f32_16x16x32_bf16(Bt[n][k], At[m][k], acc[ai][bj][m][n], 0, 0, 0); __builtin_amdgcn_s_setprio(0); } while (0)
; #define PG8_WAIT_V(n) asm volatile("s_waitcnt vmcnt(" #n ")" ::: "memory")
; #define PG8_WAIT_L(n) asm volatile("s_waitcnt lgkmcnt(" #n ")" ::: "memory")
; #define PG8_BAR __builtin_amdgcn_s_barrier()
; #define PG8_SCHED __builtin_amdgcn_sched_barrier(0)
; template <class Epi, class Sched, bool ALIGN_EPI = false, bool SP2 = false>
; __device__ __forceinline__ void gemm_phase(PG8_LAS unsigned char* lds, const Gemm g, const Sched& S, const Epi& E) {
;     ...
;             PG8_WAIT_V(8); PG8_WAIT_L(0); PG8_BAR; PG8_MMA(1, 0, At, B0); PG8_MMA(1, 1, At, B1); PG8_BAR; PG8_SCHED;
;             PG8_LDB(B0, 1, 0); PG8_LDB(B1, 1, 1); PG8_SCHED; PG8_LDA(At, 1, 0); PG8_STAGE(PG8_SA(0, 1), a2 + hstep, voffA);
;             PG8_WAIT_V(8); PG8_WAIT_L(0); PG8_BAR; PG8_MMA(0, 0, At, B0); PG8_MMA(0, 1, At, B1); PG8_BAR; PG8_SCHED;
	s_setprio 1
	s_waitcnt lgkmcnt(0)
	v_mfma_f32_16x16x32_bf16 v[62:65], v[130:133], v[180:183], v[62:65]
	v_mfma_f32_16x16x32_bf16 v[58:61], v[156:159], v[180:183], v[58:61]
	v_mfma_f32_16x16x32_bf16 v[46:49], v[130:133], v[196:199], v[46:49]
	v_mfma_f32_16x16x32_bf16 v[42:45], v[156:159], v[196:199], v[42:45]
	v_mfma_f32_16x16x32_bf16 v[30:33], v[130:133], v[204:207], v[30:33]
	v_mfma_f32_16x16x32_bf16 v[26:29], v[156:159], v[204:207], v[26:29]
	v_mfma_f32_16x16x32_bf16 v[14:17], v[130:133], v[212:215], v[14:17]
	v_mfma_f32_16x16x32_bf16 v[10:13], v[156:159], v[212:215], v[10:13]
	v_mfma_f32_16x16x32_bf16 v[62:65], v[134:137], v[184:187], v[62:65]
	v_mfma_f32_16x16x32_bf16 v[58:61], v[160:163], v[184:187], v[58:61]
	v_mfma_f32_16x16x32_bf16 v[46:49], v[134:137], v[200:203], v[46:49]
	v_mfma_f32_16x16x32_bf16 v[42:45], v[160:163], v[200:203], v[42:45]
	v_mfma_f32_16x16x32_bf16 v[30:33], v[134:137], v[208:211], v[30:33]
	v_mfma_f32_16x16x32_bf16 v[26:29], v[160:163], v[208:211], v[26:29]
	v_mfma_f32_16x16x32_bf16 v[14:17], v[134:137], v[216:219], v[14:17]
	v_mfma_f32_16x16x32_bf16 v[10:13], v[160:163], v[216:219], v[10:13]
	s_setprio 0
	s_setprio 1
	v_mfma_f32_16x16x32_bf16 v[54:57], v[164:167], v[180:183], v[54:57]
	v_mfma_f32_16x16x32_bf16 v[50:53], v[172:175], v[180:183], v[50:53]
	v_mfma_f32_16x16x32_bf16 v[38:41], v[164:167], v[196:199], v[38:41]
	v_mfma_f32_16x16x32_bf16 v[34:37], v[172:175], v[196:199], v[34:37]
	v_mfma_f32_16x16x32_bf16 v[22:25], v[164:167], v[204:207], v[22:25]
	v_mfma_f32_16x16x32_bf16 v[18:21], v[172:175], v[204:207], v[18:21]
	v_mfma_f32_16x16x32_bf16 v[6:9], v[164:167], v[212:215], v[6:9]
	v_mfma_f32_16x16x32_bf16 v[2:5], v[172:175], v[212:215], v[2:5]
	v_mfma_f32_16x16x32_bf16 v[54:57], v[168:171], v[184:187], v[54:57]
	v_mfma_f32_16x16x32_bf16 v[50:53], v[176:179], v[184:187], v[50:53]
	v_mfma_f32_16x16x32_bf16 v[38:41], v[168:171], v[200:203], v[38:41]
	v_mfma_f32_16x16x32_bf16 v[34:37], v[176:179], v[200:203], v[34:37]
	v_mfma_f32_16x16x32_bf16 v[22:25], v[168:171], v[208:211], v[22:25]
	v_mfma_f32_16x16x32_bf16 v[18:21], v[176:179], v[208:211], v[18:21]
	v_mfma_f32_16x16x32_bf16 v[6:9], v[168:171], v[216:219], v[6:9]
	v_mfma_f32_16x16x32_bf16 v[2:5], v[176:179], v[216:219], v[2:5]
	s_setprio 0
	s_barrier
	s_add_i32 s38, 0, 0x18000
	v_add_u32_e32 v146, s38, v191
	s_add_i32 s39, 0, 0x1c000
	ds_read_b128 v[130:133], v146
	ds_read_b128 v[134:137], v146 offset:1024
	ds_read_b128 v[156:159], v146 offset:2048
	ds_read_b128 v[160:163], v146 offset:3072
	v_add_u32_e32 v146, s39, v191
	ds_read_b128 v[164:167], v146
	ds_read_b128 v[168:171], v146 offset:1024
	ds_read_b128 v[172:175], v146 offset:2048
	ds_read_b128 v[176:179], v146 offset:3072
	s_add_u32 s4, s30, 0xb0000
	s_addc_u32 s5, s31, 0
	s_mov_b32 m0, s47
	s_nop 0
	s_nop 0
	ds_read_b128 v[180:183], v194 offset:32768
	ds_read_b128 v[184:187], v194 offset:33792
	ds_read_b128 v[196:199], v194 offset:34816
	ds_read_b128 v[200:203], v194 offset:35840
	ds_read_b128 v[204:207], v194 offset:36864
	ds_read_b128 v[208:211], v194 offset:37888
	ds_read_b128 v[212:215], v194 offset:38912
	ds_read_b128 v[216:219], v194 offset:39936
	global_load_lds_dwordx4 v138, s[4:5]
	s_nop 0
	s_nop 0
	s_mov_b32 m0, s48
	s_nop 0
	global_load_lds_dwordx4 v142, s[4:5]
	s_waitcnt vmcnt(8)
	s_waitcnt lgkmcnt(0)
	s_barrier
	s_setprio 1
	s_waitcnt lgkmcnt(0)
	v_mfma_f32_16x16x32_bf16 v[126:129], v[130:133], v[180:183], v[126:129]
	v_mfma_f32_16x16x32_bf16 v[122:125], v[156:159], v[180:183], v[122:125]
	v_mfma_f32_16x16x32_bf16 v[110:113], v[130:133], v[196:199], v[110:113]
	v_mfma_f32_16x16x32_bf16 v[106:109], v[156:159], v[196:199], v[106:109]
	v_mfma_f32_16x16x32_bf16 v[94:97], v[130:133], v[204:207], v[94:97]
	v_mfma_f32_16x16x32_bf16 v[90:93], v[156:159], v[204:207], v[90:93]
	v_mfma_f32_16x16x32_bf16 v[78:81], v[130:133], v[212:215], v[78:81]
	v_mfma_f32_16x16x32_bf16 v[74:77], v[156:159], v[212:215], v[74:77]
	v_mfma_f32_16x16x32_bf16 v[126:129], v[134:137], v[184:187], v[126:129]
	v_mfma_f32_16x16x32_bf16 v[122:125], v[160:163], v[184:187], v[122:125]
	v_mfma_f32_16x16x32_bf16 v[110:113], v[134:137], v[200:203], v[110:113]
	v_mfma_f32_16x16x32_bf16 v[106:109], v[160:163], v[200:203], v[106:109]
	v_mfma_f32_16x16x32_bf16 v[94:97], v[134:137], v[208:211], v[94:97]
	v_mfma_f32_16x16x32_bf16 v[90:93], v[160:163], v[208:211], v[90:93]
	v_mfma_f32_16x16x32_bf16 v[78:81], v[134:137], v[216:219], v[78:81]
	v_mfma_f32_16x16x32_bf16 v[74:77], v[160:163], v[216:219], v[74:77]
	s_setprio 0
	s_setprio 1
	v_mfma_f32_16x16x32_bf16 v[118:121], v[164:167], v[180:183], v[118:121]
	v_mfma_f32_16x16x32_bf16 v[114:117], v[172:175], v[180:183], v[114:117]
	v_mfma_f32_16x16x32_bf16 v[102:105], v[164:167], v[196:199], v[102:105]
	v_mfma_f32_16x16x32_bf16 v[98:101], v[172:175], v[196:199], v[98:101]
	v_mfma_f32_16x16x32_bf16 v[86:89], v[164:167], v[204:207], v[86:89]
	v_mfma_f32_16x16x32_bf16 v[82:85], v[172:175], v[204:207], v[82:85]
	v_mfma_f32_16x16x32_bf16 v[70:73], v[164:167], v[212:215], v[70:73]
	v_mfma_f32_16x16x32_bf16 v[66:69], v[172:175], v[212:215], v[66:69]
	v_mfma_f32_16x16x32_bf16 v[118:121], v[168:171], v[184:187], v[118:121]
	v_mfma_f32_16x16x32_bf16 v[114:117], v[176:179], v[184:187], v[114:117]
	v_mfma_f32_16x16x32_bf16 v[102:105], v[168:171], v[200:203], v[102:105]
	v_mfma_f32_16x16x32_bf16 v[98:101], v[176:179], v[200:203], v[98:101]
	v_mfma_f32_16x16x32_bf16 v[86:89], v[168:171], v[208:211], v[86:89]
	v_mfma_f32_16x16x32_bf16 v[82:85], v[176:179], v[208:211], v[82:85]
	v_mfma_f32_16x16x32_bf16 v[70:73], v[168:171], v[216:219], v[70:73]
	v_mfma_f32_16x16x32_bf16 v[66:69], v[176:179], v[216:219], v[66:69]
	s_setprio 0
	s_barrier
; #define PG8_STAGE(bufoff, gbase, voff) do { _Pragma("unroll") for (int _i = 0; _i < 2; ++_i) \
;         __builtin_amdgcn_global_load_lds((const unsigned*)((const char*)(gbase) + (voff)[_i]), (PG8_LAS unsigned*)(lds + (bufoff) + ldsw + _i * 8192), 16, 0, 0); } while (0)
; #define PG8_LDA(dst, b, h) do { _Pragma("unroll") for (int m = 0; m < 4; ++m) _Pragma("unroll") for (int k = 0; k < 2; ++k) dst[m][k] = *(const PG8_LAS bf16x8*)(lds + PG8_SA(b, h) + aoff + m * 2048 + k * 1024); } while (0)
; #define PG8_MMA(ai, bj, At, Bt) do { __builtin_amdgcn_s_setprio(1); _Pragma("unroll") for (int m = 0; m < 4; ++m) _Pragma("unroll") for (int n = 0; n < 2; ++n) _Pragma("unroll") for (int k = 0; k < 2; ++k) \
;         acc[ai][bj][m][n] = __builtin_amdgcn_mfma_f32_16x16x32_bf16(Bt[n][k], At[m][k], acc[ai][bj][m][n], 0, 0, 0); __builtin_amdgcn_s_setprio(0); } while (0)
; #define PG8_WAIT_V(n) asm volatile("s_waitcnt vmcnt(" #n ")" ::: "memory")
; #define PG8_WAIT_L(n) asm volatile("s_waitcnt lgkmcnt(" #n ")" ::: "memory")
; #define PG8_BAR __builtin_amdgcn_s_barrier()
; #define PG8_SCHED __builtin_amdgcn_sched_barrier(0)
; template <class Epi, class Sched, bool ALIGN_EPI = false, bool SP2 = false>
; __device__ __forceinline__ void gemm_phase(PG8_LAS unsigned char* lds, const Gemm g, const Sched& S, const Epi& E) {
;     ...
;         for (int t = 0; t < nt; t += 2) {
;     ...
;             PG8_LDA(At, 1, 1); PG8_STAGE(PG8_SB(1, 0), b3, voffB); PG8_STAGE(PG8_SB(1, 1), b3 + hstep, voffB); PG8_STAGE(PG8_SA(1, 0), a3, voffA);
;             PG8_WAIT_V(8); PG8_WAIT_L(0); PG8_BAR; PG8_MMA(1, 0, At, B0); PG8_MMA(1, 1, At, B1); PG8_BAR; PG8_SCHED;
	s_add_i32 s4, s38, s44
	s_nop 0
	s_nop 0
	s_mov_b32 m0, s4
	ds_read_b128 v[180:183], v194 offset:49152
	ds_read_b128 v[184:187], v194 offset:50176
	ds_read_b128 v[196:199], v194 offset:51200
	ds_read_b128 v[200:203], v194 offset:52224
	ds_read_b128 v[204:207], v194 offset:53248
	ds_read_b128 v[208:211], v194 offset:54272
	ds_read_b128 v[212:215], v194 offset:55296
	ds_read_b128 v[216:219], v194 offset:56320
	global_load_lds_dwordx4 v140, s[98:99]
	s_add_i32 m0, s4, 0x2000
	s_add_u32 s4, s6, 0xb0080
	s_nop 0
	s_nop 0
	s_addc_u32 s5, s7, 0
	s_add_i32 s6, s39, s44
	global_load_lds_dwordx4 v144, s[98:99]
	s_nop 0
	s_nop 0
	s_mov_b32 m0, s6
	s_nop 0
	global_load_lds_dwordx4 v140, s[4:5]
	s_nop 0
	s_nop 0
	s_add_i32 m0, s6, 0x2000
	s_nop 0
	global_load_lds_dwordx4 v144, s[4:5]
	s_nop 0
	s_nop 0
	s_mov_b32 m0, s55
	s_nop 0
	global_load_lds_dwordx4 v138, s[100:101]
	s_nop 0
	s_nop 0
	s_mov_b32 m0, s56
	s_nop 0
	global_load_lds_dwordx4 v142, s[100:101]
	s_waitcnt vmcnt(8)
	s_waitcnt lgkmcnt(0)
	s_barrier
	s_setprio 1
	s_waitcnt lgkmcnt(0)
	v_mfma_f32_16x16x32_bf16 v[62:65], v[130:133], v[180:183], v[62:65]
	v_mfma_f32_16x16x32_bf16 v[58:61], v[156:159], v[180:183], v[58:61]
	v_mfma_f32_16x16x32_bf16 v[46:49], v[130:133], v[196:199], v[46:49]
	v_mfma_f32_16x16x32_bf16 v[42:45], v[156:159], v[196:199], v[42:45]
	v_mfma_f32_16x16x32_bf16 v[30:33], v[130:133], v[204:207], v[30:33]
	v_mfma_f32_16x16x32_bf16 v[26:29], v[156:159], v[204:207], v[26:29]
	v_mfma_f32_16x16x32_bf16 v[14:17], v[130:133], v[212:215], v[14:17]
	v_mfma_f32_16x16x32_bf16 v[10:13], v[156:159], v[212:215], v[10:13]
	v_mfma_f32_16x16x32_bf16 v[62:65], v[134:137], v[184:187], v[62:65]
	v_mfma_f32_16x16x32_bf16 v[58:61], v[160:163], v[184:187], v[58:61]
	v_mfma_f32_16x16x32_bf16 v[46:49], v[134:137], v[200:203], v[46:49]
	v_mfma_f32_16x16x32_bf16 v[42:45], v[160:163], v[200:203], v[42:45]
	v_mfma_f32_16x16x32_bf16 v[30:33], v[134:137], v[208:211], v[30:33]
	v_mfma_f32_16x16x32_bf16 v[26:29], v[160:163], v[208:211], v[26:29]
	v_mfma_f32_16x16x32_bf16 v[14:17], v[134:137], v[216:219], v[14:17]
	v_mfma_f32_16x16x32_bf16 v[10:13], v[160:163], v[216:219], v[10:13]
	s_setprio 0
	s_setprio 1
	v_mfma_f32_16x16x32_bf16 v[54:57], v[164:167], v[180:183], v[54:57]
	v_mfma_f32_16x16x32_bf16 v[50:53], v[172:175], v[180:183], v[50:53]
	v_mfma_f32_16x16x32_bf16 v[38:41], v[164:167], v[196:199], v[38:41]
	v_mfma_f32_16x16x32_bf16 v[34:37], v[172:175], v[196:199], v[34:37]
	v_mfma_f32_16x16x32_bf16 v[22:25], v[164:167], v[204:207], v[22:25]
	v_mfma_f32_16x16x32_bf16 v[18:21], v[172:175], v[204:207], v[18:21]
	v_mfma_f32_16x16x32_bf16 v[6:9], v[164:167], v[212:215], v[6:9]
	v_mfma_f32_16x16x32_bf16 v[2:5], v[172:175], v[212:215], v[2:5]
	v_mfma_f32_16x16x32_bf16 v[54:57], v[168:171], v[184:187], v[54:57]
	v_mfma_f32_16x16x32_bf16 v[50:53], v[176:179], v[184:187], v[50:53]
	v_mfma_f32_16x16x32_bf16 v[38:41], v[168:171], v[200:203], v[38:41]
	v_mfma_f32_16x16x32_bf16 v[34:37], v[176:179], v[200:203], v[34:37]
	v_mfma_f32_16x16x32_bf16 v[22:25], v[168:171], v[208:211], v[22:25]
	v_mfma_f32_16x16x32_bf16 v[18:21], v[176:179], v[208:211], v[18:21]
	v_mfma_f32_16x16x32_bf16 v[6:9], v[168:171], v[216:219], v[6:9]
	v_mfma_f32_16x16x32_bf16 v[2:5], v[176:179], v[216:219], v[2:5]
	s_setprio 0
	s_barrier
	s_add_i32 s37, s37, 2
	s_add_u32 s35, s35, 0x100
	s_addc_u32 s36, s36, 0
	s_cmp_gt_u32 s37, 41
	s_mov_b64 s[4:5], s[0:1]
	s_cbranch_scc0 .LBB0_1069
	s_and_b64 vcc, exec, s[22:23]
	s_cbranch_vccz .LBB0_1072
	s_barrier

; __global__ void __launch_bounds__(512, 2) mk_fwd(Args A) {
	.amdhsa_kernel _Z6mk_fwd4Args
		.amdhsa_group_segment_fixed_size 0
		.amdhsa_private_segment_fixed_size 0
		.amdhsa_kernarg_size 552
		.amdhsa_user_sgpr_count 2
		.amdhsa_user_sgpr_dispatch_ptr 0
		.amdhsa_user_sgpr_queue_ptr 0
		.amdhsa_user_sgpr_kernarg_segment_ptr 1
		.amdhsa_user_sgpr_dispatch_id 0
		.amdhsa_user_sgpr_kernarg_preload_length 0
		.amdhsa_user_sgpr_kernarg_preload_offset 0
		.amdhsa_user_sgpr_private_segment_size 0
		.amdhsa_uses_dynamic_stack 0
		.amdhsa_enable_private_segment 0
		.amdhsa_system_sgpr_workgroup_id_x 1
		.amdhsa_system_sgpr_workgroup_id_y 0
		.amdhsa_system_sgpr_workgroup_id_z 0
		.amdhsa_system_sgpr_workgroup_info 0
		.amdhsa_system_vgpr_workitem_id 0
		.amdhsa_next_free_vgpr 255
		.amdhsa_next_free_sgpr 102
		.amdhsa_accum_offset 256
		.amdhsa_reserve_vcc 1
		.amdhsa_float_round_mode_32 0
		.amdhsa_float_round_mode_16_64 0
		.amdhsa_float_denorm_mode_32 3
		.amdhsa_float_denorm_mode_16_64 3
		.amdhsa_dx10_clamp 1
		.amdhsa_ieee_mode 1
		.amdhsa_fp16_overflow 0
		.amdhsa_tg_split 0
		.amdhsa_exception_fp_ieee_invalid_op 0
		.amdhsa_exception_fp_denorm_src 0
		.amdhsa_exception_fp_ieee_div_zero 0
		.amdhsa_exception_fp_ieee_overflow 0
		.amdhsa_exception_fp_ieee_underflow 0
		.amdhsa_exception_fp_ieee_inexact 0
		.amdhsa_exception_int_div_zero 0
	.end_amdhsa_kernel

; __global__ void __launch_bounds__(512, 2) mk_fwd(Args A) {
amdhsa.kernels:
  - .agpr_count:     0
    .args:
      - .offset:         0
        .size:           296
        .value_kind:     by_value
      - .offset:         296
        .size:           4
        .value_kind:     hidden_block_count_x
      - .offset:         300
        .size:           4
        .value_kind:     hidden_block_count_y
      - .offset:         304
        .size:           4
        .value_kind:     hidden_block_count_z
      - .offset:         308
        .size:           2
        .value_kind:     hidden_group_size_x
      - .offset:         310
        .size:           2
        .value_kind:     hidden_group_size_y
      - .offset:         312
        .size:           2
        .value_kind:     hidden_group_size_z
      - .offset:         314
        .size:           2
        .value_kind:     hidden_remainder_x
      - .offset:         316
        .size:           2
        .value_kind:     hidden_remainder_y
      - .offset:         318
        .size:           2
        .value_kind:     hidden_remainder_z
      - .offset:         336
        .size:           8
        .value_kind:     hidden_global_offset_x
      - .offset:         344
        .size:           8
        .value_kind:     hidden_global_offset_y
      - .offset:         352
        .size:           8
        .value_kind:     hidden_global_offset_z
      - .offset:         360
        .size:           2
        .value_kind:     hidden_grid_dims
      - .offset:         416
        .size:           4
        .value_kind:     hidden_dynamic_lds_size
    .group_segment_fixed_size: 0
    .kernarg_segment_align: 8
    .kernarg_segment_size: 552
    .language:       OpenCL C
    .language_version:
      - 2
      - 0
    .max_flat_workgroup_size: 512
    .name:           _Z6mk_fwd4Args
    .private_segment_fixed_size: 0
    .sgpr_count:     108
    .sgpr_spill_count: 49
    .symbol:         _Z6mk_fwd4Args.kd
    .uniform_work_group_size: 1
    .uses_dynamic_stack: false
    .vgpr_count:     255
    .vgpr_spill_count: 0
    .wavefront_size: 64
